# decode: one wave per workgroup streams its two decode units back to back in the first S5 phase (ring-buffered stream); S5 units over waves 1-7
# speedup vs baseline: 1.0003x; 1.0003x over previous
; __global__ void __launch_bounds__(512, 2) fwd(Params P) {
;     ...
;         for (int r2 = 0; r2 < NREP(15); ++r2) for (int id = blockIdx.x * 8 + wave; id < 4672; id += gridDim.x * 8) {
;             if (id < 2048 && (id & 7) == 0) { mlstm_decode_wave(P, shm + wave * S5_WL, id >> 3); continue; }
;             const int sidx = id < 2048 ? id - (id >> 3) - 1 : 1792 + (id - 2048);
;             if (sidx < 3904) s5_unit<0>(P, shm + wave * S5_WL, sidx); else s5_unit<2>(P, shm + wave * S5_WL, sidx - 3904); }
.LBB0_343:
	v_lshl_add_u32 v151, s94, 3, v215
	v_mov_b32_e32 v238, s94
	v_mul_u32_u24_e32 v241, 7, v238
	v_add_u32_e32 v242, -1, v215
	v_add_u32_e32 v241, v241, v242
	v_add_u32_e32 v242, 0x100, v241
	v_add_u32_e32 v240, 0x800, v241
	v_add_u32_e32 v243, 0xf00, v241
	v_cmp_gt_u32_e32 vcc, 0x340, v241
	v_mov_b32_e32 v239, 0x7fff
	s_nop 1
	v_cndmask_b32_e32 v243, v239, v243, vcc
	v_cmp_eq_u32_e32 vcc, 0, v215
	v_lshlrev_b32_e32 v244, 3, v238
	v_add_u32_e32 v237, 0x800, v244
	v_cndmask_b32_e32 v151, v242, v244, vcc
	v_cndmask_b32_e32 v240, v240, v237, vcc
	v_cndmask_b32_e32 v243, v243, v239, vcc
	v_mov_b32_e32 v241, 0
	s_movk_i32 s0, 0x1240
	v_cmp_gt_i32_e32 vcc, s0, v151
	s_barrier
	s_and_saveexec_b64 s[16:17], vcc
	s_cbranch_execz .LBB0_376
	s_movk_i32 s0, 0x4200
	v_mad_u32_u24 v153, v215, s0, 0
	v_add_u32_e32 v0, 0x1000, v153
	v_cndmask_b32_e64 v2, v0, v153, s[4:5]
	v_lshrrev_b32_e32 v0, 1, v146
	v_and_b32_e32 v150, 8, v0
	v_lshrrev_b32_e32 v1, 4, v146
	v_lshl_add_u32 v2, v150, 1, v2
	v_lshlrev_b32_e32 v3, 5, v147
	v_mov_b32_e32 v0, 0
	v_add_u32_e32 v183, v2, v3
	v_mul_u32_u24_e32 v2, 0x820, v1
	v_add3_u32 v212, v153, v2, v64
	v_and_b32_e32 v2, 48, v146
	v_lshlrev_b32_e32 v4, 3, v146
	v_mov_b32_e32 v5, v0
	v_readlane_b32 s52, v245, 34
	v_add3_u32 v213, v153, v3, v2
	v_mul_u32_u24_e32 v3, 0x110, v147
	v_add_u32_e32 v218, v153, v4
	v_lshl_add_u64 v[4:5], s[12:13], 0, v[4:5]
	s_mov_b64 s[0:1], 0x1e5cb000
	v_lshlrev_b32_e32 v158, 4, v146
	v_mov_b32_e32 v159, v0
	v_readlane_b32 s56, v245, 38
	v_readlane_b32 s57, v245, 39
	v_readlane_b32 s58, v245, 40
	v_readlane_b32 s59, v245, 41
	v_readlane_b32 s60, v245, 42
	v_readlane_b32 s61, v245, 43
	v_readlane_b32 s62, v245, 44
	v_readlane_b32 s63, v245, 45
	v_readlane_b32 s64, v245, 46
	v_readlane_b32 s65, v245, 47
	v_readlane_b32 s66, v245, 48
	v_readlane_b32 s67, v245, 49
	v_add3_u32 v216, v153, v3, v2
	v_lshl_add_u64 v[156:157], v[4:5], 0, s[0:1]
	v_readlane_b32 s72, v245, 18
	v_lshl_add_u64 v[4:5], s[66:67], 0, v[158:159]
	v_and_b32_e32 v3, 0x1c0, v214
	v_readlane_b32 s56, v245, 2
	s_add_u32 s18, s12, 0x2100000
	v_readlane_b32 s73, v245, 19
	v_cmp_eq_u32_e64 s[6:7], 0, v3
	v_mov_b32_e32 v3, v0
	v_readlane_b32 s70, v245, 16
	v_readlane_b32 s71, v245, 17
	v_lshlrev_b32_e32 v152, 2, v1
	s_addc_u32 s19, s13, 0
	v_lshlrev_b32_e32 v1, 7, v1
	v_lshlrev_b32_e32 v154, 2, v146
	s_mov_b64 s[0:1], 0xc924040
	v_lshl_add_u64 v[166:167], s[70:71], 0, v[2:3]
	v_lshl_add_u64 v[168:169], s[72:73], 0, v[2:3]
	v_and_b32_e32 v2, 16, v146
	v_lshlrev_b32_e32 v6, 6, v147
	v_add3_u32 v217, v153, v1, v148
	v_sub_u32_e32 v1, 0, v154
	v_readlane_b32 s82, v245, 28
	v_readlane_b32 s83, v245, 29
	s_add_u32 s20, s12, 0x12dc2000
	v_readlane_b32 s53, v245, 35
	v_readlane_b32 s54, v245, 36
	v_readlane_b32 s55, v245, 37
	v_lshl_add_u64 v[164:165], v[4:5], 0, s[0:1]
	v_lshl_add_u64 v[2:3], s[12:13], 0, v[2:3]
	s_mov_b64 s[0:1], 0x458a000
	s_movk_i32 s25, 0x1000
	v_lshl_add_u32 v155, v146, 6, v153
	v_lshl_add_u64 v[160:161], s[46:47], 0, v[158:159]
	v_add_u32_e32 v219, v153, v158
	v_lshl_add_u64 v[162:163], s[82:83], 0, v[158:159]
	s_addc_u32 s21, s13, 0
	s_lshl_b32 s54, s96, 3
	v_lshl_add_u64 v[170:171], v[2:3], 0, s[0:1]
	s_mov_b64 s[22:23], 0
	s_mov_b32 s33, 0x3fb8aa3b
	s_mov_b32 s55, 0xc2ce8ed0
	s_mov_b32 s50, 0x42b17218
	s_brev_b32 s51, 18
	s_mov_b32 s93, 0xfe5163ab
	v_mov_b32_e32 v220, 0x3c0881c4
	v_mov_b32_e32 v221, 0xbab64f3b
	s_movk_i32 s89, 0x1f8
	v_lshlrev_b32_e32 v222, 2, v6
	s_movk_i32 s90, 0x4800
	s_movk_i32 s91, 0x7fff
	s_mov_b32 s92, 0x4524000
	s_mov_b32 s52, 0x4724000
	v_add_u32_e32 v223, v218, v1
	s_mov_b32 s53, 0x7060302
	s_mov_b32 s88, 0x88888889
	s_mov_b32 s24, 0x3d800000
	v_mov_b32_e32 v224, 0x3ecc95a3
	s_mov_b64 s[26:27], 0x8000
	v_mov_b32_e32 v225, 0x3727c5ac
	v_mov_b32_e32 v226, 0xffffff00
	v_mov_b32_e32 v227, 0x7f800000
	v_not_b32_e32 v228, 63
	v_not_b32_e32 v229, 31
	v_mov_b32_e32 v230, 0x7fc00000
	v_mov_b32_e32 v172, 0x3f317218
	v_mov_b32_e32 v231, 0xff800000
	v_readlane_b32 s74, v245, 20
	v_readlane_b32 s75, v245, 21
	v_readlane_b32 s76, v245, 22
	v_readlane_b32 s77, v245, 23
	v_readlane_b32 s78, v245, 24
	v_readlane_b32 s79, v245, 25
	v_readlane_b32 s80, v245, 26
	v_readlane_b32 s81, v245, 27
	v_readlane_b32 s84, v245, 30
	v_readlane_b32 s85, v245, 31
	v_readlane_b32 s86, v245, 32
	v_readlane_b32 s87, v245, 33
	v_readlane_b32 s57, v245, 3
	v_readlane_b32 s58, v245, 4
	v_readlane_b32 s59, v245, 5
	v_readlane_b32 s60, v245, 6
	v_readlane_b32 s61, v245, 7
	v_readlane_b32 s62, v245, 8
	v_readlane_b32 s63, v245, 9
	v_readlane_b32 s64, v245, 10
	v_readlane_b32 s65, v245, 11
	v_readlane_b32 s66, v245, 12
	v_readlane_b32 s67, v245, 13
	v_readlane_b32 s68, v245, 14
	v_readlane_b32 s69, v245, 15
	s_branch .LBB0_347

; __device__ __forceinline__ void mlstm_decode_wave(const Params& P, unsigned char* wl, int sh) {
;     ...
;     const float* C0 = P.in[4] + (size_t)sh * 65536 + 4 * lane; float* C1 = P.out + OUT_SC + (size_t)sh * 65536 + 4 * lane;
;     f32x4 part = (f32x4){0.f, 0.f, 0.f, 0.f}; const f32x4 wv = wi * v4;
; #pragma unroll 1
;     for (int dk0 = 0; dk0 < 256; dk0 += 32) { f32x4 c[32];
; #pragma unroll
;         for (int i = 0; i < 32; ++i) c[i] = __builtin_nontemporal_load((const f32x4*)(C0 + (dk0 + i) * 256));
; #pragma unroll
;         for (int i = 0; i < 32; ++i) { const float qd = sq[dk0 + i], kd = sk[dk0 + i]; part += qd * c[i]; __builtin_nontemporal_store(wc * c[i] + kd * wv, (f32x4*)(C1 + (dk0 + i) * 256)); } }
.LBB0_372:
	s_nop 0
	v_readfirstlane_b32 s28, v204
	v_readfirstlane_b32 s29, v205
	v_readfirstlane_b32 s30, v202
	v_readfirstlane_b32 s31, v203
	s_nop 3
	s_add_u32 s30, s30, 0x4924040
	s_addc_u32 s31, s31, 0
	ds_read_b128 v[134:137], v179
	ds_read_b128 v[138:141], v179 offset:1024
	global_load_dwordx4 v[232:235], v158, s[28:29] nt
	global_load_dwordx4 v[130:133], v158, s[28:29] offset:1024 nt
	global_load_dwordx4 v[126:129], v158, s[28:29] offset:2048 nt
	global_load_dwordx4 v[122:125], v158, s[28:29] offset:3072 nt
	s_add_u32 s28, s28, 0x1000
	s_addc_u32 s29, s29, 0
	global_load_dwordx4 v[118:121], v158, s[28:29] nt
	global_load_dwordx4 v[114:117], v158, s[28:29] offset:1024 nt
	global_load_dwordx4 v[110:113], v158, s[28:29] offset:2048 nt
	global_load_dwordx4 v[106:109], v158, s[28:29] offset:3072 nt
	s_add_u32 s28, s28, 0x1000
	s_addc_u32 s29, s29, 0
	global_load_dwordx4 v[102:105], v158, s[28:29] nt
	global_load_dwordx4 v[98:101], v158, s[28:29] offset:1024 nt
	global_load_dwordx4 v[94:97], v158, s[28:29] offset:2048 nt
	global_load_dwordx4 v[90:93], v158, s[28:29] offset:3072 nt
	s_add_u32 s28, s28, 0x1000
	s_addc_u32 s29, s29, 0
	global_load_dwordx4 v[86:89], v158, s[28:29] nt
	global_load_dwordx4 v[82:85], v158, s[28:29] offset:1024 nt
	global_load_dwordx4 v[78:81], v158, s[28:29] offset:2048 nt
	global_load_dwordx4 v[74:77], v158, s[28:29] offset:3072 nt
	s_add_u32 s28, s28, 0x1000
	s_addc_u32 s29, s29, 0
	global_load_dwordx4 v[70:73], v158, s[28:29] nt
	global_load_dwordx4 v[66:69], v158, s[28:29] offset:1024 nt
	global_load_dwordx4 v[62:65], v158, s[28:29] offset:2048 nt
	global_load_dwordx4 v[58:61], v158, s[28:29] offset:3072 nt
	s_add_u32 s28, s28, 0x1000
	s_addc_u32 s29, s29, 0
	global_load_dwordx4 v[54:57], v158, s[28:29] nt
	global_load_dwordx4 v[50:53], v158, s[28:29] offset:1024 nt
	global_load_dwordx4 v[46:49], v158, s[28:29] offset:2048 nt
	global_load_dwordx4 v[42:45], v158, s[28:29] offset:3072 nt
	s_add_u32 s28, s28, 0x1000
	s_addc_u32 s29, s29, 0
	global_load_dwordx4 v[38:41], v158, s[28:29] nt
	global_load_dwordx4 v[34:37], v158, s[28:29] offset:1024 nt
	global_load_dwordx4 v[30:33], v158, s[28:29] offset:2048 nt
	global_load_dwordx4 v[26:29], v158, s[28:29] offset:3072 nt
	s_add_u32 s28, s28, 0x1000
	s_addc_u32 s29, s29, 0
	global_load_dwordx4 v[22:25], v158, s[28:29] nt
	global_load_dwordx4 v[18:21], v158, s[28:29] offset:1024 nt
	global_load_dwordx4 v[14:17], v158, s[28:29] offset:2048 nt
	global_load_dwordx4 v[10:13], v158, s[28:29] offset:3072 nt
	s_add_u32 s28, s28, 0x1000
	s_addc_u32 s29, s29, 0
	ds_read_b128 v[202:205], v179 offset:16
	ds_read_b128 v[206:209], v179 offset:1040
	s_waitcnt lgkmcnt(2)
	s_waitcnt vmcnt(31)
	v_pk_fma_f32 v[142:143], v[232:233], v[134:135], v[142:143] op_sel_hi:[1,0,1]
	v_pk_fma_f32 v[144:145], v[234:235], v[134:135], v[144:145] op_sel_hi:[1,0,1]
	v_pk_mul_f32 v[210:211], v[200:201], v[138:139] op_sel_hi:[1,0]
	v_pk_fma_f32 v[232:233], v[184:185], v[232:233], v[210:211]
	v_pk_mul_f32 v[210:211], v[198:199], v[138:139] op_sel_hi:[1,0]
	v_pk_fma_f32 v[234:235], v[190:191], v[234:235], v[210:211]
	global_store_dwordx4 v158, v[232:235], s[30:31] nt
	s_nop 0
	global_load_dwordx4 v[232:235], v158, s[28:29] nt
	s_waitcnt vmcnt(32)
	v_pk_fma_f32 v[142:143], v[130:131], v[134:135], v[142:143] op_sel:[0,1,0]
	v_pk_fma_f32 v[144:145], v[132:133], v[134:135], v[144:145] op_sel:[0,1,0]
	v_pk_mul_f32 v[210:211], v[200:201], v[138:139] op_sel:[0,1]
	v_pk_fma_f32 v[130:131], v[184:185], v[130:131], v[210:211]
	v_pk_mul_f32 v[210:211], v[198:199], v[138:139] op_sel:[0,1]
	v_pk_fma_f32 v[132:133], v[190:191], v[132:133], v[210:211]
	global_store_dwordx4 v158, v[130:133], s[30:31] offset:1024 nt
	s_nop 0
	global_load_dwordx4 v[130:133], v158, s[28:29] offset:1024 nt
	s_waitcnt vmcnt(33)
	v_pk_fma_f32 v[142:143], v[126:127], v[136:137], v[142:143] op_sel_hi:[1,0,1]
	v_pk_fma_f32 v[144:145], v[128:129], v[136:137], v[144:145] op_sel_hi:[1,0,1]
	v_pk_mul_f32 v[210:211], v[200:201], v[140:141] op_sel_hi:[1,0]
	v_pk_fma_f32 v[126:127], v[184:185], v[126:127], v[210:211]
	v_pk_mul_f32 v[210:211], v[198:199], v[140:141] op_sel_hi:[1,0]
	v_pk_fma_f32 v[128:129], v[190:191], v[128:129], v[210:211]
	global_store_dwordx4 v158, v[126:129], s[30:31] offset:2048 nt
	s_nop 0
	global_load_dwordx4 v[126:129], v158, s[28:29] offset:2048 nt
	s_waitcnt vmcnt(34)
	v_pk_fma_f32 v[142:143], v[122:123], v[136:137], v[142:143] op_sel:[0,1,0]
	v_pk_fma_f32 v[144:145], v[124:125], v[136:137], v[144:145] op_sel:[0,1,0]
	v_pk_mul_f32 v[210:211], v[200:201], v[140:141] op_sel:[0,1]
	v_pk_fma_f32 v[122:123], v[184:185], v[122:123], v[210:211]
	v_pk_mul_f32 v[210:211], v[198:199], v[140:141] op_sel:[0,1]
	v_pk_fma_f32 v[124:125], v[190:191], v[124:125], v[210:211]
	global_store_dwordx4 v158, v[122:125], s[30:31] offset:3072 nt
	s_add_u32 s30, s30, 0x1000
	s_addc_u32 s31, s31, 0
	global_load_dwordx4 v[122:125], v158, s[28:29] offset:3072 nt
	s_add_u32 s28, s28, 0x1000
	s_addc_u32 s29, s29, 0
	ds_read_b128 v[134:137], v179 offset:32
	ds_read_b128 v[138:141], v179 offset:1056
	s_waitcnt lgkmcnt(2)
	s_waitcnt vmcnt(35)
	v_pk_fma_f32 v[142:143], v[118:119], v[202:203], v[142:143] op_sel_hi:[1,0,1]
	v_pk_fma_f32 v[144:145], v[120:121], v[202:203], v[144:145] op_sel_hi:[1,0,1]
	v_pk_mul_f32 v[210:211], v[200:201], v[206:207] op_sel_hi:[1,0]
	v_pk_fma_f32 v[118:119], v[184:185], v[118:119], v[210:211]
	v_pk_mul_f32 v[210:211], v[198:199], v[206:207] op_sel_hi:[1,0]
	v_pk_fma_f32 v[120:121], v[190:191], v[120:121], v[210:211]
	global_store_dwordx4 v158, v[118:121], s[30:31] nt
	s_nop 0
	global_load_dwordx4 v[118:121], v158, s[28:29] nt
	s_waitcnt vmcnt(36)
; __device__ __forceinline__ void mlstm_decode_wave(const Params& P, unsigned char* wl, int sh) {
;     ...
;     const float* C0 = P.in[4] + (size_t)sh * 65536 + 4 * lane; float* C1 = P.out + OUT_SC + (size_t)sh * 65536 + 4 * lane;
;     f32x4 part = (f32x4){0.f, 0.f, 0.f, 0.f}; const f32x4 wv = wi * v4;
; #pragma unroll 1
;     for (int dk0 = 0; dk0 < 256; dk0 += 32) { f32x4 c[32];
; #pragma unroll
;         for (int i = 0; i < 32; ++i) c[i] = __builtin_nontemporal_load((const f32x4*)(C0 + (dk0 + i) * 256));
; #pragma unroll
;         for (int i = 0; i < 32; ++i) { const float qd = sq[dk0 + i], kd = sk[dk0 + i]; part += qd * c[i]; __builtin_nontemporal_store(wc * c[i] + kd * wv, (f32x4*)(C1 + (dk0 + i) * 256)); } }
	v_pk_fma_f32 v[142:143], v[114:115], v[202:203], v[142:143] op_sel:[0,1,0]
	v_pk_fma_f32 v[144:145], v[116:117], v[202:203], v[144:145] op_sel:[0,1,0]
	v_pk_mul_f32 v[210:211], v[200:201], v[206:207] op_sel:[0,1]
	v_pk_fma_f32 v[114:115], v[184:185], v[114:115], v[210:211]
	v_pk_mul_f32 v[210:211], v[198:199], v[206:207] op_sel:[0,1]
	v_pk_fma_f32 v[116:117], v[190:191], v[116:117], v[210:211]
	global_store_dwordx4 v158, v[114:117], s[30:31] offset:1024 nt
	s_nop 0
	global_load_dwordx4 v[114:117], v158, s[28:29] offset:1024 nt
	s_waitcnt vmcnt(37)
	v_pk_fma_f32 v[142:143], v[110:111], v[204:205], v[142:143] op_sel_hi:[1,0,1]
	v_pk_fma_f32 v[144:145], v[112:113], v[204:205], v[144:145] op_sel_hi:[1,0,1]
	v_pk_mul_f32 v[210:211], v[200:201], v[208:209] op_sel_hi:[1,0]
	v_pk_fma_f32 v[110:111], v[184:185], v[110:111], v[210:211]
	v_pk_mul_f32 v[210:211], v[198:199], v[208:209] op_sel_hi:[1,0]
	v_pk_fma_f32 v[112:113], v[190:191], v[112:113], v[210:211]
	global_store_dwordx4 v158, v[110:113], s[30:31] offset:2048 nt
	s_nop 0
	global_load_dwordx4 v[110:113], v158, s[28:29] offset:2048 nt
	s_waitcnt vmcnt(38)
	v_pk_fma_f32 v[142:143], v[106:107], v[204:205], v[142:143] op_sel:[0,1,0]
	v_pk_fma_f32 v[144:145], v[108:109], v[204:205], v[144:145] op_sel:[0,1,0]
	v_pk_mul_f32 v[210:211], v[200:201], v[208:209] op_sel:[0,1]
	v_pk_fma_f32 v[106:107], v[184:185], v[106:107], v[210:211]
	v_pk_mul_f32 v[210:211], v[198:199], v[208:209] op_sel:[0,1]
	v_pk_fma_f32 v[108:109], v[190:191], v[108:109], v[210:211]
	global_store_dwordx4 v158, v[106:109], s[30:31] offset:3072 nt
	s_add_u32 s30, s30, 0x1000
	s_addc_u32 s31, s31, 0
	global_load_dwordx4 v[106:109], v158, s[28:29] offset:3072 nt
	s_add_u32 s28, s28, 0x1000
	s_addc_u32 s29, s29, 0
	ds_read_b128 v[202:205], v179 offset:48
	ds_read_b128 v[206:209], v179 offset:1072
	s_waitcnt lgkmcnt(2)
	s_waitcnt vmcnt(39)
	v_pk_fma_f32 v[142:143], v[102:103], v[134:135], v[142:143] op_sel_hi:[1,0,1]
	v_pk_fma_f32 v[144:145], v[104:105], v[134:135], v[144:145] op_sel_hi:[1,0,1]
	v_pk_mul_f32 v[210:211], v[200:201], v[138:139] op_sel_hi:[1,0]
	v_pk_fma_f32 v[102:103], v[184:185], v[102:103], v[210:211]
	v_pk_mul_f32 v[210:211], v[198:199], v[138:139] op_sel_hi:[1,0]
	v_pk_fma_f32 v[104:105], v[190:191], v[104:105], v[210:211]
	global_store_dwordx4 v158, v[102:105], s[30:31] nt
	s_nop 0
	global_load_dwordx4 v[102:105], v158, s[28:29] nt
	s_waitcnt vmcnt(40)
	v_pk_fma_f32 v[142:143], v[98:99], v[134:135], v[142:143] op_sel:[0,1,0]
	v_pk_fma_f32 v[144:145], v[100:101], v[134:135], v[144:145] op_sel:[0,1,0]
	v_pk_mul_f32 v[210:211], v[200:201], v[138:139] op_sel:[0,1]
	v_pk_fma_f32 v[98:99], v[184:185], v[98:99], v[210:211]
	v_pk_mul_f32 v[210:211], v[198:199], v[138:139] op_sel:[0,1]
	v_pk_fma_f32 v[100:101], v[190:191], v[100:101], v[210:211]
	global_store_dwordx4 v158, v[98:101], s[30:31] offset:1024 nt
	s_nop 0
	global_load_dwordx4 v[98:101], v158, s[28:29] offset:1024 nt
	s_waitcnt vmcnt(41)
	v_pk_fma_f32 v[142:143], v[94:95], v[136:137], v[142:143] op_sel_hi:[1,0,1]
	v_pk_fma_f32 v[144:145], v[96:97], v[136:137], v[144:145] op_sel_hi:[1,0,1]
	v_pk_mul_f32 v[210:211], v[200:201], v[140:141] op_sel_hi:[1,0]
	v_pk_fma_f32 v[94:95], v[184:185], v[94:95], v[210:211]
	v_pk_mul_f32 v[210:211], v[198:199], v[140:141] op_sel_hi:[1,0]
	v_pk_fma_f32 v[96:97], v[190:191], v[96:97], v[210:211]
	global_store_dwordx4 v158, v[94:97], s[30:31] offset:2048 nt
	s_nop 0
	global_load_dwordx4 v[94:97], v158, s[28:29] offset:2048 nt
	s_waitcnt vmcnt(42)
	v_pk_fma_f32 v[142:143], v[90:91], v[136:137], v[142:143] op_sel:[0,1,0]
	v_pk_fma_f32 v[144:145], v[92:93], v[136:137], v[144:145] op_sel:[0,1,0]
	v_pk_mul_f32 v[210:211], v[200:201], v[140:141] op_sel:[0,1]
	v_pk_fma_f32 v[90:91], v[184:185], v[90:91], v[210:211]
	v_pk_mul_f32 v[210:211], v[198:199], v[140:141] op_sel:[0,1]
	v_pk_fma_f32 v[92:93], v[190:191], v[92:93], v[210:211]
	global_store_dwordx4 v158, v[90:93], s[30:31] offset:3072 nt
	s_add_u32 s30, s30, 0x1000
	s_addc_u32 s31, s31, 0
	global_load_dwordx4 v[90:93], v158, s[28:29] offset:3072 nt
	s_add_u32 s28, s28, 0x1000
	s_addc_u32 s29, s29, 0
	ds_read_b128 v[134:137], v179 offset:64
	ds_read_b128 v[138:141], v179 offset:1088
	s_waitcnt lgkmcnt(2)
	s_waitcnt vmcnt(43)
	v_pk_fma_f32 v[142:143], v[86:87], v[202:203], v[142:143] op_sel_hi:[1,0,1]
	v_pk_fma_f32 v[144:145], v[88:89], v[202:203], v[144:145] op_sel_hi:[1,0,1]
	v_pk_mul_f32 v[210:211], v[200:201], v[206:207] op_sel_hi:[1,0]
	v_pk_fma_f32 v[86:87], v[184:185], v[86:87], v[210:211]
	v_pk_mul_f32 v[210:211], v[198:199], v[206:207] op_sel_hi:[1,0]
	v_pk_fma_f32 v[88:89], v[190:191], v[88:89], v[210:211]
	global_store_dwordx4 v158, v[86:89], s[30:31] nt
	s_nop 0
	global_load_dwordx4 v[86:89], v158, s[28:29] nt
	s_waitcnt vmcnt(44)
	v_pk_fma_f32 v[142:143], v[82:83], v[202:203], v[142:143] op_sel:[0,1,0]
	v_pk_fma_f32 v[144:145], v[84:85], v[202:203], v[144:145] op_sel:[0,1,0]
	v_pk_mul_f32 v[210:211], v[200:201], v[206:207] op_sel:[0,1]
	v_pk_fma_f32 v[82:83], v[184:185], v[82:83], v[210:211]
	v_pk_mul_f32 v[210:211], v[198:199], v[206:207] op_sel:[0,1]
	v_pk_fma_f32 v[84:85], v[190:191], v[84:85], v[210:211]
	global_store_dwordx4 v158, v[82:85], s[30:31] offset:1024 nt
	s_nop 0
	global_load_dwordx4 v[82:85], v158, s[28:29] offset:1024 nt
	s_waitcnt vmcnt(45)
	v_pk_fma_f32 v[142:143], v[78:79], v[204:205], v[142:143] op_sel_hi:[1,0,1]
	v_pk_fma_f32 v[144:145], v[80:81], v[204:205], v[144:145] op_sel_hi:[1,0,1]
	v_pk_mul_f32 v[210:211], v[200:201], v[208:209] op_sel_hi:[1,0]
	v_pk_fma_f32 v[78:79], v[184:185], v[78:79], v[210:211]
	v_pk_mul_f32 v[210:211], v[198:199], v[208:209] op_sel_hi:[1,0]
	v_pk_fma_f32 v[80:81], v[190:191], v[80:81], v[210:211]
	global_store_dwordx4 v158, v[78:81], s[30:31] offset:2048 nt
	s_nop 0
	global_load_dwordx4 v[78:81], v158, s[28:29] offset:2048 nt
	s_waitcnt vmcnt(46)
; __device__ __forceinline__ void mlstm_decode_wave(const Params& P, unsigned char* wl, int sh) {
;     ...
;     const float* C0 = P.in[4] + (size_t)sh * 65536 + 4 * lane; float* C1 = P.out + OUT_SC + (size_t)sh * 65536 + 4 * lane;
;     f32x4 part = (f32x4){0.f, 0.f, 0.f, 0.f}; const f32x4 wv = wi * v4;
; #pragma unroll 1
;     for (int dk0 = 0; dk0 < 256; dk0 += 32) { f32x4 c[32];
; #pragma unroll
;         for (int i = 0; i < 32; ++i) c[i] = __builtin_nontemporal_load((const f32x4*)(C0 + (dk0 + i) * 256));
; #pragma unroll
;         for (int i = 0; i < 32; ++i) { const float qd = sq[dk0 + i], kd = sk[dk0 + i]; part += qd * c[i]; __builtin_nontemporal_store(wc * c[i] + kd * wv, (f32x4*)(C1 + (dk0 + i) * 256)); } }
	v_pk_fma_f32 v[142:143], v[74:75], v[204:205], v[142:143] op_sel:[0,1,0]
	v_pk_fma_f32 v[144:145], v[76:77], v[204:205], v[144:145] op_sel:[0,1,0]
	v_pk_mul_f32 v[210:211], v[200:201], v[208:209] op_sel:[0,1]
	v_pk_fma_f32 v[74:75], v[184:185], v[74:75], v[210:211]
	v_pk_mul_f32 v[210:211], v[198:199], v[208:209] op_sel:[0,1]
	v_pk_fma_f32 v[76:77], v[190:191], v[76:77], v[210:211]
	global_store_dwordx4 v158, v[74:77], s[30:31] offset:3072 nt
	s_add_u32 s30, s30, 0x1000
	s_addc_u32 s31, s31, 0
	global_load_dwordx4 v[74:77], v158, s[28:29] offset:3072 nt
	s_add_u32 s28, s28, 0x1000
	s_addc_u32 s29, s29, 0
	ds_read_b128 v[202:205], v179 offset:80
	ds_read_b128 v[206:209], v179 offset:1104
	s_waitcnt lgkmcnt(2)
	s_waitcnt vmcnt(47)
	v_pk_fma_f32 v[142:143], v[70:71], v[134:135], v[142:143] op_sel_hi:[1,0,1]
	v_pk_fma_f32 v[144:145], v[72:73], v[134:135], v[144:145] op_sel_hi:[1,0,1]
	v_pk_mul_f32 v[210:211], v[200:201], v[138:139] op_sel_hi:[1,0]
	v_pk_fma_f32 v[70:71], v[184:185], v[70:71], v[210:211]
	v_pk_mul_f32 v[210:211], v[198:199], v[138:139] op_sel_hi:[1,0]
	v_pk_fma_f32 v[72:73], v[190:191], v[72:73], v[210:211]
	global_store_dwordx4 v158, v[70:73], s[30:31] nt
	s_nop 0
	global_load_dwordx4 v[70:73], v158, s[28:29] nt
	s_waitcnt vmcnt(48)
	v_pk_fma_f32 v[142:143], v[66:67], v[134:135], v[142:143] op_sel:[0,1,0]
	v_pk_fma_f32 v[144:145], v[68:69], v[134:135], v[144:145] op_sel:[0,1,0]
	v_pk_mul_f32 v[210:211], v[200:201], v[138:139] op_sel:[0,1]
	v_pk_fma_f32 v[66:67], v[184:185], v[66:67], v[210:211]
	v_pk_mul_f32 v[210:211], v[198:199], v[138:139] op_sel:[0,1]
	v_pk_fma_f32 v[68:69], v[190:191], v[68:69], v[210:211]
	global_store_dwordx4 v158, v[66:69], s[30:31] offset:1024 nt
	s_nop 0
	global_load_dwordx4 v[66:69], v158, s[28:29] offset:1024 nt
	s_waitcnt vmcnt(49)
	v_pk_fma_f32 v[142:143], v[62:63], v[136:137], v[142:143] op_sel_hi:[1,0,1]
	v_pk_fma_f32 v[144:145], v[64:65], v[136:137], v[144:145] op_sel_hi:[1,0,1]
	v_pk_mul_f32 v[210:211], v[200:201], v[140:141] op_sel_hi:[1,0]
	v_pk_fma_f32 v[62:63], v[184:185], v[62:63], v[210:211]
	v_pk_mul_f32 v[210:211], v[198:199], v[140:141] op_sel_hi:[1,0]
	v_pk_fma_f32 v[64:65], v[190:191], v[64:65], v[210:211]
	global_store_dwordx4 v158, v[62:65], s[30:31] offset:2048 nt
	s_nop 0
	global_load_dwordx4 v[62:65], v158, s[28:29] offset:2048 nt
	s_waitcnt vmcnt(50)
	v_pk_fma_f32 v[142:143], v[58:59], v[136:137], v[142:143] op_sel:[0,1,0]
	v_pk_fma_f32 v[144:145], v[60:61], v[136:137], v[144:145] op_sel:[0,1,0]
	v_pk_mul_f32 v[210:211], v[200:201], v[140:141] op_sel:[0,1]
	v_pk_fma_f32 v[58:59], v[184:185], v[58:59], v[210:211]
	v_pk_mul_f32 v[210:211], v[198:199], v[140:141] op_sel:[0,1]
	v_pk_fma_f32 v[60:61], v[190:191], v[60:61], v[210:211]
	global_store_dwordx4 v158, v[58:61], s[30:31] offset:3072 nt
	s_add_u32 s30, s30, 0x1000
	s_addc_u32 s31, s31, 0
	global_load_dwordx4 v[58:61], v158, s[28:29] offset:3072 nt
	s_add_u32 s28, s28, 0x1000
	s_addc_u32 s29, s29, 0
	ds_read_b128 v[134:137], v179 offset:96
	ds_read_b128 v[138:141], v179 offset:1120
	s_waitcnt lgkmcnt(2)
	s_waitcnt vmcnt(51)
	v_pk_fma_f32 v[142:143], v[54:55], v[202:203], v[142:143] op_sel_hi:[1,0,1]
	v_pk_fma_f32 v[144:145], v[56:57], v[202:203], v[144:145] op_sel_hi:[1,0,1]
	v_pk_mul_f32 v[210:211], v[200:201], v[206:207] op_sel_hi:[1,0]
	v_pk_fma_f32 v[54:55], v[184:185], v[54:55], v[210:211]
	v_pk_mul_f32 v[210:211], v[198:199], v[206:207] op_sel_hi:[1,0]
	v_pk_fma_f32 v[56:57], v[190:191], v[56:57], v[210:211]
	global_store_dwordx4 v158, v[54:57], s[30:31] nt
	s_nop 0
	global_load_dwordx4 v[54:57], v158, s[28:29] nt
	s_waitcnt vmcnt(52)
	v_pk_fma_f32 v[142:143], v[50:51], v[202:203], v[142:143] op_sel:[0,1,0]
	v_pk_fma_f32 v[144:145], v[52:53], v[202:203], v[144:145] op_sel:[0,1,0]
	v_pk_mul_f32 v[210:211], v[200:201], v[206:207] op_sel:[0,1]
	v_pk_fma_f32 v[50:51], v[184:185], v[50:51], v[210:211]
	v_pk_mul_f32 v[210:211], v[198:199], v[206:207] op_sel:[0,1]
	v_pk_fma_f32 v[52:53], v[190:191], v[52:53], v[210:211]
	global_store_dwordx4 v158, v[50:53], s[30:31] offset:1024 nt
	s_nop 0
	global_load_dwordx4 v[50:53], v158, s[28:29] offset:1024 nt
	s_waitcnt vmcnt(53)
	v_pk_fma_f32 v[142:143], v[46:47], v[204:205], v[142:143] op_sel_hi:[1,0,1]
	v_pk_fma_f32 v[144:145], v[48:49], v[204:205], v[144:145] op_sel_hi:[1,0,1]
	v_pk_mul_f32 v[210:211], v[200:201], v[208:209] op_sel_hi:[1,0]
	v_pk_fma_f32 v[46:47], v[184:185], v[46:47], v[210:211]
	v_pk_mul_f32 v[210:211], v[198:199], v[208:209] op_sel_hi:[1,0]
	v_pk_fma_f32 v[48:49], v[190:191], v[48:49], v[210:211]
	global_store_dwordx4 v158, v[46:49], s[30:31] offset:2048 nt
	s_nop 0
	global_load_dwordx4 v[46:49], v158, s[28:29] offset:2048 nt
	s_waitcnt vmcnt(54)
	v_pk_fma_f32 v[142:143], v[42:43], v[204:205], v[142:143] op_sel:[0,1,0]
	v_pk_fma_f32 v[144:145], v[44:45], v[204:205], v[144:145] op_sel:[0,1,0]
	v_pk_mul_f32 v[210:211], v[200:201], v[208:209] op_sel:[0,1]
	v_pk_fma_f32 v[42:43], v[184:185], v[42:43], v[210:211]
	v_pk_mul_f32 v[210:211], v[198:199], v[208:209] op_sel:[0,1]
	v_pk_fma_f32 v[44:45], v[190:191], v[44:45], v[210:211]
	global_store_dwordx4 v158, v[42:45], s[30:31] offset:3072 nt
	s_add_u32 s30, s30, 0x1000
	s_addc_u32 s31, s31, 0
	global_load_dwordx4 v[42:45], v158, s[28:29] offset:3072 nt
	s_add_u32 s28, s28, 0x1000
	s_addc_u32 s29, s29, 0
	ds_read_b128 v[202:205], v179 offset:112
	ds_read_b128 v[206:209], v179 offset:1136
	s_waitcnt lgkmcnt(2)
	s_waitcnt vmcnt(55)
; __device__ __forceinline__ void mlstm_decode_wave(const Params& P, unsigned char* wl, int sh) {
;     ...
;     const float* C0 = P.in[4] + (size_t)sh * 65536 + 4 * lane; float* C1 = P.out + OUT_SC + (size_t)sh * 65536 + 4 * lane;
;     f32x4 part = (f32x4){0.f, 0.f, 0.f, 0.f}; const f32x4 wv = wi * v4;
; #pragma unroll 1
;     for (int dk0 = 0; dk0 < 256; dk0 += 32) { f32x4 c[32];
; #pragma unroll
;         for (int i = 0; i < 32; ++i) c[i] = __builtin_nontemporal_load((const f32x4*)(C0 + (dk0 + i) * 256));
; #pragma unroll
;         for (int i = 0; i < 32; ++i) { const float qd = sq[dk0 + i], kd = sk[dk0 + i]; part += qd * c[i]; __builtin_nontemporal_store(wc * c[i] + kd * wv, (f32x4*)(C1 + (dk0 + i) * 256)); } }
	v_pk_fma_f32 v[142:143], v[38:39], v[134:135], v[142:143] op_sel_hi:[1,0,1]
	v_pk_fma_f32 v[144:145], v[40:41], v[134:135], v[144:145] op_sel_hi:[1,0,1]
	v_pk_mul_f32 v[210:211], v[200:201], v[138:139] op_sel_hi:[1,0]
	v_pk_fma_f32 v[38:39], v[184:185], v[38:39], v[210:211]
	v_pk_mul_f32 v[210:211], v[198:199], v[138:139] op_sel_hi:[1,0]
	v_pk_fma_f32 v[40:41], v[190:191], v[40:41], v[210:211]
	global_store_dwordx4 v158, v[38:41], s[30:31] nt
	s_nop 0
	global_load_dwordx4 v[38:41], v158, s[28:29] nt
	s_waitcnt vmcnt(56)
	v_pk_fma_f32 v[142:143], v[34:35], v[134:135], v[142:143] op_sel:[0,1,0]
	v_pk_fma_f32 v[144:145], v[36:37], v[134:135], v[144:145] op_sel:[0,1,0]
	v_pk_mul_f32 v[210:211], v[200:201], v[138:139] op_sel:[0,1]
	v_pk_fma_f32 v[34:35], v[184:185], v[34:35], v[210:211]
	v_pk_mul_f32 v[210:211], v[198:199], v[138:139] op_sel:[0,1]
	v_pk_fma_f32 v[36:37], v[190:191], v[36:37], v[210:211]
	global_store_dwordx4 v158, v[34:37], s[30:31] offset:1024 nt
	s_nop 0
	global_load_dwordx4 v[34:37], v158, s[28:29] offset:1024 nt
	s_waitcnt vmcnt(57)
	v_pk_fma_f32 v[142:143], v[30:31], v[136:137], v[142:143] op_sel_hi:[1,0,1]
	v_pk_fma_f32 v[144:145], v[32:33], v[136:137], v[144:145] op_sel_hi:[1,0,1]
	v_pk_mul_f32 v[210:211], v[200:201], v[140:141] op_sel_hi:[1,0]
	v_pk_fma_f32 v[30:31], v[184:185], v[30:31], v[210:211]
	v_pk_mul_f32 v[210:211], v[198:199], v[140:141] op_sel_hi:[1,0]
	v_pk_fma_f32 v[32:33], v[190:191], v[32:33], v[210:211]
	global_store_dwordx4 v158, v[30:33], s[30:31] offset:2048 nt
	s_nop 0
	global_load_dwordx4 v[30:33], v158, s[28:29] offset:2048 nt
	s_waitcnt vmcnt(58)
	v_pk_fma_f32 v[142:143], v[26:27], v[136:137], v[142:143] op_sel:[0,1,0]
	v_pk_fma_f32 v[144:145], v[28:29], v[136:137], v[144:145] op_sel:[0,1,0]
	v_pk_mul_f32 v[210:211], v[200:201], v[140:141] op_sel:[0,1]
	v_pk_fma_f32 v[26:27], v[184:185], v[26:27], v[210:211]
	v_pk_mul_f32 v[210:211], v[198:199], v[140:141] op_sel:[0,1]
	v_pk_fma_f32 v[28:29], v[190:191], v[28:29], v[210:211]
	global_store_dwordx4 v158, v[26:29], s[30:31] offset:3072 nt
	s_add_u32 s30, s30, 0x1000
	s_addc_u32 s31, s31, 0
	global_load_dwordx4 v[26:29], v158, s[28:29] offset:3072 nt
	s_add_u32 s28, s28, 0x1000
	s_addc_u32 s29, s29, 0
	ds_read_b128 v[134:137], v179 offset:128
	ds_read_b128 v[138:141], v179 offset:1152
	s_waitcnt lgkmcnt(2)
	s_waitcnt vmcnt(59)
	v_pk_fma_f32 v[142:143], v[22:23], v[202:203], v[142:143] op_sel_hi:[1,0,1]
	v_pk_fma_f32 v[144:145], v[24:25], v[202:203], v[144:145] op_sel_hi:[1,0,1]
	v_pk_mul_f32 v[210:211], v[200:201], v[206:207] op_sel_hi:[1,0]
	v_pk_fma_f32 v[22:23], v[184:185], v[22:23], v[210:211]
	v_pk_mul_f32 v[210:211], v[198:199], v[206:207] op_sel_hi:[1,0]
	v_pk_fma_f32 v[24:25], v[190:191], v[24:25], v[210:211]
	global_store_dwordx4 v158, v[22:25], s[30:31] nt
	s_nop 0
	global_load_dwordx4 v[22:25], v158, s[28:29] nt
	s_waitcnt vmcnt(60)
	v_pk_fma_f32 v[142:143], v[18:19], v[202:203], v[142:143] op_sel:[0,1,0]
	v_pk_fma_f32 v[144:145], v[20:21], v[202:203], v[144:145] op_sel:[0,1,0]
	v_pk_mul_f32 v[210:211], v[200:201], v[206:207] op_sel:[0,1]
	v_pk_fma_f32 v[18:19], v[184:185], v[18:19], v[210:211]
	v_pk_mul_f32 v[210:211], v[198:199], v[206:207] op_sel:[0,1]
	v_pk_fma_f32 v[20:21], v[190:191], v[20:21], v[210:211]
	global_store_dwordx4 v158, v[18:21], s[30:31] offset:1024 nt
	s_nop 0
	global_load_dwordx4 v[18:21], v158, s[28:29] offset:1024 nt
	s_waitcnt vmcnt(61)
	v_pk_fma_f32 v[142:143], v[14:15], v[204:205], v[142:143] op_sel_hi:[1,0,1]
	v_pk_fma_f32 v[144:145], v[16:17], v[204:205], v[144:145] op_sel_hi:[1,0,1]
	v_pk_mul_f32 v[210:211], v[200:201], v[208:209] op_sel_hi:[1,0]
	v_pk_fma_f32 v[14:15], v[184:185], v[14:15], v[210:211]
	v_pk_mul_f32 v[210:211], v[198:199], v[208:209] op_sel_hi:[1,0]
	v_pk_fma_f32 v[16:17], v[190:191], v[16:17], v[210:211]
	global_store_dwordx4 v158, v[14:17], s[30:31] offset:2048 nt
	s_nop 0
	global_load_dwordx4 v[14:17], v158, s[28:29] offset:2048 nt
	s_waitcnt vmcnt(62)
	v_pk_fma_f32 v[142:143], v[10:11], v[204:205], v[142:143] op_sel:[0,1,0]
	v_pk_fma_f32 v[144:145], v[12:13], v[204:205], v[144:145] op_sel:[0,1,0]
	v_pk_mul_f32 v[210:211], v[200:201], v[208:209] op_sel:[0,1]
	v_pk_fma_f32 v[10:11], v[184:185], v[10:11], v[210:211]
	v_pk_mul_f32 v[210:211], v[198:199], v[208:209] op_sel:[0,1]
	v_pk_fma_f32 v[12:13], v[190:191], v[12:13], v[210:211]
	global_store_dwordx4 v158, v[10:13], s[30:31] offset:3072 nt
	s_add_u32 s30, s30, 0x1000
	s_addc_u32 s31, s31, 0
	global_load_dwordx4 v[10:13], v158, s[28:29] offset:3072 nt
	s_add_u32 s28, s28, 0x1000
	s_addc_u32 s29, s29, 0
	ds_read_b128 v[202:205], v179 offset:144
	ds_read_b128 v[206:209], v179 offset:1168
	s_waitcnt lgkmcnt(2)
	s_waitcnt vmcnt(62)
	v_pk_fma_f32 v[142:143], v[232:233], v[134:135], v[142:143] op_sel_hi:[1,0,1]
	v_pk_fma_f32 v[144:145], v[234:235], v[134:135], v[144:145] op_sel_hi:[1,0,1]
	v_pk_mul_f32 v[210:211], v[200:201], v[138:139] op_sel_hi:[1,0]
	v_pk_fma_f32 v[232:233], v[184:185], v[232:233], v[210:211]
	v_pk_mul_f32 v[210:211], v[198:199], v[138:139] op_sel_hi:[1,0]
	v_pk_fma_f32 v[234:235], v[190:191], v[234:235], v[210:211]
	global_store_dwordx4 v158, v[232:235], s[30:31] nt
	s_nop 0
	global_load_dwordx4 v[232:235], v158, s[28:29] nt
	s_waitcnt vmcnt(62)
	v_pk_fma_f32 v[142:143], v[130:131], v[134:135], v[142:143] op_sel:[0,1,0]
	v_pk_fma_f32 v[144:145], v[132:133], v[134:135], v[144:145] op_sel:[0,1,0]
	v_pk_mul_f32 v[210:211], v[200:201], v[138:139] op_sel:[0,1]
	v_pk_fma_f32 v[130:131], v[184:185], v[130:131], v[210:211]
	v_pk_mul_f32 v[210:211], v[198:199], v[138:139] op_sel:[0,1]
	v_pk_fma_f32 v[132:133], v[190:191], v[132:133], v[210:211]
	global_store_dwordx4 v158, v[130:133], s[30:31] offset:1024 nt
	s_nop 0
	global_load_dwordx4 v[130:133], v158, s[28:29] offset:1024 nt
	s_waitcnt vmcnt(62)
; __device__ __forceinline__ void mlstm_decode_wave(const Params& P, unsigned char* wl, int sh) {
;     ...
;     const float* C0 = P.in[4] + (size_t)sh * 65536 + 4 * lane; float* C1 = P.out + OUT_SC + (size_t)sh * 65536 + 4 * lane;
;     f32x4 part = (f32x4){0.f, 0.f, 0.f, 0.f}; const f32x4 wv = wi * v4;
; #pragma unroll 1
;     for (int dk0 = 0; dk0 < 256; dk0 += 32) { f32x4 c[32];
; #pragma unroll
;         for (int i = 0; i < 32; ++i) c[i] = __builtin_nontemporal_load((const f32x4*)(C0 + (dk0 + i) * 256));
; #pragma unroll
;         for (int i = 0; i < 32; ++i) { const float qd = sq[dk0 + i], kd = sk[dk0 + i]; part += qd * c[i]; __builtin_nontemporal_store(wc * c[i] + kd * wv, (f32x4*)(C1 + (dk0 + i) * 256)); } }
	v_pk_fma_f32 v[142:143], v[126:127], v[136:137], v[142:143] op_sel_hi:[1,0,1]
	v_pk_fma_f32 v[144:145], v[128:129], v[136:137], v[144:145] op_sel_hi:[1,0,1]
	v_pk_mul_f32 v[210:211], v[200:201], v[140:141] op_sel_hi:[1,0]
	v_pk_fma_f32 v[126:127], v[184:185], v[126:127], v[210:211]
	v_pk_mul_f32 v[210:211], v[198:199], v[140:141] op_sel_hi:[1,0]
	v_pk_fma_f32 v[128:129], v[190:191], v[128:129], v[210:211]
	global_store_dwordx4 v158, v[126:129], s[30:31] offset:2048 nt
	s_nop 0
	global_load_dwordx4 v[126:129], v158, s[28:29] offset:2048 nt
	s_waitcnt vmcnt(62)
	v_pk_fma_f32 v[142:143], v[122:123], v[136:137], v[142:143] op_sel:[0,1,0]
	v_pk_fma_f32 v[144:145], v[124:125], v[136:137], v[144:145] op_sel:[0,1,0]
	v_pk_mul_f32 v[210:211], v[200:201], v[140:141] op_sel:[0,1]
	v_pk_fma_f32 v[122:123], v[184:185], v[122:123], v[210:211]
	v_pk_mul_f32 v[210:211], v[198:199], v[140:141] op_sel:[0,1]
	v_pk_fma_f32 v[124:125], v[190:191], v[124:125], v[210:211]
	global_store_dwordx4 v158, v[122:125], s[30:31] offset:3072 nt
	s_add_u32 s30, s30, 0x1000
	s_addc_u32 s31, s31, 0
	global_load_dwordx4 v[122:125], v158, s[28:29] offset:3072 nt
	s_add_u32 s28, s28, 0x1000
	s_addc_u32 s29, s29, 0
	ds_read_b128 v[134:137], v179 offset:160
	ds_read_b128 v[138:141], v179 offset:1184
	s_waitcnt lgkmcnt(2)
	s_waitcnt vmcnt(62)
	v_pk_fma_f32 v[142:143], v[118:119], v[202:203], v[142:143] op_sel_hi:[1,0,1]
	v_pk_fma_f32 v[144:145], v[120:121], v[202:203], v[144:145] op_sel_hi:[1,0,1]
	v_pk_mul_f32 v[210:211], v[200:201], v[206:207] op_sel_hi:[1,0]
	v_pk_fma_f32 v[118:119], v[184:185], v[118:119], v[210:211]
	v_pk_mul_f32 v[210:211], v[198:199], v[206:207] op_sel_hi:[1,0]
	v_pk_fma_f32 v[120:121], v[190:191], v[120:121], v[210:211]
	global_store_dwordx4 v158, v[118:121], s[30:31] nt
	s_nop 0
	global_load_dwordx4 v[118:121], v158, s[28:29] nt
	s_waitcnt vmcnt(62)
	v_pk_fma_f32 v[142:143], v[114:115], v[202:203], v[142:143] op_sel:[0,1,0]
	v_pk_fma_f32 v[144:145], v[116:117], v[202:203], v[144:145] op_sel:[0,1,0]
	v_pk_mul_f32 v[210:211], v[200:201], v[206:207] op_sel:[0,1]
	v_pk_fma_f32 v[114:115], v[184:185], v[114:115], v[210:211]
	v_pk_mul_f32 v[210:211], v[198:199], v[206:207] op_sel:[0,1]
	v_pk_fma_f32 v[116:117], v[190:191], v[116:117], v[210:211]
	global_store_dwordx4 v158, v[114:117], s[30:31] offset:1024 nt
	s_nop 0
	global_load_dwordx4 v[114:117], v158, s[28:29] offset:1024 nt
	s_waitcnt vmcnt(62)
	v_pk_fma_f32 v[142:143], v[110:111], v[204:205], v[142:143] op_sel_hi:[1,0,1]
	v_pk_fma_f32 v[144:145], v[112:113], v[204:205], v[144:145] op_sel_hi:[1,0,1]
	v_pk_mul_f32 v[210:211], v[200:201], v[208:209] op_sel_hi:[1,0]
	v_pk_fma_f32 v[110:111], v[184:185], v[110:111], v[210:211]
	v_pk_mul_f32 v[210:211], v[198:199], v[208:209] op_sel_hi:[1,0]
	v_pk_fma_f32 v[112:113], v[190:191], v[112:113], v[210:211]
	global_store_dwordx4 v158, v[110:113], s[30:31] offset:2048 nt
	s_nop 0
	global_load_dwordx4 v[110:113], v158, s[28:29] offset:2048 nt
	s_waitcnt vmcnt(62)
	v_pk_fma_f32 v[142:143], v[106:107], v[204:205], v[142:143] op_sel:[0,1,0]
	v_pk_fma_f32 v[144:145], v[108:109], v[204:205], v[144:145] op_sel:[0,1,0]
	v_pk_mul_f32 v[210:211], v[200:201], v[208:209] op_sel:[0,1]
	v_pk_fma_f32 v[106:107], v[184:185], v[106:107], v[210:211]
	v_pk_mul_f32 v[210:211], v[198:199], v[208:209] op_sel:[0,1]
	v_pk_fma_f32 v[108:109], v[190:191], v[108:109], v[210:211]
	global_store_dwordx4 v158, v[106:109], s[30:31] offset:3072 nt
	s_add_u32 s30, s30, 0x1000
	s_addc_u32 s31, s31, 0
	global_load_dwordx4 v[106:109], v158, s[28:29] offset:3072 nt
	s_add_u32 s28, s28, 0x1000
	s_addc_u32 s29, s29, 0
	ds_read_b128 v[202:205], v179 offset:176
	ds_read_b128 v[206:209], v179 offset:1200
	s_waitcnt lgkmcnt(2)
	s_waitcnt vmcnt(62)
	v_pk_fma_f32 v[142:143], v[102:103], v[134:135], v[142:143] op_sel_hi:[1,0,1]
	v_pk_fma_f32 v[144:145], v[104:105], v[134:135], v[144:145] op_sel_hi:[1,0,1]
	v_pk_mul_f32 v[210:211], v[200:201], v[138:139] op_sel_hi:[1,0]
	v_pk_fma_f32 v[102:103], v[184:185], v[102:103], v[210:211]
	v_pk_mul_f32 v[210:211], v[198:199], v[138:139] op_sel_hi:[1,0]
	v_pk_fma_f32 v[104:105], v[190:191], v[104:105], v[210:211]
	global_store_dwordx4 v158, v[102:105], s[30:31] nt
	s_nop 0
	global_load_dwordx4 v[102:105], v158, s[28:29] nt
	s_waitcnt vmcnt(62)
	v_pk_fma_f32 v[142:143], v[98:99], v[134:135], v[142:143] op_sel:[0,1,0]
	v_pk_fma_f32 v[144:145], v[100:101], v[134:135], v[144:145] op_sel:[0,1,0]
	v_pk_mul_f32 v[210:211], v[200:201], v[138:139] op_sel:[0,1]
	v_pk_fma_f32 v[98:99], v[184:185], v[98:99], v[210:211]
	v_pk_mul_f32 v[210:211], v[198:199], v[138:139] op_sel:[0,1]
	v_pk_fma_f32 v[100:101], v[190:191], v[100:101], v[210:211]
	global_store_dwordx4 v158, v[98:101], s[30:31] offset:1024 nt
	s_nop 0
	global_load_dwordx4 v[98:101], v158, s[28:29] offset:1024 nt
	s_waitcnt vmcnt(62)
	v_pk_fma_f32 v[142:143], v[94:95], v[136:137], v[142:143] op_sel_hi:[1,0,1]
	v_pk_fma_f32 v[144:145], v[96:97], v[136:137], v[144:145] op_sel_hi:[1,0,1]
	v_pk_mul_f32 v[210:211], v[200:201], v[140:141] op_sel_hi:[1,0]
	v_pk_fma_f32 v[94:95], v[184:185], v[94:95], v[210:211]
	v_pk_mul_f32 v[210:211], v[198:199], v[140:141] op_sel_hi:[1,0]
	v_pk_fma_f32 v[96:97], v[190:191], v[96:97], v[210:211]
	global_store_dwordx4 v158, v[94:97], s[30:31] offset:2048 nt
	s_nop 0
	global_load_dwordx4 v[94:97], v158, s[28:29] offset:2048 nt
	s_waitcnt vmcnt(62)
; __device__ __forceinline__ void mlstm_decode_wave(const Params& P, unsigned char* wl, int sh) {
;     ...
;     const float* C0 = P.in[4] + (size_t)sh * 65536 + 4 * lane; float* C1 = P.out + OUT_SC + (size_t)sh * 65536 + 4 * lane;
;     f32x4 part = (f32x4){0.f, 0.f, 0.f, 0.f}; const f32x4 wv = wi * v4;
; #pragma unroll 1
;     for (int dk0 = 0; dk0 < 256; dk0 += 32) { f32x4 c[32];
; #pragma unroll
;         for (int i = 0; i < 32; ++i) c[i] = __builtin_nontemporal_load((const f32x4*)(C0 + (dk0 + i) * 256));
; #pragma unroll
;         for (int i = 0; i < 32; ++i) { const float qd = sq[dk0 + i], kd = sk[dk0 + i]; part += qd * c[i]; __builtin_nontemporal_store(wc * c[i] + kd * wv, (f32x4*)(C1 + (dk0 + i) * 256)); } }
	v_pk_fma_f32 v[142:143], v[90:91], v[136:137], v[142:143] op_sel:[0,1,0]
	v_pk_fma_f32 v[144:145], v[92:93], v[136:137], v[144:145] op_sel:[0,1,0]
	v_pk_mul_f32 v[210:211], v[200:201], v[140:141] op_sel:[0,1]
	v_pk_fma_f32 v[90:91], v[184:185], v[90:91], v[210:211]
	v_pk_mul_f32 v[210:211], v[198:199], v[140:141] op_sel:[0,1]
	v_pk_fma_f32 v[92:93], v[190:191], v[92:93], v[210:211]
	global_store_dwordx4 v158, v[90:93], s[30:31] offset:3072 nt
	s_add_u32 s30, s30, 0x1000
	s_addc_u32 s31, s31, 0
	global_load_dwordx4 v[90:93], v158, s[28:29] offset:3072 nt
	s_add_u32 s28, s28, 0x1000
	s_addc_u32 s29, s29, 0
	ds_read_b128 v[134:137], v179 offset:192
	ds_read_b128 v[138:141], v179 offset:1216
	s_waitcnt lgkmcnt(2)
	s_waitcnt vmcnt(62)
	v_pk_fma_f32 v[142:143], v[86:87], v[202:203], v[142:143] op_sel_hi:[1,0,1]
	v_pk_fma_f32 v[144:145], v[88:89], v[202:203], v[144:145] op_sel_hi:[1,0,1]
	v_pk_mul_f32 v[210:211], v[200:201], v[206:207] op_sel_hi:[1,0]
	v_pk_fma_f32 v[86:87], v[184:185], v[86:87], v[210:211]
	v_pk_mul_f32 v[210:211], v[198:199], v[206:207] op_sel_hi:[1,0]
	v_pk_fma_f32 v[88:89], v[190:191], v[88:89], v[210:211]
	global_store_dwordx4 v158, v[86:89], s[30:31] nt
	s_nop 0
	global_load_dwordx4 v[86:89], v158, s[28:29] nt
	s_waitcnt vmcnt(62)
	v_pk_fma_f32 v[142:143], v[82:83], v[202:203], v[142:143] op_sel:[0,1,0]
	v_pk_fma_f32 v[144:145], v[84:85], v[202:203], v[144:145] op_sel:[0,1,0]
	v_pk_mul_f32 v[210:211], v[200:201], v[206:207] op_sel:[0,1]
	v_pk_fma_f32 v[82:83], v[184:185], v[82:83], v[210:211]
	v_pk_mul_f32 v[210:211], v[198:199], v[206:207] op_sel:[0,1]
	v_pk_fma_f32 v[84:85], v[190:191], v[84:85], v[210:211]
	global_store_dwordx4 v158, v[82:85], s[30:31] offset:1024 nt
	s_nop 0
	global_load_dwordx4 v[82:85], v158, s[28:29] offset:1024 nt
	s_waitcnt vmcnt(62)
	v_pk_fma_f32 v[142:143], v[78:79], v[204:205], v[142:143] op_sel_hi:[1,0,1]
	v_pk_fma_f32 v[144:145], v[80:81], v[204:205], v[144:145] op_sel_hi:[1,0,1]
	v_pk_mul_f32 v[210:211], v[200:201], v[208:209] op_sel_hi:[1,0]
	v_pk_fma_f32 v[78:79], v[184:185], v[78:79], v[210:211]
	v_pk_mul_f32 v[210:211], v[198:199], v[208:209] op_sel_hi:[1,0]
	v_pk_fma_f32 v[80:81], v[190:191], v[80:81], v[210:211]
	global_store_dwordx4 v158, v[78:81], s[30:31] offset:2048 nt
	s_nop 0
	global_load_dwordx4 v[78:81], v158, s[28:29] offset:2048 nt
	s_waitcnt vmcnt(62)
	v_pk_fma_f32 v[142:143], v[74:75], v[204:205], v[142:143] op_sel:[0,1,0]
	v_pk_fma_f32 v[144:145], v[76:77], v[204:205], v[144:145] op_sel:[0,1,0]
	v_pk_mul_f32 v[210:211], v[200:201], v[208:209] op_sel:[0,1]
	v_pk_fma_f32 v[74:75], v[184:185], v[74:75], v[210:211]
	v_pk_mul_f32 v[210:211], v[198:199], v[208:209] op_sel:[0,1]
	v_pk_fma_f32 v[76:77], v[190:191], v[76:77], v[210:211]
	global_store_dwordx4 v158, v[74:77], s[30:31] offset:3072 nt
	s_add_u32 s30, s30, 0x1000
	s_addc_u32 s31, s31, 0
	global_load_dwordx4 v[74:77], v158, s[28:29] offset:3072 nt
	s_add_u32 s28, s28, 0x1000
	s_addc_u32 s29, s29, 0
	ds_read_b128 v[202:205], v179 offset:208
	ds_read_b128 v[206:209], v179 offset:1232
	s_waitcnt lgkmcnt(2)
	s_waitcnt vmcnt(62)
	v_pk_fma_f32 v[142:143], v[70:71], v[134:135], v[142:143] op_sel_hi:[1,0,1]
	v_pk_fma_f32 v[144:145], v[72:73], v[134:135], v[144:145] op_sel_hi:[1,0,1]
	v_pk_mul_f32 v[210:211], v[200:201], v[138:139] op_sel_hi:[1,0]
	v_pk_fma_f32 v[70:71], v[184:185], v[70:71], v[210:211]
	v_pk_mul_f32 v[210:211], v[198:199], v[138:139] op_sel_hi:[1,0]
	v_pk_fma_f32 v[72:73], v[190:191], v[72:73], v[210:211]
	global_store_dwordx4 v158, v[70:73], s[30:31] nt
	s_nop 0
	global_load_dwordx4 v[70:73], v158, s[28:29] nt
	s_waitcnt vmcnt(62)
	v_pk_fma_f32 v[142:143], v[66:67], v[134:135], v[142:143] op_sel:[0,1,0]
	v_pk_fma_f32 v[144:145], v[68:69], v[134:135], v[144:145] op_sel:[0,1,0]
	v_pk_mul_f32 v[210:211], v[200:201], v[138:139] op_sel:[0,1]
	v_pk_fma_f32 v[66:67], v[184:185], v[66:67], v[210:211]
	v_pk_mul_f32 v[210:211], v[198:199], v[138:139] op_sel:[0,1]
	v_pk_fma_f32 v[68:69], v[190:191], v[68:69], v[210:211]
	global_store_dwordx4 v158, v[66:69], s[30:31] offset:1024 nt
	s_nop 0
	global_load_dwordx4 v[66:69], v158, s[28:29] offset:1024 nt
	s_waitcnt vmcnt(62)
	v_pk_fma_f32 v[142:143], v[62:63], v[136:137], v[142:143] op_sel_hi:[1,0,1]
	v_pk_fma_f32 v[144:145], v[64:65], v[136:137], v[144:145] op_sel_hi:[1,0,1]
	v_pk_mul_f32 v[210:211], v[200:201], v[140:141] op_sel_hi:[1,0]
	v_pk_fma_f32 v[62:63], v[184:185], v[62:63], v[210:211]
	v_pk_mul_f32 v[210:211], v[198:199], v[140:141] op_sel_hi:[1,0]
	v_pk_fma_f32 v[64:65], v[190:191], v[64:65], v[210:211]
	global_store_dwordx4 v158, v[62:65], s[30:31] offset:2048 nt
	s_nop 0
	global_load_dwordx4 v[62:65], v158, s[28:29] offset:2048 nt
	s_waitcnt vmcnt(62)
	v_pk_fma_f32 v[142:143], v[58:59], v[136:137], v[142:143] op_sel:[0,1,0]
	v_pk_fma_f32 v[144:145], v[60:61], v[136:137], v[144:145] op_sel:[0,1,0]
	v_pk_mul_f32 v[210:211], v[200:201], v[140:141] op_sel:[0,1]
	v_pk_fma_f32 v[58:59], v[184:185], v[58:59], v[210:211]
	v_pk_mul_f32 v[210:211], v[198:199], v[140:141] op_sel:[0,1]
	v_pk_fma_f32 v[60:61], v[190:191], v[60:61], v[210:211]
	global_store_dwordx4 v158, v[58:61], s[30:31] offset:3072 nt
	s_add_u32 s30, s30, 0x1000
	s_addc_u32 s31, s31, 0
	global_load_dwordx4 v[58:61], v158, s[28:29] offset:3072 nt
	s_add_u32 s28, s28, 0x1000
	s_addc_u32 s29, s29, 0
	ds_read_b128 v[134:137], v179 offset:224
	ds_read_b128 v[138:141], v179 offset:1248
	s_waitcnt lgkmcnt(2)
	s_waitcnt vmcnt(62)
; __device__ __forceinline__ void mlstm_decode_wave(const Params& P, unsigned char* wl, int sh) {
;     ...
;     const float* C0 = P.in[4] + (size_t)sh * 65536 + 4 * lane; float* C1 = P.out + OUT_SC + (size_t)sh * 65536 + 4 * lane;
;     f32x4 part = (f32x4){0.f, 0.f, 0.f, 0.f}; const f32x4 wv = wi * v4;
; #pragma unroll 1
;     for (int dk0 = 0; dk0 < 256; dk0 += 32) { f32x4 c[32];
; #pragma unroll
;         for (int i = 0; i < 32; ++i) c[i] = __builtin_nontemporal_load((const f32x4*)(C0 + (dk0 + i) * 256));
; #pragma unroll
;         for (int i = 0; i < 32; ++i) { const float qd = sq[dk0 + i], kd = sk[dk0 + i]; part += qd * c[i]; __builtin_nontemporal_store(wc * c[i] + kd * wv, (f32x4*)(C1 + (dk0 + i) * 256)); } }
	v_pk_fma_f32 v[142:143], v[54:55], v[202:203], v[142:143] op_sel_hi:[1,0,1]
	v_pk_fma_f32 v[144:145], v[56:57], v[202:203], v[144:145] op_sel_hi:[1,0,1]
	v_pk_mul_f32 v[210:211], v[200:201], v[206:207] op_sel_hi:[1,0]
	v_pk_fma_f32 v[54:55], v[184:185], v[54:55], v[210:211]
	v_pk_mul_f32 v[210:211], v[198:199], v[206:207] op_sel_hi:[1,0]
	v_pk_fma_f32 v[56:57], v[190:191], v[56:57], v[210:211]
	global_store_dwordx4 v158, v[54:57], s[30:31] nt
	s_nop 0
	global_load_dwordx4 v[54:57], v158, s[28:29] nt
	s_waitcnt vmcnt(62)
	v_pk_fma_f32 v[142:143], v[50:51], v[202:203], v[142:143] op_sel:[0,1,0]
	v_pk_fma_f32 v[144:145], v[52:53], v[202:203], v[144:145] op_sel:[0,1,0]
	v_pk_mul_f32 v[210:211], v[200:201], v[206:207] op_sel:[0,1]
	v_pk_fma_f32 v[50:51], v[184:185], v[50:51], v[210:211]
	v_pk_mul_f32 v[210:211], v[198:199], v[206:207] op_sel:[0,1]
	v_pk_fma_f32 v[52:53], v[190:191], v[52:53], v[210:211]
	global_store_dwordx4 v158, v[50:53], s[30:31] offset:1024 nt
	s_nop 0
	global_load_dwordx4 v[50:53], v158, s[28:29] offset:1024 nt
	s_waitcnt vmcnt(62)
	v_pk_fma_f32 v[142:143], v[46:47], v[204:205], v[142:143] op_sel_hi:[1,0,1]
	v_pk_fma_f32 v[144:145], v[48:49], v[204:205], v[144:145] op_sel_hi:[1,0,1]
	v_pk_mul_f32 v[210:211], v[200:201], v[208:209] op_sel_hi:[1,0]
	v_pk_fma_f32 v[46:47], v[184:185], v[46:47], v[210:211]
	v_pk_mul_f32 v[210:211], v[198:199], v[208:209] op_sel_hi:[1,0]
	v_pk_fma_f32 v[48:49], v[190:191], v[48:49], v[210:211]
	global_store_dwordx4 v158, v[46:49], s[30:31] offset:2048 nt
	s_nop 0
	global_load_dwordx4 v[46:49], v158, s[28:29] offset:2048 nt
	s_waitcnt vmcnt(62)
	v_pk_fma_f32 v[142:143], v[42:43], v[204:205], v[142:143] op_sel:[0,1,0]
	v_pk_fma_f32 v[144:145], v[44:45], v[204:205], v[144:145] op_sel:[0,1,0]
	v_pk_mul_f32 v[210:211], v[200:201], v[208:209] op_sel:[0,1]
	v_pk_fma_f32 v[42:43], v[184:185], v[42:43], v[210:211]
	v_pk_mul_f32 v[210:211], v[198:199], v[208:209] op_sel:[0,1]
	v_pk_fma_f32 v[44:45], v[190:191], v[44:45], v[210:211]
	global_store_dwordx4 v158, v[42:45], s[30:31] offset:3072 nt
	s_add_u32 s30, s30, 0x1000
	s_addc_u32 s31, s31, 0
	global_load_dwordx4 v[42:45], v158, s[28:29] offset:3072 nt
	s_add_u32 s28, s28, 0x1000
	s_addc_u32 s29, s29, 0
	ds_read_b128 v[202:205], v179 offset:240
	ds_read_b128 v[206:209], v179 offset:1264
	s_waitcnt lgkmcnt(2)
	s_waitcnt vmcnt(62)
	v_pk_fma_f32 v[142:143], v[38:39], v[134:135], v[142:143] op_sel_hi:[1,0,1]
	v_pk_fma_f32 v[144:145], v[40:41], v[134:135], v[144:145] op_sel_hi:[1,0,1]
	v_pk_mul_f32 v[210:211], v[200:201], v[138:139] op_sel_hi:[1,0]
	v_pk_fma_f32 v[38:39], v[184:185], v[38:39], v[210:211]
	v_pk_mul_f32 v[210:211], v[198:199], v[138:139] op_sel_hi:[1,0]
	v_pk_fma_f32 v[40:41], v[190:191], v[40:41], v[210:211]
	global_store_dwordx4 v158, v[38:41], s[30:31] nt
	s_nop 0
	global_load_dwordx4 v[38:41], v158, s[28:29] nt
	s_waitcnt vmcnt(62)
	v_pk_fma_f32 v[142:143], v[34:35], v[134:135], v[142:143] op_sel:[0,1,0]
	v_pk_fma_f32 v[144:145], v[36:37], v[134:135], v[144:145] op_sel:[0,1,0]
	v_pk_mul_f32 v[210:211], v[200:201], v[138:139] op_sel:[0,1]
	v_pk_fma_f32 v[34:35], v[184:185], v[34:35], v[210:211]
	v_pk_mul_f32 v[210:211], v[198:199], v[138:139] op_sel:[0,1]
	v_pk_fma_f32 v[36:37], v[190:191], v[36:37], v[210:211]
	global_store_dwordx4 v158, v[34:37], s[30:31] offset:1024 nt
	s_nop 0
	global_load_dwordx4 v[34:37], v158, s[28:29] offset:1024 nt
	s_waitcnt vmcnt(62)
	v_pk_fma_f32 v[142:143], v[30:31], v[136:137], v[142:143] op_sel_hi:[1,0,1]
	v_pk_fma_f32 v[144:145], v[32:33], v[136:137], v[144:145] op_sel_hi:[1,0,1]
	v_pk_mul_f32 v[210:211], v[200:201], v[140:141] op_sel_hi:[1,0]
	v_pk_fma_f32 v[30:31], v[184:185], v[30:31], v[210:211]
	v_pk_mul_f32 v[210:211], v[198:199], v[140:141] op_sel_hi:[1,0]
	v_pk_fma_f32 v[32:33], v[190:191], v[32:33], v[210:211]
	global_store_dwordx4 v158, v[30:33], s[30:31] offset:2048 nt
	s_nop 0
	global_load_dwordx4 v[30:33], v158, s[28:29] offset:2048 nt
	s_waitcnt vmcnt(62)
	v_pk_fma_f32 v[142:143], v[26:27], v[136:137], v[142:143] op_sel:[0,1,0]
	v_pk_fma_f32 v[144:145], v[28:29], v[136:137], v[144:145] op_sel:[0,1,0]
	v_pk_mul_f32 v[210:211], v[200:201], v[140:141] op_sel:[0,1]
	v_pk_fma_f32 v[26:27], v[184:185], v[26:27], v[210:211]
	v_pk_mul_f32 v[210:211], v[198:199], v[140:141] op_sel:[0,1]
	v_pk_fma_f32 v[28:29], v[190:191], v[28:29], v[210:211]
	global_store_dwordx4 v158, v[26:29], s[30:31] offset:3072 nt
	s_add_u32 s30, s30, 0x1000
	s_addc_u32 s31, s31, 0
	global_load_dwordx4 v[26:29], v158, s[28:29] offset:3072 nt
	s_add_u32 s28, s28, 0x1000
	s_addc_u32 s29, s29, 0
	ds_read_b128 v[134:137], v179 offset:256
	ds_read_b128 v[138:141], v179 offset:1280
	s_waitcnt lgkmcnt(2)
	s_waitcnt vmcnt(62)
	v_pk_fma_f32 v[142:143], v[22:23], v[202:203], v[142:143] op_sel_hi:[1,0,1]
	v_pk_fma_f32 v[144:145], v[24:25], v[202:203], v[144:145] op_sel_hi:[1,0,1]
	v_pk_mul_f32 v[210:211], v[200:201], v[206:207] op_sel_hi:[1,0]
	v_pk_fma_f32 v[22:23], v[184:185], v[22:23], v[210:211]
	v_pk_mul_f32 v[210:211], v[198:199], v[206:207] op_sel_hi:[1,0]
	v_pk_fma_f32 v[24:25], v[190:191], v[24:25], v[210:211]
	global_store_dwordx4 v158, v[22:25], s[30:31] nt
	s_nop 0
	global_load_dwordx4 v[22:25], v158, s[28:29] nt
	s_waitcnt vmcnt(62)
	v_pk_fma_f32 v[142:143], v[18:19], v[202:203], v[142:143] op_sel:[0,1,0]
	v_pk_fma_f32 v[144:145], v[20:21], v[202:203], v[144:145] op_sel:[0,1,0]
	v_pk_mul_f32 v[210:211], v[200:201], v[206:207] op_sel:[0,1]
	v_pk_fma_f32 v[18:19], v[184:185], v[18:19], v[210:211]
	v_pk_mul_f32 v[210:211], v[198:199], v[206:207] op_sel:[0,1]
	v_pk_fma_f32 v[20:21], v[190:191], v[20:21], v[210:211]
	global_store_dwordx4 v158, v[18:21], s[30:31] offset:1024 nt
	s_nop 0
	global_load_dwordx4 v[18:21], v158, s[28:29] offset:1024 nt
	s_waitcnt vmcnt(62)
; __device__ __forceinline__ void mlstm_decode_wave(const Params& P, unsigned char* wl, int sh) {
;     ...
;     const float* C0 = P.in[4] + (size_t)sh * 65536 + 4 * lane; float* C1 = P.out + OUT_SC + (size_t)sh * 65536 + 4 * lane;
;     f32x4 part = (f32x4){0.f, 0.f, 0.f, 0.f}; const f32x4 wv = wi * v4;
; #pragma unroll 1
;     for (int dk0 = 0; dk0 < 256; dk0 += 32) { f32x4 c[32];
; #pragma unroll
;         for (int i = 0; i < 32; ++i) c[i] = __builtin_nontemporal_load((const f32x4*)(C0 + (dk0 + i) * 256));
; #pragma unroll
;         for (int i = 0; i < 32; ++i) { const float qd = sq[dk0 + i], kd = sk[dk0 + i]; part += qd * c[i]; __builtin_nontemporal_store(wc * c[i] + kd * wv, (f32x4*)(C1 + (dk0 + i) * 256)); } }
	v_pk_fma_f32 v[142:143], v[14:15], v[204:205], v[142:143] op_sel_hi:[1,0,1]
	v_pk_fma_f32 v[144:145], v[16:17], v[204:205], v[144:145] op_sel_hi:[1,0,1]
	v_pk_mul_f32 v[210:211], v[200:201], v[208:209] op_sel_hi:[1,0]
	v_pk_fma_f32 v[14:15], v[184:185], v[14:15], v[210:211]
	v_pk_mul_f32 v[210:211], v[198:199], v[208:209] op_sel_hi:[1,0]
	v_pk_fma_f32 v[16:17], v[190:191], v[16:17], v[210:211]
	global_store_dwordx4 v158, v[14:17], s[30:31] offset:2048 nt
	s_nop 0
	global_load_dwordx4 v[14:17], v158, s[28:29] offset:2048 nt
	s_waitcnt vmcnt(62)
	v_pk_fma_f32 v[142:143], v[10:11], v[204:205], v[142:143] op_sel:[0,1,0]
	v_pk_fma_f32 v[144:145], v[12:13], v[204:205], v[144:145] op_sel:[0,1,0]
	v_pk_mul_f32 v[210:211], v[200:201], v[208:209] op_sel:[0,1]
	v_pk_fma_f32 v[10:11], v[184:185], v[10:11], v[210:211]
	v_pk_mul_f32 v[210:211], v[198:199], v[208:209] op_sel:[0,1]
	v_pk_fma_f32 v[12:13], v[190:191], v[12:13], v[210:211]
	global_store_dwordx4 v158, v[10:13], s[30:31] offset:3072 nt
	s_add_u32 s30, s30, 0x1000
	s_addc_u32 s31, s31, 0
	global_load_dwordx4 v[10:13], v158, s[28:29] offset:3072 nt
	s_add_u32 s28, s28, 0x1000
	s_addc_u32 s29, s29, 0
	ds_read_b128 v[202:205], v179 offset:272
	ds_read_b128 v[206:209], v179 offset:1296
	s_waitcnt lgkmcnt(2)
	s_waitcnt vmcnt(62)
	v_pk_fma_f32 v[142:143], v[232:233], v[134:135], v[142:143] op_sel_hi:[1,0,1]
	v_pk_fma_f32 v[144:145], v[234:235], v[134:135], v[144:145] op_sel_hi:[1,0,1]
	v_pk_mul_f32 v[210:211], v[200:201], v[138:139] op_sel_hi:[1,0]
	v_pk_fma_f32 v[232:233], v[184:185], v[232:233], v[210:211]
	v_pk_mul_f32 v[210:211], v[198:199], v[138:139] op_sel_hi:[1,0]
	v_pk_fma_f32 v[234:235], v[190:191], v[234:235], v[210:211]
	global_store_dwordx4 v158, v[232:235], s[30:31] nt
	s_nop 0
	global_load_dwordx4 v[232:235], v158, s[28:29] nt
	s_waitcnt vmcnt(62)
	v_pk_fma_f32 v[142:143], v[130:131], v[134:135], v[142:143] op_sel:[0,1,0]
	v_pk_fma_f32 v[144:145], v[132:133], v[134:135], v[144:145] op_sel:[0,1,0]
	v_pk_mul_f32 v[210:211], v[200:201], v[138:139] op_sel:[0,1]
	v_pk_fma_f32 v[130:131], v[184:185], v[130:131], v[210:211]
	v_pk_mul_f32 v[210:211], v[198:199], v[138:139] op_sel:[0,1]
	v_pk_fma_f32 v[132:133], v[190:191], v[132:133], v[210:211]
	global_store_dwordx4 v158, v[130:133], s[30:31] offset:1024 nt
	s_nop 0
	global_load_dwordx4 v[130:133], v158, s[28:29] offset:1024 nt
	s_waitcnt vmcnt(62)
	v_pk_fma_f32 v[142:143], v[126:127], v[136:137], v[142:143] op_sel_hi:[1,0,1]
	v_pk_fma_f32 v[144:145], v[128:129], v[136:137], v[144:145] op_sel_hi:[1,0,1]
	v_pk_mul_f32 v[210:211], v[200:201], v[140:141] op_sel_hi:[1,0]
	v_pk_fma_f32 v[126:127], v[184:185], v[126:127], v[210:211]
	v_pk_mul_f32 v[210:211], v[198:199], v[140:141] op_sel_hi:[1,0]
	v_pk_fma_f32 v[128:129], v[190:191], v[128:129], v[210:211]
	global_store_dwordx4 v158, v[126:129], s[30:31] offset:2048 nt
	s_nop 0
	global_load_dwordx4 v[126:129], v158, s[28:29] offset:2048 nt
	s_waitcnt vmcnt(62)
	v_pk_fma_f32 v[142:143], v[122:123], v[136:137], v[142:143] op_sel:[0,1,0]
	v_pk_fma_f32 v[144:145], v[124:125], v[136:137], v[144:145] op_sel:[0,1,0]
	v_pk_mul_f32 v[210:211], v[200:201], v[140:141] op_sel:[0,1]
	v_pk_fma_f32 v[122:123], v[184:185], v[122:123], v[210:211]
	v_pk_mul_f32 v[210:211], v[198:199], v[140:141] op_sel:[0,1]
	v_pk_fma_f32 v[124:125], v[190:191], v[124:125], v[210:211]
	global_store_dwordx4 v158, v[122:125], s[30:31] offset:3072 nt
	s_add_u32 s30, s30, 0x1000
	s_addc_u32 s31, s31, 0
	global_load_dwordx4 v[122:125], v158, s[28:29] offset:3072 nt
	s_add_u32 s28, s28, 0x1000
	s_addc_u32 s29, s29, 0
	ds_read_b128 v[134:137], v179 offset:288
	ds_read_b128 v[138:141], v179 offset:1312
	s_waitcnt lgkmcnt(2)
	s_waitcnt vmcnt(62)
	v_pk_fma_f32 v[142:143], v[118:119], v[202:203], v[142:143] op_sel_hi:[1,0,1]
	v_pk_fma_f32 v[144:145], v[120:121], v[202:203], v[144:145] op_sel_hi:[1,0,1]
	v_pk_mul_f32 v[210:211], v[200:201], v[206:207] op_sel_hi:[1,0]
	v_pk_fma_f32 v[118:119], v[184:185], v[118:119], v[210:211]
	v_pk_mul_f32 v[210:211], v[198:199], v[206:207] op_sel_hi:[1,0]
	v_pk_fma_f32 v[120:121], v[190:191], v[120:121], v[210:211]
	global_store_dwordx4 v158, v[118:121], s[30:31] nt
	s_nop 0
	global_load_dwordx4 v[118:121], v158, s[28:29] nt
	s_waitcnt vmcnt(62)
	v_pk_fma_f32 v[142:143], v[114:115], v[202:203], v[142:143] op_sel:[0,1,0]
	v_pk_fma_f32 v[144:145], v[116:117], v[202:203], v[144:145] op_sel:[0,1,0]
	v_pk_mul_f32 v[210:211], v[200:201], v[206:207] op_sel:[0,1]
	v_pk_fma_f32 v[114:115], v[184:185], v[114:115], v[210:211]
	v_pk_mul_f32 v[210:211], v[198:199], v[206:207] op_sel:[0,1]
	v_pk_fma_f32 v[116:117], v[190:191], v[116:117], v[210:211]
	global_store_dwordx4 v158, v[114:117], s[30:31] offset:1024 nt
	s_nop 0
	global_load_dwordx4 v[114:117], v158, s[28:29] offset:1024 nt
	s_waitcnt vmcnt(62)
	v_pk_fma_f32 v[142:143], v[110:111], v[204:205], v[142:143] op_sel_hi:[1,0,1]
	v_pk_fma_f32 v[144:145], v[112:113], v[204:205], v[144:145] op_sel_hi:[1,0,1]
	v_pk_mul_f32 v[210:211], v[200:201], v[208:209] op_sel_hi:[1,0]
	v_pk_fma_f32 v[110:111], v[184:185], v[110:111], v[210:211]
	v_pk_mul_f32 v[210:211], v[198:199], v[208:209] op_sel_hi:[1,0]
	v_pk_fma_f32 v[112:113], v[190:191], v[112:113], v[210:211]
	global_store_dwordx4 v158, v[110:113], s[30:31] offset:2048 nt
	s_nop 0
	global_load_dwordx4 v[110:113], v158, s[28:29] offset:2048 nt
	s_waitcnt vmcnt(62)
; __device__ __forceinline__ void mlstm_decode_wave(const Params& P, unsigned char* wl, int sh) {
;     ...
;     const float* C0 = P.in[4] + (size_t)sh * 65536 + 4 * lane; float* C1 = P.out + OUT_SC + (size_t)sh * 65536 + 4 * lane;
;     f32x4 part = (f32x4){0.f, 0.f, 0.f, 0.f}; const f32x4 wv = wi * v4;
; #pragma unroll 1
;     for (int dk0 = 0; dk0 < 256; dk0 += 32) { f32x4 c[32];
; #pragma unroll
;         for (int i = 0; i < 32; ++i) c[i] = __builtin_nontemporal_load((const f32x4*)(C0 + (dk0 + i) * 256));
; #pragma unroll
;         for (int i = 0; i < 32; ++i) { const float qd = sq[dk0 + i], kd = sk[dk0 + i]; part += qd * c[i]; __builtin_nontemporal_store(wc * c[i] + kd * wv, (f32x4*)(C1 + (dk0 + i) * 256)); } }
	v_pk_fma_f32 v[142:143], v[106:107], v[204:205], v[142:143] op_sel:[0,1,0]
	v_pk_fma_f32 v[144:145], v[108:109], v[204:205], v[144:145] op_sel:[0,1,0]
	v_pk_mul_f32 v[210:211], v[200:201], v[208:209] op_sel:[0,1]
	v_pk_fma_f32 v[106:107], v[184:185], v[106:107], v[210:211]
	v_pk_mul_f32 v[210:211], v[198:199], v[208:209] op_sel:[0,1]
	v_pk_fma_f32 v[108:109], v[190:191], v[108:109], v[210:211]
	global_store_dwordx4 v158, v[106:109], s[30:31] offset:3072 nt
	s_add_u32 s30, s30, 0x1000
	s_addc_u32 s31, s31, 0
	global_load_dwordx4 v[106:109], v158, s[28:29] offset:3072 nt
	s_add_u32 s28, s28, 0x1000
	s_addc_u32 s29, s29, 0
	ds_read_b128 v[202:205], v179 offset:304
	ds_read_b128 v[206:209], v179 offset:1328
	s_waitcnt lgkmcnt(2)
	s_waitcnt vmcnt(62)
	v_pk_fma_f32 v[142:143], v[102:103], v[134:135], v[142:143] op_sel_hi:[1,0,1]
	v_pk_fma_f32 v[144:145], v[104:105], v[134:135], v[144:145] op_sel_hi:[1,0,1]
	v_pk_mul_f32 v[210:211], v[200:201], v[138:139] op_sel_hi:[1,0]
	v_pk_fma_f32 v[102:103], v[184:185], v[102:103], v[210:211]
	v_pk_mul_f32 v[210:211], v[198:199], v[138:139] op_sel_hi:[1,0]
	v_pk_fma_f32 v[104:105], v[190:191], v[104:105], v[210:211]
	global_store_dwordx4 v158, v[102:105], s[30:31] nt
	s_nop 0
	global_load_dwordx4 v[102:105], v158, s[28:29] nt
	s_waitcnt vmcnt(62)
	v_pk_fma_f32 v[142:143], v[98:99], v[134:135], v[142:143] op_sel:[0,1,0]
	v_pk_fma_f32 v[144:145], v[100:101], v[134:135], v[144:145] op_sel:[0,1,0]
	v_pk_mul_f32 v[210:211], v[200:201], v[138:139] op_sel:[0,1]
	v_pk_fma_f32 v[98:99], v[184:185], v[98:99], v[210:211]
	v_pk_mul_f32 v[210:211], v[198:199], v[138:139] op_sel:[0,1]
	v_pk_fma_f32 v[100:101], v[190:191], v[100:101], v[210:211]
	global_store_dwordx4 v158, v[98:101], s[30:31] offset:1024 nt
	s_nop 0
	global_load_dwordx4 v[98:101], v158, s[28:29] offset:1024 nt
	s_waitcnt vmcnt(62)
	v_pk_fma_f32 v[142:143], v[94:95], v[136:137], v[142:143] op_sel_hi:[1,0,1]
	v_pk_fma_f32 v[144:145], v[96:97], v[136:137], v[144:145] op_sel_hi:[1,0,1]
	v_pk_mul_f32 v[210:211], v[200:201], v[140:141] op_sel_hi:[1,0]
	v_pk_fma_f32 v[94:95], v[184:185], v[94:95], v[210:211]
	v_pk_mul_f32 v[210:211], v[198:199], v[140:141] op_sel_hi:[1,0]
	v_pk_fma_f32 v[96:97], v[190:191], v[96:97], v[210:211]
	global_store_dwordx4 v158, v[94:97], s[30:31] offset:2048 nt
	s_nop 0
	global_load_dwordx4 v[94:97], v158, s[28:29] offset:2048 nt
	s_waitcnt vmcnt(62)
	v_pk_fma_f32 v[142:143], v[90:91], v[136:137], v[142:143] op_sel:[0,1,0]
	v_pk_fma_f32 v[144:145], v[92:93], v[136:137], v[144:145] op_sel:[0,1,0]
	v_pk_mul_f32 v[210:211], v[200:201], v[140:141] op_sel:[0,1]
	v_pk_fma_f32 v[90:91], v[184:185], v[90:91], v[210:211]
	v_pk_mul_f32 v[210:211], v[198:199], v[140:141] op_sel:[0,1]
	v_pk_fma_f32 v[92:93], v[190:191], v[92:93], v[210:211]
	global_store_dwordx4 v158, v[90:93], s[30:31] offset:3072 nt
	s_add_u32 s30, s30, 0x1000
	s_addc_u32 s31, s31, 0
	global_load_dwordx4 v[90:93], v158, s[28:29] offset:3072 nt
	s_add_u32 s28, s28, 0x1000
	s_addc_u32 s29, s29, 0
	ds_read_b128 v[134:137], v179 offset:320
	ds_read_b128 v[138:141], v179 offset:1344
	s_waitcnt lgkmcnt(2)
	s_waitcnt vmcnt(62)
	v_pk_fma_f32 v[142:143], v[86:87], v[202:203], v[142:143] op_sel_hi:[1,0,1]
	v_pk_fma_f32 v[144:145], v[88:89], v[202:203], v[144:145] op_sel_hi:[1,0,1]
	v_pk_mul_f32 v[210:211], v[200:201], v[206:207] op_sel_hi:[1,0]
	v_pk_fma_f32 v[86:87], v[184:185], v[86:87], v[210:211]
	v_pk_mul_f32 v[210:211], v[198:199], v[206:207] op_sel_hi:[1,0]
	v_pk_fma_f32 v[88:89], v[190:191], v[88:89], v[210:211]
	global_store_dwordx4 v158, v[86:89], s[30:31] nt
	s_nop 0
	global_load_dwordx4 v[86:89], v158, s[28:29] nt
	s_waitcnt vmcnt(62)
	v_pk_fma_f32 v[142:143], v[82:83], v[202:203], v[142:143] op_sel:[0,1,0]
	v_pk_fma_f32 v[144:145], v[84:85], v[202:203], v[144:145] op_sel:[0,1,0]
	v_pk_mul_f32 v[210:211], v[200:201], v[206:207] op_sel:[0,1]
	v_pk_fma_f32 v[82:83], v[184:185], v[82:83], v[210:211]
	v_pk_mul_f32 v[210:211], v[198:199], v[206:207] op_sel:[0,1]
	v_pk_fma_f32 v[84:85], v[190:191], v[84:85], v[210:211]
	global_store_dwordx4 v158, v[82:85], s[30:31] offset:1024 nt
	s_nop 0
	global_load_dwordx4 v[82:85], v158, s[28:29] offset:1024 nt
	s_waitcnt vmcnt(62)
	v_pk_fma_f32 v[142:143], v[78:79], v[204:205], v[142:143] op_sel_hi:[1,0,1]
	v_pk_fma_f32 v[144:145], v[80:81], v[204:205], v[144:145] op_sel_hi:[1,0,1]
	v_pk_mul_f32 v[210:211], v[200:201], v[208:209] op_sel_hi:[1,0]
	v_pk_fma_f32 v[78:79], v[184:185], v[78:79], v[210:211]
	v_pk_mul_f32 v[210:211], v[198:199], v[208:209] op_sel_hi:[1,0]
	v_pk_fma_f32 v[80:81], v[190:191], v[80:81], v[210:211]
	global_store_dwordx4 v158, v[78:81], s[30:31] offset:2048 nt
	s_nop 0
	global_load_dwordx4 v[78:81], v158, s[28:29] offset:2048 nt
	s_waitcnt vmcnt(62)
	v_pk_fma_f32 v[142:143], v[74:75], v[204:205], v[142:143] op_sel:[0,1,0]
	v_pk_fma_f32 v[144:145], v[76:77], v[204:205], v[144:145] op_sel:[0,1,0]
	v_pk_mul_f32 v[210:211], v[200:201], v[208:209] op_sel:[0,1]
	v_pk_fma_f32 v[74:75], v[184:185], v[74:75], v[210:211]
	v_pk_mul_f32 v[210:211], v[198:199], v[208:209] op_sel:[0,1]
	v_pk_fma_f32 v[76:77], v[190:191], v[76:77], v[210:211]
	global_store_dwordx4 v158, v[74:77], s[30:31] offset:3072 nt
	s_add_u32 s30, s30, 0x1000
	s_addc_u32 s31, s31, 0
	global_load_dwordx4 v[74:77], v158, s[28:29] offset:3072 nt
	s_add_u32 s28, s28, 0x1000
	s_addc_u32 s29, s29, 0
	ds_read_b128 v[202:205], v179 offset:336
	ds_read_b128 v[206:209], v179 offset:1360
	s_waitcnt lgkmcnt(2)
	s_waitcnt vmcnt(62)
; __device__ __forceinline__ void mlstm_decode_wave(const Params& P, unsigned char* wl, int sh) {
;     ...
;     const float* C0 = P.in[4] + (size_t)sh * 65536 + 4 * lane; float* C1 = P.out + OUT_SC + (size_t)sh * 65536 + 4 * lane;
;     f32x4 part = (f32x4){0.f, 0.f, 0.f, 0.f}; const f32x4 wv = wi * v4;
; #pragma unroll 1
;     for (int dk0 = 0; dk0 < 256; dk0 += 32) { f32x4 c[32];
; #pragma unroll
;         for (int i = 0; i < 32; ++i) c[i] = __builtin_nontemporal_load((const f32x4*)(C0 + (dk0 + i) * 256));
; #pragma unroll
;         for (int i = 0; i < 32; ++i) { const float qd = sq[dk0 + i], kd = sk[dk0 + i]; part += qd * c[i]; __builtin_nontemporal_store(wc * c[i] + kd * wv, (f32x4*)(C1 + (dk0 + i) * 256)); } }
	v_pk_fma_f32 v[142:143], v[70:71], v[134:135], v[142:143] op_sel_hi:[1,0,1]
	v_pk_fma_f32 v[144:145], v[72:73], v[134:135], v[144:145] op_sel_hi:[1,0,1]
	v_pk_mul_f32 v[210:211], v[200:201], v[138:139] op_sel_hi:[1,0]
	v_pk_fma_f32 v[70:71], v[184:185], v[70:71], v[210:211]
	v_pk_mul_f32 v[210:211], v[198:199], v[138:139] op_sel_hi:[1,0]
	v_pk_fma_f32 v[72:73], v[190:191], v[72:73], v[210:211]
	global_store_dwordx4 v158, v[70:73], s[30:31] nt
	s_nop 0
	global_load_dwordx4 v[70:73], v158, s[28:29] nt
	s_waitcnt vmcnt(62)
	v_pk_fma_f32 v[142:143], v[66:67], v[134:135], v[142:143] op_sel:[0,1,0]
	v_pk_fma_f32 v[144:145], v[68:69], v[134:135], v[144:145] op_sel:[0,1,0]
	v_pk_mul_f32 v[210:211], v[200:201], v[138:139] op_sel:[0,1]
	v_pk_fma_f32 v[66:67], v[184:185], v[66:67], v[210:211]
	v_pk_mul_f32 v[210:211], v[198:199], v[138:139] op_sel:[0,1]
	v_pk_fma_f32 v[68:69], v[190:191], v[68:69], v[210:211]
	global_store_dwordx4 v158, v[66:69], s[30:31] offset:1024 nt
	s_nop 0
	global_load_dwordx4 v[66:69], v158, s[28:29] offset:1024 nt
	s_waitcnt vmcnt(62)
	v_pk_fma_f32 v[142:143], v[62:63], v[136:137], v[142:143] op_sel_hi:[1,0,1]
	v_pk_fma_f32 v[144:145], v[64:65], v[136:137], v[144:145] op_sel_hi:[1,0,1]
	v_pk_mul_f32 v[210:211], v[200:201], v[140:141] op_sel_hi:[1,0]
	v_pk_fma_f32 v[62:63], v[184:185], v[62:63], v[210:211]
	v_pk_mul_f32 v[210:211], v[198:199], v[140:141] op_sel_hi:[1,0]
	v_pk_fma_f32 v[64:65], v[190:191], v[64:65], v[210:211]
	global_store_dwordx4 v158, v[62:65], s[30:31] offset:2048 nt
	s_nop 0
	global_load_dwordx4 v[62:65], v158, s[28:29] offset:2048 nt
	s_waitcnt vmcnt(62)
	v_pk_fma_f32 v[142:143], v[58:59], v[136:137], v[142:143] op_sel:[0,1,0]
	v_pk_fma_f32 v[144:145], v[60:61], v[136:137], v[144:145] op_sel:[0,1,0]
	v_pk_mul_f32 v[210:211], v[200:201], v[140:141] op_sel:[0,1]
	v_pk_fma_f32 v[58:59], v[184:185], v[58:59], v[210:211]
	v_pk_mul_f32 v[210:211], v[198:199], v[140:141] op_sel:[0,1]
	v_pk_fma_f32 v[60:61], v[190:191], v[60:61], v[210:211]
	global_store_dwordx4 v158, v[58:61], s[30:31] offset:3072 nt
	s_add_u32 s30, s30, 0x1000
	s_addc_u32 s31, s31, 0
	global_load_dwordx4 v[58:61], v158, s[28:29] offset:3072 nt
	s_add_u32 s28, s28, 0x1000
	s_addc_u32 s29, s29, 0
	ds_read_b128 v[134:137], v179 offset:352
	ds_read_b128 v[138:141], v179 offset:1376
	s_waitcnt lgkmcnt(2)
	s_waitcnt vmcnt(62)
	v_pk_fma_f32 v[142:143], v[54:55], v[202:203], v[142:143] op_sel_hi:[1,0,1]
	v_pk_fma_f32 v[144:145], v[56:57], v[202:203], v[144:145] op_sel_hi:[1,0,1]
	v_pk_mul_f32 v[210:211], v[200:201], v[206:207] op_sel_hi:[1,0]
	v_pk_fma_f32 v[54:55], v[184:185], v[54:55], v[210:211]
	v_pk_mul_f32 v[210:211], v[198:199], v[206:207] op_sel_hi:[1,0]
	v_pk_fma_f32 v[56:57], v[190:191], v[56:57], v[210:211]
	global_store_dwordx4 v158, v[54:57], s[30:31] nt
	s_nop 0
	global_load_dwordx4 v[54:57], v158, s[28:29] nt
	s_waitcnt vmcnt(62)
	v_pk_fma_f32 v[142:143], v[50:51], v[202:203], v[142:143] op_sel:[0,1,0]
	v_pk_fma_f32 v[144:145], v[52:53], v[202:203], v[144:145] op_sel:[0,1,0]
	v_pk_mul_f32 v[210:211], v[200:201], v[206:207] op_sel:[0,1]
	v_pk_fma_f32 v[50:51], v[184:185], v[50:51], v[210:211]
	v_pk_mul_f32 v[210:211], v[198:199], v[206:207] op_sel:[0,1]
	v_pk_fma_f32 v[52:53], v[190:191], v[52:53], v[210:211]
	global_store_dwordx4 v158, v[50:53], s[30:31] offset:1024 nt
	s_nop 0
	global_load_dwordx4 v[50:53], v158, s[28:29] offset:1024 nt
	s_waitcnt vmcnt(62)
	v_pk_fma_f32 v[142:143], v[46:47], v[204:205], v[142:143] op_sel_hi:[1,0,1]
	v_pk_fma_f32 v[144:145], v[48:49], v[204:205], v[144:145] op_sel_hi:[1,0,1]
	v_pk_mul_f32 v[210:211], v[200:201], v[208:209] op_sel_hi:[1,0]
	v_pk_fma_f32 v[46:47], v[184:185], v[46:47], v[210:211]
	v_pk_mul_f32 v[210:211], v[198:199], v[208:209] op_sel_hi:[1,0]
	v_pk_fma_f32 v[48:49], v[190:191], v[48:49], v[210:211]
	global_store_dwordx4 v158, v[46:49], s[30:31] offset:2048 nt
	s_nop 0
	global_load_dwordx4 v[46:49], v158, s[28:29] offset:2048 nt
	s_waitcnt vmcnt(62)
	v_pk_fma_f32 v[142:143], v[42:43], v[204:205], v[142:143] op_sel:[0,1,0]
	v_pk_fma_f32 v[144:145], v[44:45], v[204:205], v[144:145] op_sel:[0,1,0]
	v_pk_mul_f32 v[210:211], v[200:201], v[208:209] op_sel:[0,1]
	v_pk_fma_f32 v[42:43], v[184:185], v[42:43], v[210:211]
	v_pk_mul_f32 v[210:211], v[198:199], v[208:209] op_sel:[0,1]
	v_pk_fma_f32 v[44:45], v[190:191], v[44:45], v[210:211]
	global_store_dwordx4 v158, v[42:45], s[30:31] offset:3072 nt
	s_add_u32 s30, s30, 0x1000
	s_addc_u32 s31, s31, 0
	global_load_dwordx4 v[42:45], v158, s[28:29] offset:3072 nt
	s_add_u32 s28, s28, 0x1000
	s_addc_u32 s29, s29, 0
	ds_read_b128 v[202:205], v179 offset:368
	ds_read_b128 v[206:209], v179 offset:1392
	s_waitcnt lgkmcnt(2)
	s_waitcnt vmcnt(62)
	v_pk_fma_f32 v[142:143], v[38:39], v[134:135], v[142:143] op_sel_hi:[1,0,1]
	v_pk_fma_f32 v[144:145], v[40:41], v[134:135], v[144:145] op_sel_hi:[1,0,1]
	v_pk_mul_f32 v[210:211], v[200:201], v[138:139] op_sel_hi:[1,0]
	v_pk_fma_f32 v[38:39], v[184:185], v[38:39], v[210:211]
	v_pk_mul_f32 v[210:211], v[198:199], v[138:139] op_sel_hi:[1,0]
	v_pk_fma_f32 v[40:41], v[190:191], v[40:41], v[210:211]
	global_store_dwordx4 v158, v[38:41], s[30:31] nt
	s_nop 0
	global_load_dwordx4 v[38:41], v158, s[28:29] nt
	s_waitcnt vmcnt(62)
	v_pk_fma_f32 v[142:143], v[34:35], v[134:135], v[142:143] op_sel:[0,1,0]
	v_pk_fma_f32 v[144:145], v[36:37], v[134:135], v[144:145] op_sel:[0,1,0]
	v_pk_mul_f32 v[210:211], v[200:201], v[138:139] op_sel:[0,1]
	v_pk_fma_f32 v[34:35], v[184:185], v[34:35], v[210:211]
	v_pk_mul_f32 v[210:211], v[198:199], v[138:139] op_sel:[0,1]
	v_pk_fma_f32 v[36:37], v[190:191], v[36:37], v[210:211]
	global_store_dwordx4 v158, v[34:37], s[30:31] offset:1024 nt
	s_nop 0
	global_load_dwordx4 v[34:37], v158, s[28:29] offset:1024 nt
	s_waitcnt vmcnt(62)
; __device__ __forceinline__ void mlstm_decode_wave(const Params& P, unsigned char* wl, int sh) {
;     ...
;     const float* C0 = P.in[4] + (size_t)sh * 65536 + 4 * lane; float* C1 = P.out + OUT_SC + (size_t)sh * 65536 + 4 * lane;
;     f32x4 part = (f32x4){0.f, 0.f, 0.f, 0.f}; const f32x4 wv = wi * v4;
; #pragma unroll 1
;     for (int dk0 = 0; dk0 < 256; dk0 += 32) { f32x4 c[32];
; #pragma unroll
;         for (int i = 0; i < 32; ++i) c[i] = __builtin_nontemporal_load((const f32x4*)(C0 + (dk0 + i) * 256));
; #pragma unroll
;         for (int i = 0; i < 32; ++i) { const float qd = sq[dk0 + i], kd = sk[dk0 + i]; part += qd * c[i]; __builtin_nontemporal_store(wc * c[i] + kd * wv, (f32x4*)(C1 + (dk0 + i) * 256)); } }
	v_pk_fma_f32 v[142:143], v[30:31], v[136:137], v[142:143] op_sel_hi:[1,0,1]
	v_pk_fma_f32 v[144:145], v[32:33], v[136:137], v[144:145] op_sel_hi:[1,0,1]
	v_pk_mul_f32 v[210:211], v[200:201], v[140:141] op_sel_hi:[1,0]
	v_pk_fma_f32 v[30:31], v[184:185], v[30:31], v[210:211]
	v_pk_mul_f32 v[210:211], v[198:199], v[140:141] op_sel_hi:[1,0]
	v_pk_fma_f32 v[32:33], v[190:191], v[32:33], v[210:211]
	global_store_dwordx4 v158, v[30:33], s[30:31] offset:2048 nt
	s_nop 0
	global_load_dwordx4 v[30:33], v158, s[28:29] offset:2048 nt
	s_waitcnt vmcnt(62)
	v_pk_fma_f32 v[142:143], v[26:27], v[136:137], v[142:143] op_sel:[0,1,0]
	v_pk_fma_f32 v[144:145], v[28:29], v[136:137], v[144:145] op_sel:[0,1,0]
	v_pk_mul_f32 v[210:211], v[200:201], v[140:141] op_sel:[0,1]
	v_pk_fma_f32 v[26:27], v[184:185], v[26:27], v[210:211]
	v_pk_mul_f32 v[210:211], v[198:199], v[140:141] op_sel:[0,1]
	v_pk_fma_f32 v[28:29], v[190:191], v[28:29], v[210:211]
	global_store_dwordx4 v158, v[26:29], s[30:31] offset:3072 nt
	s_add_u32 s30, s30, 0x1000
	s_addc_u32 s31, s31, 0
	global_load_dwordx4 v[26:29], v158, s[28:29] offset:3072 nt
	s_add_u32 s28, s28, 0x1000
	s_addc_u32 s29, s29, 0
	ds_read_b128 v[134:137], v179 offset:384
	ds_read_b128 v[138:141], v179 offset:1408
	s_waitcnt lgkmcnt(2)
	s_waitcnt vmcnt(62)
	v_pk_fma_f32 v[142:143], v[22:23], v[202:203], v[142:143] op_sel_hi:[1,0,1]
	v_pk_fma_f32 v[144:145], v[24:25], v[202:203], v[144:145] op_sel_hi:[1,0,1]
	v_pk_mul_f32 v[210:211], v[200:201], v[206:207] op_sel_hi:[1,0]
	v_pk_fma_f32 v[22:23], v[184:185], v[22:23], v[210:211]
	v_pk_mul_f32 v[210:211], v[198:199], v[206:207] op_sel_hi:[1,0]
	v_pk_fma_f32 v[24:25], v[190:191], v[24:25], v[210:211]
	global_store_dwordx4 v158, v[22:25], s[30:31] nt
	s_nop 0
	global_load_dwordx4 v[22:25], v158, s[28:29] nt
	s_waitcnt vmcnt(62)
	v_pk_fma_f32 v[142:143], v[18:19], v[202:203], v[142:143] op_sel:[0,1,0]
	v_pk_fma_f32 v[144:145], v[20:21], v[202:203], v[144:145] op_sel:[0,1,0]
	v_pk_mul_f32 v[210:211], v[200:201], v[206:207] op_sel:[0,1]
	v_pk_fma_f32 v[18:19], v[184:185], v[18:19], v[210:211]
	v_pk_mul_f32 v[210:211], v[198:199], v[206:207] op_sel:[0,1]
	v_pk_fma_f32 v[20:21], v[190:191], v[20:21], v[210:211]
	global_store_dwordx4 v158, v[18:21], s[30:31] offset:1024 nt
	s_nop 0
	global_load_dwordx4 v[18:21], v158, s[28:29] offset:1024 nt
	s_waitcnt vmcnt(62)
	v_pk_fma_f32 v[142:143], v[14:15], v[204:205], v[142:143] op_sel_hi:[1,0,1]
	v_pk_fma_f32 v[144:145], v[16:17], v[204:205], v[144:145] op_sel_hi:[1,0,1]
	v_pk_mul_f32 v[210:211], v[200:201], v[208:209] op_sel_hi:[1,0]
	v_pk_fma_f32 v[14:15], v[184:185], v[14:15], v[210:211]
	v_pk_mul_f32 v[210:211], v[198:199], v[208:209] op_sel_hi:[1,0]
	v_pk_fma_f32 v[16:17], v[190:191], v[16:17], v[210:211]
	global_store_dwordx4 v158, v[14:17], s[30:31] offset:2048 nt
	s_nop 0
	global_load_dwordx4 v[14:17], v158, s[28:29] offset:2048 nt
	s_waitcnt vmcnt(62)
	v_pk_fma_f32 v[142:143], v[10:11], v[204:205], v[142:143] op_sel:[0,1,0]
	v_pk_fma_f32 v[144:145], v[12:13], v[204:205], v[144:145] op_sel:[0,1,0]
	v_pk_mul_f32 v[210:211], v[200:201], v[208:209] op_sel:[0,1]
	v_pk_fma_f32 v[10:11], v[184:185], v[10:11], v[210:211]
	v_pk_mul_f32 v[210:211], v[198:199], v[208:209] op_sel:[0,1]
	v_pk_fma_f32 v[12:13], v[190:191], v[12:13], v[210:211]
	global_store_dwordx4 v158, v[10:13], s[30:31] offset:3072 nt
	s_add_u32 s30, s30, 0x1000
	s_addc_u32 s31, s31, 0
	global_load_dwordx4 v[10:13], v158, s[28:29] offset:3072 nt
	s_add_u32 s28, s28, 0x1000
	s_addc_u32 s29, s29, 0
	ds_read_b128 v[202:205], v179 offset:400
	ds_read_b128 v[206:209], v179 offset:1424
	s_waitcnt lgkmcnt(2)
	s_waitcnt vmcnt(62)
	v_pk_fma_f32 v[142:143], v[232:233], v[134:135], v[142:143] op_sel_hi:[1,0,1]
	v_pk_fma_f32 v[144:145], v[234:235], v[134:135], v[144:145] op_sel_hi:[1,0,1]
	v_pk_mul_f32 v[210:211], v[200:201], v[138:139] op_sel_hi:[1,0]
	v_pk_fma_f32 v[232:233], v[184:185], v[232:233], v[210:211]
	v_pk_mul_f32 v[210:211], v[198:199], v[138:139] op_sel_hi:[1,0]
	v_pk_fma_f32 v[234:235], v[190:191], v[234:235], v[210:211]
	global_store_dwordx4 v158, v[232:235], s[30:31] nt
	s_nop 0
	global_load_dwordx4 v[232:235], v158, s[28:29] nt
	s_waitcnt vmcnt(62)
	v_pk_fma_f32 v[142:143], v[130:131], v[134:135], v[142:143] op_sel:[0,1,0]
	v_pk_fma_f32 v[144:145], v[132:133], v[134:135], v[144:145] op_sel:[0,1,0]
	v_pk_mul_f32 v[210:211], v[200:201], v[138:139] op_sel:[0,1]
	v_pk_fma_f32 v[130:131], v[184:185], v[130:131], v[210:211]
	v_pk_mul_f32 v[210:211], v[198:199], v[138:139] op_sel:[0,1]
	v_pk_fma_f32 v[132:133], v[190:191], v[132:133], v[210:211]
	global_store_dwordx4 v158, v[130:133], s[30:31] offset:1024 nt
	s_nop 0
	global_load_dwordx4 v[130:133], v158, s[28:29] offset:1024 nt
	s_waitcnt vmcnt(62)
	v_pk_fma_f32 v[142:143], v[126:127], v[136:137], v[142:143] op_sel_hi:[1,0,1]
	v_pk_fma_f32 v[144:145], v[128:129], v[136:137], v[144:145] op_sel_hi:[1,0,1]
	v_pk_mul_f32 v[210:211], v[200:201], v[140:141] op_sel_hi:[1,0]
	v_pk_fma_f32 v[126:127], v[184:185], v[126:127], v[210:211]
	v_pk_mul_f32 v[210:211], v[198:199], v[140:141] op_sel_hi:[1,0]
	v_pk_fma_f32 v[128:129], v[190:191], v[128:129], v[210:211]
	global_store_dwordx4 v158, v[126:129], s[30:31] offset:2048 nt
	s_nop 0
	global_load_dwordx4 v[126:129], v158, s[28:29] offset:2048 nt
	s_waitcnt vmcnt(62)
; __device__ __forceinline__ void mlstm_decode_wave(const Params& P, unsigned char* wl, int sh) {
;     ...
;     for (int dk0 = 0; dk0 < 256; dk0 += 32) { f32x4 c[32];
; #pragma unroll
;         for (int i = 0; i < 32; ++i) c[i] = __builtin_nontemporal_load((const f32x4*)(C0 + (dk0 + i) * 256));
; #pragma unroll
;         for (int i = 0; i < 32; ++i) { const float qd = sq[dk0 + i], kd = sk[dk0 + i]; part += qd * c[i]; __builtin_nontemporal_store(wc * c[i] + kd * wv, (f32x4*)(C1 + (dk0 + i) * 256)); } }
	v_pk_fma_f32 v[142:143], v[122:123], v[136:137], v[142:143] op_sel:[0,1,0]
	v_pk_fma_f32 v[144:145], v[124:125], v[136:137], v[144:145] op_sel:[0,1,0]
	v_pk_mul_f32 v[210:211], v[200:201], v[140:141] op_sel:[0,1]
	v_pk_fma_f32 v[122:123], v[184:185], v[122:123], v[210:211]
	v_pk_mul_f32 v[210:211], v[198:199], v[140:141] op_sel:[0,1]
	v_pk_fma_f32 v[124:125], v[190:191], v[124:125], v[210:211]
	global_store_dwordx4 v158, v[122:125], s[30:31] offset:3072 nt
	s_add_u32 s30, s30, 0x1000
	s_addc_u32 s31, s31, 0
	global_load_dwordx4 v[122:125], v158, s[28:29] offset:3072 nt
	s_add_u32 s28, s28, 0x1000
	s_addc_u32 s29, s29, 0
	ds_read_b128 v[134:137], v179 offset:416
	ds_read_b128 v[138:141], v179 offset:1440
	s_waitcnt lgkmcnt(2)
	s_waitcnt vmcnt(62)
	v_pk_fma_f32 v[142:143], v[118:119], v[202:203], v[142:143] op_sel_hi:[1,0,1]
	v_pk_fma_f32 v[144:145], v[120:121], v[202:203], v[144:145] op_sel_hi:[1,0,1]
	v_pk_mul_f32 v[210:211], v[200:201], v[206:207] op_sel_hi:[1,0]
	v_pk_fma_f32 v[118:119], v[184:185], v[118:119], v[210:211]
	v_pk_mul_f32 v[210:211], v[198:199], v[206:207] op_sel_hi:[1,0]
	v_pk_fma_f32 v[120:121], v[190:191], v[120:121], v[210:211]
	global_store_dwordx4 v158, v[118:121], s[30:31] nt
	s_nop 0
	global_load_dwordx4 v[118:121], v158, s[28:29] nt
	s_waitcnt vmcnt(62)
	v_pk_fma_f32 v[142:143], v[114:115], v[202:203], v[142:143] op_sel:[0,1,0]
	v_pk_fma_f32 v[144:145], v[116:117], v[202:203], v[144:145] op_sel:[0,1,0]
	v_pk_mul_f32 v[210:211], v[200:201], v[206:207] op_sel:[0,1]
	v_pk_fma_f32 v[114:115], v[184:185], v[114:115], v[210:211]
	v_pk_mul_f32 v[210:211], v[198:199], v[206:207] op_sel:[0,1]
	v_pk_fma_f32 v[116:117], v[190:191], v[116:117], v[210:211]
	global_store_dwordx4 v158, v[114:117], s[30:31] offset:1024 nt
	s_nop 0
	global_load_dwordx4 v[114:117], v158, s[28:29] offset:1024 nt
	s_waitcnt vmcnt(62)
	v_pk_fma_f32 v[142:143], v[110:111], v[204:205], v[142:143] op_sel_hi:[1,0,1]
	v_pk_fma_f32 v[144:145], v[112:113], v[204:205], v[144:145] op_sel_hi:[1,0,1]
	v_pk_mul_f32 v[210:211], v[200:201], v[208:209] op_sel_hi:[1,0]
	v_pk_fma_f32 v[110:111], v[184:185], v[110:111], v[210:211]
	v_pk_mul_f32 v[210:211], v[198:199], v[208:209] op_sel_hi:[1,0]
	v_pk_fma_f32 v[112:113], v[190:191], v[112:113], v[210:211]
	global_store_dwordx4 v158, v[110:113], s[30:31] offset:2048 nt
	s_nop 0
	global_load_dwordx4 v[110:113], v158, s[28:29] offset:2048 nt
	s_waitcnt vmcnt(62)
	v_pk_fma_f32 v[142:143], v[106:107], v[204:205], v[142:143] op_sel:[0,1,0]
	v_pk_fma_f32 v[144:145], v[108:109], v[204:205], v[144:145] op_sel:[0,1,0]
	v_pk_mul_f32 v[210:211], v[200:201], v[208:209] op_sel:[0,1]
	v_pk_fma_f32 v[106:107], v[184:185], v[106:107], v[210:211]
	v_pk_mul_f32 v[210:211], v[198:199], v[208:209] op_sel:[0,1]
	v_pk_fma_f32 v[108:109], v[190:191], v[108:109], v[210:211]
	global_store_dwordx4 v158, v[106:109], s[30:31] offset:3072 nt
	s_add_u32 s30, s30, 0x1000
	s_addc_u32 s31, s31, 0
	global_load_dwordx4 v[106:109], v158, s[28:29] offset:3072 nt
	s_add_u32 s28, s28, 0x1000
	s_addc_u32 s29, s29, 0
	ds_read_b128 v[202:205], v179 offset:432
	ds_read_b128 v[206:209], v179 offset:1456
	s_waitcnt lgkmcnt(2)
	s_waitcnt vmcnt(62)
	v_pk_fma_f32 v[142:143], v[102:103], v[134:135], v[142:143] op_sel_hi:[1,0,1]
	v_pk_fma_f32 v[144:145], v[104:105], v[134:135], v[144:145] op_sel_hi:[1,0,1]
	v_pk_mul_f32 v[210:211], v[200:201], v[138:139] op_sel_hi:[1,0]
	v_pk_fma_f32 v[102:103], v[184:185], v[102:103], v[210:211]
	v_pk_mul_f32 v[210:211], v[198:199], v[138:139] op_sel_hi:[1,0]
	v_pk_fma_f32 v[104:105], v[190:191], v[104:105], v[210:211]
	global_store_dwordx4 v158, v[102:105], s[30:31] nt
	s_nop 0
	global_load_dwordx4 v[102:105], v158, s[28:29] nt
	s_waitcnt vmcnt(62)
	v_pk_fma_f32 v[142:143], v[98:99], v[134:135], v[142:143] op_sel:[0,1,0]
	v_pk_fma_f32 v[144:145], v[100:101], v[134:135], v[144:145] op_sel:[0,1,0]
	v_pk_mul_f32 v[210:211], v[200:201], v[138:139] op_sel:[0,1]
	v_pk_fma_f32 v[98:99], v[184:185], v[98:99], v[210:211]
	v_pk_mul_f32 v[210:211], v[198:199], v[138:139] op_sel:[0,1]
	v_pk_fma_f32 v[100:101], v[190:191], v[100:101], v[210:211]
	global_store_dwordx4 v158, v[98:101], s[30:31] offset:1024 nt
	s_nop 0
	global_load_dwordx4 v[98:101], v158, s[28:29] offset:1024 nt
	s_waitcnt vmcnt(62)
	v_pk_fma_f32 v[142:143], v[94:95], v[136:137], v[142:143] op_sel_hi:[1,0,1]
	v_pk_fma_f32 v[144:145], v[96:97], v[136:137], v[144:145] op_sel_hi:[1,0,1]
	v_pk_mul_f32 v[210:211], v[200:201], v[140:141] op_sel_hi:[1,0]
	v_pk_fma_f32 v[94:95], v[184:185], v[94:95], v[210:211]
	v_pk_mul_f32 v[210:211], v[198:199], v[140:141] op_sel_hi:[1,0]
	v_pk_fma_f32 v[96:97], v[190:191], v[96:97], v[210:211]
	global_store_dwordx4 v158, v[94:97], s[30:31] offset:2048 nt
	s_nop 0
	global_load_dwordx4 v[94:97], v158, s[28:29] offset:2048 nt
	s_waitcnt vmcnt(62)
	v_pk_fma_f32 v[142:143], v[90:91], v[136:137], v[142:143] op_sel:[0,1,0]
	v_pk_fma_f32 v[144:145], v[92:93], v[136:137], v[144:145] op_sel:[0,1,0]
	v_pk_mul_f32 v[210:211], v[200:201], v[140:141] op_sel:[0,1]
	v_pk_fma_f32 v[90:91], v[184:185], v[90:91], v[210:211]
	v_pk_mul_f32 v[210:211], v[198:199], v[140:141] op_sel:[0,1]
	v_pk_fma_f32 v[92:93], v[190:191], v[92:93], v[210:211]
	global_store_dwordx4 v158, v[90:93], s[30:31] offset:3072 nt
	s_add_u32 s30, s30, 0x1000
	s_addc_u32 s31, s31, 0
	global_load_dwordx4 v[90:93], v158, s[28:29] offset:3072 nt
	s_add_u32 s28, s28, 0x1000
	s_addc_u32 s29, s29, 0
	ds_read_b128 v[134:137], v179 offset:448
	ds_read_b128 v[138:141], v179 offset:1472
	s_waitcnt lgkmcnt(2)
	s_waitcnt vmcnt(62)
; __device__ __forceinline__ void mlstm_decode_wave(const Params& P, unsigned char* wl, int sh) {
;     ...
;     for (int dk0 = 0; dk0 < 256; dk0 += 32) { f32x4 c[32];
; #pragma unroll
;         for (int i = 0; i < 32; ++i) c[i] = __builtin_nontemporal_load((const f32x4*)(C0 + (dk0 + i) * 256));
; #pragma unroll
;         for (int i = 0; i < 32; ++i) { const float qd = sq[dk0 + i], kd = sk[dk0 + i]; part += qd * c[i]; __builtin_nontemporal_store(wc * c[i] + kd * wv, (f32x4*)(C1 + (dk0 + i) * 256)); } }
	v_pk_fma_f32 v[142:143], v[86:87], v[202:203], v[142:143] op_sel_hi:[1,0,1]
	v_pk_fma_f32 v[144:145], v[88:89], v[202:203], v[144:145] op_sel_hi:[1,0,1]
	v_pk_mul_f32 v[210:211], v[200:201], v[206:207] op_sel_hi:[1,0]
	v_pk_fma_f32 v[86:87], v[184:185], v[86:87], v[210:211]
	v_pk_mul_f32 v[210:211], v[198:199], v[206:207] op_sel_hi:[1,0]
	v_pk_fma_f32 v[88:89], v[190:191], v[88:89], v[210:211]
	global_store_dwordx4 v158, v[86:89], s[30:31] nt
	s_nop 0
	global_load_dwordx4 v[86:89], v158, s[28:29] nt
	s_waitcnt vmcnt(62)
	v_pk_fma_f32 v[142:143], v[82:83], v[202:203], v[142:143] op_sel:[0,1,0]
	v_pk_fma_f32 v[144:145], v[84:85], v[202:203], v[144:145] op_sel:[0,1,0]
	v_pk_mul_f32 v[210:211], v[200:201], v[206:207] op_sel:[0,1]
	v_pk_fma_f32 v[82:83], v[184:185], v[82:83], v[210:211]
	v_pk_mul_f32 v[210:211], v[198:199], v[206:207] op_sel:[0,1]
	v_pk_fma_f32 v[84:85], v[190:191], v[84:85], v[210:211]
	global_store_dwordx4 v158, v[82:85], s[30:31] offset:1024 nt
	s_nop 0
	global_load_dwordx4 v[82:85], v158, s[28:29] offset:1024 nt
	s_waitcnt vmcnt(62)
	v_pk_fma_f32 v[142:143], v[78:79], v[204:205], v[142:143] op_sel_hi:[1,0,1]
	v_pk_fma_f32 v[144:145], v[80:81], v[204:205], v[144:145] op_sel_hi:[1,0,1]
	v_pk_mul_f32 v[210:211], v[200:201], v[208:209] op_sel_hi:[1,0]
	v_pk_fma_f32 v[78:79], v[184:185], v[78:79], v[210:211]
	v_pk_mul_f32 v[210:211], v[198:199], v[208:209] op_sel_hi:[1,0]
	v_pk_fma_f32 v[80:81], v[190:191], v[80:81], v[210:211]
	global_store_dwordx4 v158, v[78:81], s[30:31] offset:2048 nt
	s_nop 0
	global_load_dwordx4 v[78:81], v158, s[28:29] offset:2048 nt
	s_waitcnt vmcnt(62)
	v_pk_fma_f32 v[142:143], v[74:75], v[204:205], v[142:143] op_sel:[0,1,0]
	v_pk_fma_f32 v[144:145], v[76:77], v[204:205], v[144:145] op_sel:[0,1,0]
	v_pk_mul_f32 v[210:211], v[200:201], v[208:209] op_sel:[0,1]
	v_pk_fma_f32 v[74:75], v[184:185], v[74:75], v[210:211]
	v_pk_mul_f32 v[210:211], v[198:199], v[208:209] op_sel:[0,1]
	v_pk_fma_f32 v[76:77], v[190:191], v[76:77], v[210:211]
	global_store_dwordx4 v158, v[74:77], s[30:31] offset:3072 nt
	s_add_u32 s30, s30, 0x1000
	s_addc_u32 s31, s31, 0
	global_load_dwordx4 v[74:77], v158, s[28:29] offset:3072 nt
	s_add_u32 s28, s28, 0x1000
	s_addc_u32 s29, s29, 0
	ds_read_b128 v[202:205], v179 offset:464
	ds_read_b128 v[206:209], v179 offset:1488
	s_waitcnt lgkmcnt(2)
	s_waitcnt vmcnt(62)
	v_pk_fma_f32 v[142:143], v[70:71], v[134:135], v[142:143] op_sel_hi:[1,0,1]
	v_pk_fma_f32 v[144:145], v[72:73], v[134:135], v[144:145] op_sel_hi:[1,0,1]
	v_pk_mul_f32 v[210:211], v[200:201], v[138:139] op_sel_hi:[1,0]
	v_pk_fma_f32 v[70:71], v[184:185], v[70:71], v[210:211]
	v_pk_mul_f32 v[210:211], v[198:199], v[138:139] op_sel_hi:[1,0]
	v_pk_fma_f32 v[72:73], v[190:191], v[72:73], v[210:211]
	global_store_dwordx4 v158, v[70:73], s[30:31] nt
	s_nop 0
	global_load_dwordx4 v[70:73], v158, s[28:29] nt
	s_waitcnt vmcnt(62)
	v_pk_fma_f32 v[142:143], v[66:67], v[134:135], v[142:143] op_sel:[0,1,0]
	v_pk_fma_f32 v[144:145], v[68:69], v[134:135], v[144:145] op_sel:[0,1,0]
	v_pk_mul_f32 v[210:211], v[200:201], v[138:139] op_sel:[0,1]
	v_pk_fma_f32 v[66:67], v[184:185], v[66:67], v[210:211]
	v_pk_mul_f32 v[210:211], v[198:199], v[138:139] op_sel:[0,1]
	v_pk_fma_f32 v[68:69], v[190:191], v[68:69], v[210:211]
	global_store_dwordx4 v158, v[66:69], s[30:31] offset:1024 nt
	s_nop 0
	global_load_dwordx4 v[66:69], v158, s[28:29] offset:1024 nt
	s_waitcnt vmcnt(62)
	v_pk_fma_f32 v[142:143], v[62:63], v[136:137], v[142:143] op_sel_hi:[1,0,1]
	v_pk_fma_f32 v[144:145], v[64:65], v[136:137], v[144:145] op_sel_hi:[1,0,1]
	v_pk_mul_f32 v[210:211], v[200:201], v[140:141] op_sel_hi:[1,0]
	v_pk_fma_f32 v[62:63], v[184:185], v[62:63], v[210:211]
	v_pk_mul_f32 v[210:211], v[198:199], v[140:141] op_sel_hi:[1,0]
	v_pk_fma_f32 v[64:65], v[190:191], v[64:65], v[210:211]
	global_store_dwordx4 v158, v[62:65], s[30:31] offset:2048 nt
	s_nop 0
	global_load_dwordx4 v[62:65], v158, s[28:29] offset:2048 nt
	s_waitcnt vmcnt(62)
	v_pk_fma_f32 v[142:143], v[58:59], v[136:137], v[142:143] op_sel:[0,1,0]
	v_pk_fma_f32 v[144:145], v[60:61], v[136:137], v[144:145] op_sel:[0,1,0]
	v_pk_mul_f32 v[210:211], v[200:201], v[140:141] op_sel:[0,1]
	v_pk_fma_f32 v[58:59], v[184:185], v[58:59], v[210:211]
	v_pk_mul_f32 v[210:211], v[198:199], v[140:141] op_sel:[0,1]
	v_pk_fma_f32 v[60:61], v[190:191], v[60:61], v[210:211]
	global_store_dwordx4 v158, v[58:61], s[30:31] offset:3072 nt
	s_add_u32 s30, s30, 0x1000
	s_addc_u32 s31, s31, 0
	global_load_dwordx4 v[58:61], v158, s[28:29] offset:3072 nt
	s_add_u32 s28, s28, 0x1000
	s_addc_u32 s29, s29, 0
	ds_read_b128 v[134:137], v179 offset:480
	ds_read_b128 v[138:141], v179 offset:1504
	s_waitcnt lgkmcnt(2)
	s_waitcnt vmcnt(62)
	v_pk_fma_f32 v[142:143], v[54:55], v[202:203], v[142:143] op_sel_hi:[1,0,1]
	v_pk_fma_f32 v[144:145], v[56:57], v[202:203], v[144:145] op_sel_hi:[1,0,1]
	v_pk_mul_f32 v[210:211], v[200:201], v[206:207] op_sel_hi:[1,0]
	v_pk_fma_f32 v[54:55], v[184:185], v[54:55], v[210:211]
	v_pk_mul_f32 v[210:211], v[198:199], v[206:207] op_sel_hi:[1,0]
	v_pk_fma_f32 v[56:57], v[190:191], v[56:57], v[210:211]
	global_store_dwordx4 v158, v[54:57], s[30:31] nt
	s_nop 0
	global_load_dwordx4 v[54:57], v158, s[28:29] nt
	s_waitcnt vmcnt(62)
	v_pk_fma_f32 v[142:143], v[50:51], v[202:203], v[142:143] op_sel:[0,1,0]
	v_pk_fma_f32 v[144:145], v[52:53], v[202:203], v[144:145] op_sel:[0,1,0]
	v_pk_mul_f32 v[210:211], v[200:201], v[206:207] op_sel:[0,1]
	v_pk_fma_f32 v[50:51], v[184:185], v[50:51], v[210:211]
	v_pk_mul_f32 v[210:211], v[198:199], v[206:207] op_sel:[0,1]
	v_pk_fma_f32 v[52:53], v[190:191], v[52:53], v[210:211]
	global_store_dwordx4 v158, v[50:53], s[30:31] offset:1024 nt
	s_nop 0
	global_load_dwordx4 v[50:53], v158, s[28:29] offset:1024 nt
	s_waitcnt vmcnt(62)
; __device__ __forceinline__ void mlstm_decode_wave(const Params& P, unsigned char* wl, int sh) {
;     ...
;     for (int dk0 = 0; dk0 < 256; dk0 += 32) { f32x4 c[32];
; #pragma unroll
;         for (int i = 0; i < 32; ++i) c[i] = __builtin_nontemporal_load((const f32x4*)(C0 + (dk0 + i) * 256));
; #pragma unroll
;         for (int i = 0; i < 32; ++i) { const float qd = sq[dk0 + i], kd = sk[dk0 + i]; part += qd * c[i]; __builtin_nontemporal_store(wc * c[i] + kd * wv, (f32x4*)(C1 + (dk0 + i) * 256)); } }
	v_pk_fma_f32 v[142:143], v[46:47], v[204:205], v[142:143] op_sel_hi:[1,0,1]
	v_pk_fma_f32 v[144:145], v[48:49], v[204:205], v[144:145] op_sel_hi:[1,0,1]
	v_pk_mul_f32 v[210:211], v[200:201], v[208:209] op_sel_hi:[1,0]
	v_pk_fma_f32 v[46:47], v[184:185], v[46:47], v[210:211]
	v_pk_mul_f32 v[210:211], v[198:199], v[208:209] op_sel_hi:[1,0]
	v_pk_fma_f32 v[48:49], v[190:191], v[48:49], v[210:211]
	global_store_dwordx4 v158, v[46:49], s[30:31] offset:2048 nt
	s_nop 0
	global_load_dwordx4 v[46:49], v158, s[28:29] offset:2048 nt
	s_waitcnt vmcnt(62)
	v_pk_fma_f32 v[142:143], v[42:43], v[204:205], v[142:143] op_sel:[0,1,0]
	v_pk_fma_f32 v[144:145], v[44:45], v[204:205], v[144:145] op_sel:[0,1,0]
	v_pk_mul_f32 v[210:211], v[200:201], v[208:209] op_sel:[0,1]
	v_pk_fma_f32 v[42:43], v[184:185], v[42:43], v[210:211]
	v_pk_mul_f32 v[210:211], v[198:199], v[208:209] op_sel:[0,1]
	v_pk_fma_f32 v[44:45], v[190:191], v[44:45], v[210:211]
	global_store_dwordx4 v158, v[42:45], s[30:31] offset:3072 nt
	s_add_u32 s30, s30, 0x1000
	s_addc_u32 s31, s31, 0
	global_load_dwordx4 v[42:45], v158, s[28:29] offset:3072 nt
	s_add_u32 s28, s28, 0x1000
	s_addc_u32 s29, s29, 0
	ds_read_b128 v[202:205], v179 offset:496
	ds_read_b128 v[206:209], v179 offset:1520
	s_waitcnt lgkmcnt(2)
	s_waitcnt vmcnt(62)
	v_pk_fma_f32 v[142:143], v[38:39], v[134:135], v[142:143] op_sel_hi:[1,0,1]
	v_pk_fma_f32 v[144:145], v[40:41], v[134:135], v[144:145] op_sel_hi:[1,0,1]
	v_pk_mul_f32 v[210:211], v[200:201], v[138:139] op_sel_hi:[1,0]
	v_pk_fma_f32 v[38:39], v[184:185], v[38:39], v[210:211]
	v_pk_mul_f32 v[210:211], v[198:199], v[138:139] op_sel_hi:[1,0]
	v_pk_fma_f32 v[40:41], v[190:191], v[40:41], v[210:211]
	global_store_dwordx4 v158, v[38:41], s[30:31] nt
	s_nop 0
	global_load_dwordx4 v[38:41], v158, s[28:29] nt
	s_waitcnt vmcnt(62)
	v_pk_fma_f32 v[142:143], v[34:35], v[134:135], v[142:143] op_sel:[0,1,0]
	v_pk_fma_f32 v[144:145], v[36:37], v[134:135], v[144:145] op_sel:[0,1,0]
	v_pk_mul_f32 v[210:211], v[200:201], v[138:139] op_sel:[0,1]
	v_pk_fma_f32 v[34:35], v[184:185], v[34:35], v[210:211]
	v_pk_mul_f32 v[210:211], v[198:199], v[138:139] op_sel:[0,1]
	v_pk_fma_f32 v[36:37], v[190:191], v[36:37], v[210:211]
	global_store_dwordx4 v158, v[34:37], s[30:31] offset:1024 nt
	s_nop 0
	global_load_dwordx4 v[34:37], v158, s[28:29] offset:1024 nt
	s_waitcnt vmcnt(62)
	v_pk_fma_f32 v[142:143], v[30:31], v[136:137], v[142:143] op_sel_hi:[1,0,1]
	v_pk_fma_f32 v[144:145], v[32:33], v[136:137], v[144:145] op_sel_hi:[1,0,1]
	v_pk_mul_f32 v[210:211], v[200:201], v[140:141] op_sel_hi:[1,0]
	v_pk_fma_f32 v[30:31], v[184:185], v[30:31], v[210:211]
	v_pk_mul_f32 v[210:211], v[198:199], v[140:141] op_sel_hi:[1,0]
	v_pk_fma_f32 v[32:33], v[190:191], v[32:33], v[210:211]
	global_store_dwordx4 v158, v[30:33], s[30:31] offset:2048 nt
	s_nop 0
	global_load_dwordx4 v[30:33], v158, s[28:29] offset:2048 nt
	s_waitcnt vmcnt(62)
	v_pk_fma_f32 v[142:143], v[26:27], v[136:137], v[142:143] op_sel:[0,1,0]
	v_pk_fma_f32 v[144:145], v[28:29], v[136:137], v[144:145] op_sel:[0,1,0]
	v_pk_mul_f32 v[210:211], v[200:201], v[140:141] op_sel:[0,1]
	v_pk_fma_f32 v[26:27], v[184:185], v[26:27], v[210:211]
	v_pk_mul_f32 v[210:211], v[198:199], v[140:141] op_sel:[0,1]
	v_pk_fma_f32 v[28:29], v[190:191], v[28:29], v[210:211]
	global_store_dwordx4 v158, v[26:29], s[30:31] offset:3072 nt
	s_add_u32 s30, s30, 0x1000
	s_addc_u32 s31, s31, 0
	global_load_dwordx4 v[26:29], v158, s[28:29] offset:3072 nt
	s_add_u32 s28, s28, 0x1000
	s_addc_u32 s29, s29, 0
	ds_read_b128 v[134:137], v179 offset:512
	ds_read_b128 v[138:141], v179 offset:1536
	s_waitcnt lgkmcnt(2)
	s_waitcnt vmcnt(62)
	v_pk_fma_f32 v[142:143], v[22:23], v[202:203], v[142:143] op_sel_hi:[1,0,1]
	v_pk_fma_f32 v[144:145], v[24:25], v[202:203], v[144:145] op_sel_hi:[1,0,1]
	v_pk_mul_f32 v[210:211], v[200:201], v[206:207] op_sel_hi:[1,0]
	v_pk_fma_f32 v[22:23], v[184:185], v[22:23], v[210:211]
	v_pk_mul_f32 v[210:211], v[198:199], v[206:207] op_sel_hi:[1,0]
	v_pk_fma_f32 v[24:25], v[190:191], v[24:25], v[210:211]
	global_store_dwordx4 v158, v[22:25], s[30:31] nt
	s_nop 0
	global_load_dwordx4 v[22:25], v158, s[28:29] nt
	s_waitcnt vmcnt(62)
	v_pk_fma_f32 v[142:143], v[18:19], v[202:203], v[142:143] op_sel:[0,1,0]
	v_pk_fma_f32 v[144:145], v[20:21], v[202:203], v[144:145] op_sel:[0,1,0]
	v_pk_mul_f32 v[210:211], v[200:201], v[206:207] op_sel:[0,1]
	v_pk_fma_f32 v[18:19], v[184:185], v[18:19], v[210:211]
	v_pk_mul_f32 v[210:211], v[198:199], v[206:207] op_sel:[0,1]
	v_pk_fma_f32 v[20:21], v[190:191], v[20:21], v[210:211]
	global_store_dwordx4 v158, v[18:21], s[30:31] offset:1024 nt
	s_nop 0
	global_load_dwordx4 v[18:21], v158, s[28:29] offset:1024 nt
	s_waitcnt vmcnt(62)
	v_pk_fma_f32 v[142:143], v[14:15], v[204:205], v[142:143] op_sel_hi:[1,0,1]
	v_pk_fma_f32 v[144:145], v[16:17], v[204:205], v[144:145] op_sel_hi:[1,0,1]
	v_pk_mul_f32 v[210:211], v[200:201], v[208:209] op_sel_hi:[1,0]
	v_pk_fma_f32 v[14:15], v[184:185], v[14:15], v[210:211]
	v_pk_mul_f32 v[210:211], v[198:199], v[208:209] op_sel_hi:[1,0]
	v_pk_fma_f32 v[16:17], v[190:191], v[16:17], v[210:211]
	global_store_dwordx4 v158, v[14:17], s[30:31] offset:2048 nt
	s_nop 0
	global_load_dwordx4 v[14:17], v158, s[28:29] offset:2048 nt
	s_waitcnt vmcnt(62)
	v_pk_fma_f32 v[142:143], v[10:11], v[204:205], v[142:143] op_sel:[0,1,0]
	v_pk_fma_f32 v[144:145], v[12:13], v[204:205], v[144:145] op_sel:[0,1,0]
	v_pk_mul_f32 v[210:211], v[200:201], v[208:209] op_sel:[0,1]
	v_pk_fma_f32 v[10:11], v[184:185], v[10:11], v[210:211]
	v_pk_mul_f32 v[210:211], v[198:199], v[208:209] op_sel:[0,1]
	v_pk_fma_f32 v[12:13], v[190:191], v[12:13], v[210:211]
	global_store_dwordx4 v158, v[10:13], s[30:31] offset:3072 nt
	s_add_u32 s30, s30, 0x1000
	s_addc_u32 s31, s31, 0
	global_load_dwordx4 v[10:13], v158, s[28:29] offset:3072 nt
	s_add_u32 s28, s28, 0x1000
	s_addc_u32 s29, s29, 0
	ds_read_b128 v[202:205], v179 offset:528
	ds_read_b128 v[206:209], v179 offset:1552
	s_waitcnt lgkmcnt(2)
; __device__ __forceinline__ void mlstm_decode_wave(const Params& P, unsigned char* wl, int sh) {
;     ...
;     for (int dk0 = 0; dk0 < 256; dk0 += 32) { f32x4 c[32];
; #pragma unroll
;         for (int i = 0; i < 32; ++i) c[i] = __builtin_nontemporal_load((const f32x4*)(C0 + (dk0 + i) * 256));
; #pragma unroll
;         for (int i = 0; i < 32; ++i) { const float qd = sq[dk0 + i], kd = sk[dk0 + i]; part += qd * c[i]; __builtin_nontemporal_store(wc * c[i] + kd * wv, (f32x4*)(C1 + (dk0 + i) * 256)); } }
	s_waitcnt vmcnt(62)
	v_pk_fma_f32 v[142:143], v[232:233], v[134:135], v[142:143] op_sel_hi:[1,0,1]
	v_pk_fma_f32 v[144:145], v[234:235], v[134:135], v[144:145] op_sel_hi:[1,0,1]
	v_pk_mul_f32 v[210:211], v[200:201], v[138:139] op_sel_hi:[1,0]
	v_pk_fma_f32 v[232:233], v[184:185], v[232:233], v[210:211]
	v_pk_mul_f32 v[210:211], v[198:199], v[138:139] op_sel_hi:[1,0]
	v_pk_fma_f32 v[234:235], v[190:191], v[234:235], v[210:211]
	global_store_dwordx4 v158, v[232:235], s[30:31] nt
	s_nop 0
	global_load_dwordx4 v[232:235], v158, s[28:29] nt
	s_waitcnt vmcnt(62)
	v_pk_fma_f32 v[142:143], v[130:131], v[134:135], v[142:143] op_sel:[0,1,0]
	v_pk_fma_f32 v[144:145], v[132:133], v[134:135], v[144:145] op_sel:[0,1,0]
	v_pk_mul_f32 v[210:211], v[200:201], v[138:139] op_sel:[0,1]
	v_pk_fma_f32 v[130:131], v[184:185], v[130:131], v[210:211]
	v_pk_mul_f32 v[210:211], v[198:199], v[138:139] op_sel:[0,1]
	v_pk_fma_f32 v[132:133], v[190:191], v[132:133], v[210:211]
	global_store_dwordx4 v158, v[130:133], s[30:31] offset:1024 nt
	s_nop 0
	global_load_dwordx4 v[130:133], v158, s[28:29] offset:1024 nt
	s_waitcnt vmcnt(62)
	v_pk_fma_f32 v[142:143], v[126:127], v[136:137], v[142:143] op_sel_hi:[1,0,1]
	v_pk_fma_f32 v[144:145], v[128:129], v[136:137], v[144:145] op_sel_hi:[1,0,1]
	v_pk_mul_f32 v[210:211], v[200:201], v[140:141] op_sel_hi:[1,0]
	v_pk_fma_f32 v[126:127], v[184:185], v[126:127], v[210:211]
	v_pk_mul_f32 v[210:211], v[198:199], v[140:141] op_sel_hi:[1,0]
	v_pk_fma_f32 v[128:129], v[190:191], v[128:129], v[210:211]
	global_store_dwordx4 v158, v[126:129], s[30:31] offset:2048 nt
	s_nop 0
	global_load_dwordx4 v[126:129], v158, s[28:29] offset:2048 nt
	s_waitcnt vmcnt(62)
	v_pk_fma_f32 v[142:143], v[122:123], v[136:137], v[142:143] op_sel:[0,1,0]
	v_pk_fma_f32 v[144:145], v[124:125], v[136:137], v[144:145] op_sel:[0,1,0]
	v_pk_mul_f32 v[210:211], v[200:201], v[140:141] op_sel:[0,1]
	v_pk_fma_f32 v[122:123], v[184:185], v[122:123], v[210:211]
	v_pk_mul_f32 v[210:211], v[198:199], v[140:141] op_sel:[0,1]
	v_pk_fma_f32 v[124:125], v[190:191], v[124:125], v[210:211]
	global_store_dwordx4 v158, v[122:125], s[30:31] offset:3072 nt
	s_add_u32 s30, s30, 0x1000
	s_addc_u32 s31, s31, 0
	global_load_dwordx4 v[122:125], v158, s[28:29] offset:3072 nt
	s_add_u32 s28, s28, 0x1000
	s_addc_u32 s29, s29, 0
	ds_read_b128 v[134:137], v179 offset:544
	ds_read_b128 v[138:141], v179 offset:1568
	s_waitcnt lgkmcnt(2)
	s_waitcnt vmcnt(62)
	v_pk_fma_f32 v[142:143], v[118:119], v[202:203], v[142:143] op_sel_hi:[1,0,1]
	v_pk_fma_f32 v[144:145], v[120:121], v[202:203], v[144:145] op_sel_hi:[1,0,1]
	v_pk_mul_f32 v[210:211], v[200:201], v[206:207] op_sel_hi:[1,0]
	v_pk_fma_f32 v[118:119], v[184:185], v[118:119], v[210:211]
	v_pk_mul_f32 v[210:211], v[198:199], v[206:207] op_sel_hi:[1,0]
	v_pk_fma_f32 v[120:121], v[190:191], v[120:121], v[210:211]
	global_store_dwordx4 v158, v[118:121], s[30:31] nt
	s_nop 0
	global_load_dwordx4 v[118:121], v158, s[28:29] nt
	s_waitcnt vmcnt(62)
	v_pk_fma_f32 v[142:143], v[114:115], v[202:203], v[142:143] op_sel:[0,1,0]
	v_pk_fma_f32 v[144:145], v[116:117], v[202:203], v[144:145] op_sel:[0,1,0]
	v_pk_mul_f32 v[210:211], v[200:201], v[206:207] op_sel:[0,1]
	v_pk_fma_f32 v[114:115], v[184:185], v[114:115], v[210:211]
	v_pk_mul_f32 v[210:211], v[198:199], v[206:207] op_sel:[0,1]
	v_pk_fma_f32 v[116:117], v[190:191], v[116:117], v[210:211]
	global_store_dwordx4 v158, v[114:117], s[30:31] offset:1024 nt
	s_nop 0
	global_load_dwordx4 v[114:117], v158, s[28:29] offset:1024 nt
	s_waitcnt vmcnt(62)
	v_pk_fma_f32 v[142:143], v[110:111], v[204:205], v[142:143] op_sel_hi:[1,0,1]
	v_pk_fma_f32 v[144:145], v[112:113], v[204:205], v[144:145] op_sel_hi:[1,0,1]
	v_pk_mul_f32 v[210:211], v[200:201], v[208:209] op_sel_hi:[1,0]
	v_pk_fma_f32 v[110:111], v[184:185], v[110:111], v[210:211]
	v_pk_mul_f32 v[210:211], v[198:199], v[208:209] op_sel_hi:[1,0]
	v_pk_fma_f32 v[112:113], v[190:191], v[112:113], v[210:211]
	global_store_dwordx4 v158, v[110:113], s[30:31] offset:2048 nt
	s_nop 0
	global_load_dwordx4 v[110:113], v158, s[28:29] offset:2048 nt
	s_waitcnt vmcnt(62)
	v_pk_fma_f32 v[142:143], v[106:107], v[204:205], v[142:143] op_sel:[0,1,0]
	v_pk_fma_f32 v[144:145], v[108:109], v[204:205], v[144:145] op_sel:[0,1,0]
	v_pk_mul_f32 v[210:211], v[200:201], v[208:209] op_sel:[0,1]
	v_pk_fma_f32 v[106:107], v[184:185], v[106:107], v[210:211]
	v_pk_mul_f32 v[210:211], v[198:199], v[208:209] op_sel:[0,1]
	v_pk_fma_f32 v[108:109], v[190:191], v[108:109], v[210:211]
	global_store_dwordx4 v158, v[106:109], s[30:31] offset:3072 nt
	s_add_u32 s30, s30, 0x1000
	s_addc_u32 s31, s31, 0
	global_load_dwordx4 v[106:109], v158, s[28:29] offset:3072 nt
	s_add_u32 s28, s28, 0x1000
	s_addc_u32 s29, s29, 0
	ds_read_b128 v[202:205], v179 offset:560
	ds_read_b128 v[206:209], v179 offset:1584
	s_waitcnt lgkmcnt(2)
	s_waitcnt vmcnt(62)
	v_pk_fma_f32 v[142:143], v[102:103], v[134:135], v[142:143] op_sel_hi:[1,0,1]
	v_pk_fma_f32 v[144:145], v[104:105], v[134:135], v[144:145] op_sel_hi:[1,0,1]
	v_pk_mul_f32 v[210:211], v[200:201], v[138:139] op_sel_hi:[1,0]
	v_pk_fma_f32 v[102:103], v[184:185], v[102:103], v[210:211]
	v_pk_mul_f32 v[210:211], v[198:199], v[138:139] op_sel_hi:[1,0]
	v_pk_fma_f32 v[104:105], v[190:191], v[104:105], v[210:211]
	global_store_dwordx4 v158, v[102:105], s[30:31] nt
	s_nop 0
	global_load_dwordx4 v[102:105], v158, s[28:29] nt
	s_waitcnt vmcnt(62)
; __device__ __forceinline__ void mlstm_decode_wave(const Params& P, unsigned char* wl, int sh) {
;     ...
;     for (int dk0 = 0; dk0 < 256; dk0 += 32) { f32x4 c[32];
; #pragma unroll
;         for (int i = 0; i < 32; ++i) c[i] = __builtin_nontemporal_load((const f32x4*)(C0 + (dk0 + i) * 256));
; #pragma unroll
;         for (int i = 0; i < 32; ++i) { const float qd = sq[dk0 + i], kd = sk[dk0 + i]; part += qd * c[i]; __builtin_nontemporal_store(wc * c[i] + kd * wv, (f32x4*)(C1 + (dk0 + i) * 256)); } }
	v_pk_fma_f32 v[142:143], v[98:99], v[134:135], v[142:143] op_sel:[0,1,0]
	v_pk_fma_f32 v[144:145], v[100:101], v[134:135], v[144:145] op_sel:[0,1,0]
	v_pk_mul_f32 v[210:211], v[200:201], v[138:139] op_sel:[0,1]
	v_pk_fma_f32 v[98:99], v[184:185], v[98:99], v[210:211]
	v_pk_mul_f32 v[210:211], v[198:199], v[138:139] op_sel:[0,1]
	v_pk_fma_f32 v[100:101], v[190:191], v[100:101], v[210:211]
	global_store_dwordx4 v158, v[98:101], s[30:31] offset:1024 nt
	s_nop 0
	global_load_dwordx4 v[98:101], v158, s[28:29] offset:1024 nt
	s_waitcnt vmcnt(62)
	v_pk_fma_f32 v[142:143], v[94:95], v[136:137], v[142:143] op_sel_hi:[1,0,1]
	v_pk_fma_f32 v[144:145], v[96:97], v[136:137], v[144:145] op_sel_hi:[1,0,1]
	v_pk_mul_f32 v[210:211], v[200:201], v[140:141] op_sel_hi:[1,0]
	v_pk_fma_f32 v[94:95], v[184:185], v[94:95], v[210:211]
	v_pk_mul_f32 v[210:211], v[198:199], v[140:141] op_sel_hi:[1,0]
	v_pk_fma_f32 v[96:97], v[190:191], v[96:97], v[210:211]
	global_store_dwordx4 v158, v[94:97], s[30:31] offset:2048 nt
	s_nop 0
	global_load_dwordx4 v[94:97], v158, s[28:29] offset:2048 nt
	s_waitcnt vmcnt(62)
	v_pk_fma_f32 v[142:143], v[90:91], v[136:137], v[142:143] op_sel:[0,1,0]
	v_pk_fma_f32 v[144:145], v[92:93], v[136:137], v[144:145] op_sel:[0,1,0]
	v_pk_mul_f32 v[210:211], v[200:201], v[140:141] op_sel:[0,1]
	v_pk_fma_f32 v[90:91], v[184:185], v[90:91], v[210:211]
	v_pk_mul_f32 v[210:211], v[198:199], v[140:141] op_sel:[0,1]
	v_pk_fma_f32 v[92:93], v[190:191], v[92:93], v[210:211]
	global_store_dwordx4 v158, v[90:93], s[30:31] offset:3072 nt
	s_add_u32 s30, s30, 0x1000
	s_addc_u32 s31, s31, 0
	global_load_dwordx4 v[90:93], v158, s[28:29] offset:3072 nt
	s_add_u32 s28, s28, 0x1000
	s_addc_u32 s29, s29, 0
	ds_read_b128 v[134:137], v179 offset:576
	ds_read_b128 v[138:141], v179 offset:1600
	s_waitcnt lgkmcnt(2)
	s_waitcnt vmcnt(62)
	v_pk_fma_f32 v[142:143], v[86:87], v[202:203], v[142:143] op_sel_hi:[1,0,1]
	v_pk_fma_f32 v[144:145], v[88:89], v[202:203], v[144:145] op_sel_hi:[1,0,1]
	v_pk_mul_f32 v[210:211], v[200:201], v[206:207] op_sel_hi:[1,0]
	v_pk_fma_f32 v[86:87], v[184:185], v[86:87], v[210:211]
	v_pk_mul_f32 v[210:211], v[198:199], v[206:207] op_sel_hi:[1,0]
	v_pk_fma_f32 v[88:89], v[190:191], v[88:89], v[210:211]
	global_store_dwordx4 v158, v[86:89], s[30:31] nt
	s_nop 0
	global_load_dwordx4 v[86:89], v158, s[28:29] nt
	s_waitcnt vmcnt(62)
	v_pk_fma_f32 v[142:143], v[82:83], v[202:203], v[142:143] op_sel:[0,1,0]
	v_pk_fma_f32 v[144:145], v[84:85], v[202:203], v[144:145] op_sel:[0,1,0]
	v_pk_mul_f32 v[210:211], v[200:201], v[206:207] op_sel:[0,1]
	v_pk_fma_f32 v[82:83], v[184:185], v[82:83], v[210:211]
	v_pk_mul_f32 v[210:211], v[198:199], v[206:207] op_sel:[0,1]
	v_pk_fma_f32 v[84:85], v[190:191], v[84:85], v[210:211]
	global_store_dwordx4 v158, v[82:85], s[30:31] offset:1024 nt
	s_nop 0
	global_load_dwordx4 v[82:85], v158, s[28:29] offset:1024 nt
	s_waitcnt vmcnt(62)
	v_pk_fma_f32 v[142:143], v[78:79], v[204:205], v[142:143] op_sel_hi:[1,0,1]
	v_pk_fma_f32 v[144:145], v[80:81], v[204:205], v[144:145] op_sel_hi:[1,0,1]
	v_pk_mul_f32 v[210:211], v[200:201], v[208:209] op_sel_hi:[1,0]
	v_pk_fma_f32 v[78:79], v[184:185], v[78:79], v[210:211]
	v_pk_mul_f32 v[210:211], v[198:199], v[208:209] op_sel_hi:[1,0]
	v_pk_fma_f32 v[80:81], v[190:191], v[80:81], v[210:211]
	global_store_dwordx4 v158, v[78:81], s[30:31] offset:2048 nt
	s_nop 0
	global_load_dwordx4 v[78:81], v158, s[28:29] offset:2048 nt
	s_waitcnt vmcnt(62)
	v_pk_fma_f32 v[142:143], v[74:75], v[204:205], v[142:143] op_sel:[0,1,0]
	v_pk_fma_f32 v[144:145], v[76:77], v[204:205], v[144:145] op_sel:[0,1,0]
	v_pk_mul_f32 v[210:211], v[200:201], v[208:209] op_sel:[0,1]
	v_pk_fma_f32 v[74:75], v[184:185], v[74:75], v[210:211]
	v_pk_mul_f32 v[210:211], v[198:199], v[208:209] op_sel:[0,1]
	v_pk_fma_f32 v[76:77], v[190:191], v[76:77], v[210:211]
	global_store_dwordx4 v158, v[74:77], s[30:31] offset:3072 nt
	s_add_u32 s30, s30, 0x1000
	s_addc_u32 s31, s31, 0
	global_load_dwordx4 v[74:77], v158, s[28:29] offset:3072 nt
	s_add_u32 s28, s28, 0x1000
	s_addc_u32 s29, s29, 0
	ds_read_b128 v[202:205], v179 offset:592
	ds_read_b128 v[206:209], v179 offset:1616
	s_waitcnt lgkmcnt(2)
	s_waitcnt vmcnt(62)
	v_pk_fma_f32 v[142:143], v[70:71], v[134:135], v[142:143] op_sel_hi:[1,0,1]
	v_pk_fma_f32 v[144:145], v[72:73], v[134:135], v[144:145] op_sel_hi:[1,0,1]
	v_pk_mul_f32 v[210:211], v[200:201], v[138:139] op_sel_hi:[1,0]
	v_pk_fma_f32 v[70:71], v[184:185], v[70:71], v[210:211]
	v_pk_mul_f32 v[210:211], v[198:199], v[138:139] op_sel_hi:[1,0]
	v_pk_fma_f32 v[72:73], v[190:191], v[72:73], v[210:211]
	global_store_dwordx4 v158, v[70:73], s[30:31] nt
	s_nop 0
	global_load_dwordx4 v[70:73], v158, s[28:29] nt
	s_waitcnt vmcnt(62)
	v_pk_fma_f32 v[142:143], v[66:67], v[134:135], v[142:143] op_sel:[0,1,0]
	v_pk_fma_f32 v[144:145], v[68:69], v[134:135], v[144:145] op_sel:[0,1,0]
	v_pk_mul_f32 v[210:211], v[200:201], v[138:139] op_sel:[0,1]
	v_pk_fma_f32 v[66:67], v[184:185], v[66:67], v[210:211]
	v_pk_mul_f32 v[210:211], v[198:199], v[138:139] op_sel:[0,1]
	v_pk_fma_f32 v[68:69], v[190:191], v[68:69], v[210:211]
	global_store_dwordx4 v158, v[66:69], s[30:31] offset:1024 nt
	s_nop 0
	global_load_dwordx4 v[66:69], v158, s[28:29] offset:1024 nt
	s_waitcnt vmcnt(62)
	v_pk_fma_f32 v[142:143], v[62:63], v[136:137], v[142:143] op_sel_hi:[1,0,1]
	v_pk_fma_f32 v[144:145], v[64:65], v[136:137], v[144:145] op_sel_hi:[1,0,1]
	v_pk_mul_f32 v[210:211], v[200:201], v[140:141] op_sel_hi:[1,0]
	v_pk_fma_f32 v[62:63], v[184:185], v[62:63], v[210:211]
	v_pk_mul_f32 v[210:211], v[198:199], v[140:141] op_sel_hi:[1,0]
	v_pk_fma_f32 v[64:65], v[190:191], v[64:65], v[210:211]
	global_store_dwordx4 v158, v[62:65], s[30:31] offset:2048 nt
	s_nop 0
	global_load_dwordx4 v[62:65], v158, s[28:29] offset:2048 nt
	s_waitcnt vmcnt(62)
; __device__ __forceinline__ void mlstm_decode_wave(const Params& P, unsigned char* wl, int sh) {
;     ...
;     for (int dk0 = 0; dk0 < 256; dk0 += 32) { f32x4 c[32];
; #pragma unroll
;         for (int i = 0; i < 32; ++i) c[i] = __builtin_nontemporal_load((const f32x4*)(C0 + (dk0 + i) * 256));
; #pragma unroll
;         for (int i = 0; i < 32; ++i) { const float qd = sq[dk0 + i], kd = sk[dk0 + i]; part += qd * c[i]; __builtin_nontemporal_store(wc * c[i] + kd * wv, (f32x4*)(C1 + (dk0 + i) * 256)); } }
	v_pk_fma_f32 v[142:143], v[58:59], v[136:137], v[142:143] op_sel:[0,1,0]
	v_pk_fma_f32 v[144:145], v[60:61], v[136:137], v[144:145] op_sel:[0,1,0]
	v_pk_mul_f32 v[210:211], v[200:201], v[140:141] op_sel:[0,1]
	v_pk_fma_f32 v[58:59], v[184:185], v[58:59], v[210:211]
	v_pk_mul_f32 v[210:211], v[198:199], v[140:141] op_sel:[0,1]
	v_pk_fma_f32 v[60:61], v[190:191], v[60:61], v[210:211]
	global_store_dwordx4 v158, v[58:61], s[30:31] offset:3072 nt
	s_add_u32 s30, s30, 0x1000
	s_addc_u32 s31, s31, 0
	global_load_dwordx4 v[58:61], v158, s[28:29] offset:3072 nt
	s_add_u32 s28, s28, 0x1000
	s_addc_u32 s29, s29, 0
	ds_read_b128 v[134:137], v179 offset:608
	ds_read_b128 v[138:141], v179 offset:1632
	s_waitcnt lgkmcnt(2)
	s_waitcnt vmcnt(62)
	v_pk_fma_f32 v[142:143], v[54:55], v[202:203], v[142:143] op_sel_hi:[1,0,1]
	v_pk_fma_f32 v[144:145], v[56:57], v[202:203], v[144:145] op_sel_hi:[1,0,1]
	v_pk_mul_f32 v[210:211], v[200:201], v[206:207] op_sel_hi:[1,0]
	v_pk_fma_f32 v[54:55], v[184:185], v[54:55], v[210:211]
	v_pk_mul_f32 v[210:211], v[198:199], v[206:207] op_sel_hi:[1,0]
	v_pk_fma_f32 v[56:57], v[190:191], v[56:57], v[210:211]
	global_store_dwordx4 v158, v[54:57], s[30:31] nt
	s_nop 0
	global_load_dwordx4 v[54:57], v158, s[28:29] nt
	s_waitcnt vmcnt(62)
	v_pk_fma_f32 v[142:143], v[50:51], v[202:203], v[142:143] op_sel:[0,1,0]
	v_pk_fma_f32 v[144:145], v[52:53], v[202:203], v[144:145] op_sel:[0,1,0]
	v_pk_mul_f32 v[210:211], v[200:201], v[206:207] op_sel:[0,1]
	v_pk_fma_f32 v[50:51], v[184:185], v[50:51], v[210:211]
	v_pk_mul_f32 v[210:211], v[198:199], v[206:207] op_sel:[0,1]
	v_pk_fma_f32 v[52:53], v[190:191], v[52:53], v[210:211]
	global_store_dwordx4 v158, v[50:53], s[30:31] offset:1024 nt
	s_nop 0
	global_load_dwordx4 v[50:53], v158, s[28:29] offset:1024 nt
	s_waitcnt vmcnt(62)
	v_pk_fma_f32 v[142:143], v[46:47], v[204:205], v[142:143] op_sel_hi:[1,0,1]
	v_pk_fma_f32 v[144:145], v[48:49], v[204:205], v[144:145] op_sel_hi:[1,0,1]
	v_pk_mul_f32 v[210:211], v[200:201], v[208:209] op_sel_hi:[1,0]
	v_pk_fma_f32 v[46:47], v[184:185], v[46:47], v[210:211]
	v_pk_mul_f32 v[210:211], v[198:199], v[208:209] op_sel_hi:[1,0]
	v_pk_fma_f32 v[48:49], v[190:191], v[48:49], v[210:211]
	global_store_dwordx4 v158, v[46:49], s[30:31] offset:2048 nt
	s_nop 0
	global_load_dwordx4 v[46:49], v158, s[28:29] offset:2048 nt
	s_waitcnt vmcnt(62)
	v_pk_fma_f32 v[142:143], v[42:43], v[204:205], v[142:143] op_sel:[0,1,0]
	v_pk_fma_f32 v[144:145], v[44:45], v[204:205], v[144:145] op_sel:[0,1,0]
	v_pk_mul_f32 v[210:211], v[200:201], v[208:209] op_sel:[0,1]
	v_pk_fma_f32 v[42:43], v[184:185], v[42:43], v[210:211]
	v_pk_mul_f32 v[210:211], v[198:199], v[208:209] op_sel:[0,1]
	v_pk_fma_f32 v[44:45], v[190:191], v[44:45], v[210:211]
	global_store_dwordx4 v158, v[42:45], s[30:31] offset:3072 nt
	s_add_u32 s30, s30, 0x1000
	s_addc_u32 s31, s31, 0
	global_load_dwordx4 v[42:45], v158, s[28:29] offset:3072 nt
	s_add_u32 s28, s28, 0x1000
	s_addc_u32 s29, s29, 0
	ds_read_b128 v[202:205], v179 offset:624
	ds_read_b128 v[206:209], v179 offset:1648
	s_waitcnt lgkmcnt(2)
	s_waitcnt vmcnt(62)
	v_pk_fma_f32 v[142:143], v[38:39], v[134:135], v[142:143] op_sel_hi:[1,0,1]
	v_pk_fma_f32 v[144:145], v[40:41], v[134:135], v[144:145] op_sel_hi:[1,0,1]
	v_pk_mul_f32 v[210:211], v[200:201], v[138:139] op_sel_hi:[1,0]
	v_pk_fma_f32 v[38:39], v[184:185], v[38:39], v[210:211]
	v_pk_mul_f32 v[210:211], v[198:199], v[138:139] op_sel_hi:[1,0]
	v_pk_fma_f32 v[40:41], v[190:191], v[40:41], v[210:211]
	global_store_dwordx4 v158, v[38:41], s[30:31] nt
	s_nop 0
	global_load_dwordx4 v[38:41], v158, s[28:29] nt
	s_waitcnt vmcnt(62)
	v_pk_fma_f32 v[142:143], v[34:35], v[134:135], v[142:143] op_sel:[0,1,0]
	v_pk_fma_f32 v[144:145], v[36:37], v[134:135], v[144:145] op_sel:[0,1,0]
	v_pk_mul_f32 v[210:211], v[200:201], v[138:139] op_sel:[0,1]
	v_pk_fma_f32 v[34:35], v[184:185], v[34:35], v[210:211]
	v_pk_mul_f32 v[210:211], v[198:199], v[138:139] op_sel:[0,1]
	v_pk_fma_f32 v[36:37], v[190:191], v[36:37], v[210:211]
	global_store_dwordx4 v158, v[34:37], s[30:31] offset:1024 nt
	s_nop 0
	global_load_dwordx4 v[34:37], v158, s[28:29] offset:1024 nt
	s_waitcnt vmcnt(62)
	v_pk_fma_f32 v[142:143], v[30:31], v[136:137], v[142:143] op_sel_hi:[1,0,1]
	v_pk_fma_f32 v[144:145], v[32:33], v[136:137], v[144:145] op_sel_hi:[1,0,1]
	v_pk_mul_f32 v[210:211], v[200:201], v[140:141] op_sel_hi:[1,0]
	v_pk_fma_f32 v[30:31], v[184:185], v[30:31], v[210:211]
	v_pk_mul_f32 v[210:211], v[198:199], v[140:141] op_sel_hi:[1,0]
	v_pk_fma_f32 v[32:33], v[190:191], v[32:33], v[210:211]
	global_store_dwordx4 v158, v[30:33], s[30:31] offset:2048 nt
	s_nop 0
	global_load_dwordx4 v[30:33], v158, s[28:29] offset:2048 nt
	s_waitcnt vmcnt(62)
	v_pk_fma_f32 v[142:143], v[26:27], v[136:137], v[142:143] op_sel:[0,1,0]
	v_pk_fma_f32 v[144:145], v[28:29], v[136:137], v[144:145] op_sel:[0,1,0]
	v_pk_mul_f32 v[210:211], v[200:201], v[140:141] op_sel:[0,1]
	v_pk_fma_f32 v[26:27], v[184:185], v[26:27], v[210:211]
	v_pk_mul_f32 v[210:211], v[198:199], v[140:141] op_sel:[0,1]
	v_pk_fma_f32 v[28:29], v[190:191], v[28:29], v[210:211]
	global_store_dwordx4 v158, v[26:29], s[30:31] offset:3072 nt
	s_add_u32 s30, s30, 0x1000
	s_addc_u32 s31, s31, 0
	global_load_dwordx4 v[26:29], v158, s[28:29] offset:3072 nt
	s_add_u32 s28, s28, 0x1000
	s_addc_u32 s29, s29, 0
	ds_read_b128 v[134:137], v179 offset:640
	ds_read_b128 v[138:141], v179 offset:1664
	s_waitcnt lgkmcnt(2)
	s_waitcnt vmcnt(62)
; __device__ __forceinline__ void mlstm_decode_wave(const Params& P, unsigned char* wl, int sh) {
;     ...
;     for (int dk0 = 0; dk0 < 256; dk0 += 32) { f32x4 c[32];
; #pragma unroll
;         for (int i = 0; i < 32; ++i) c[i] = __builtin_nontemporal_load((const f32x4*)(C0 + (dk0 + i) * 256));
; #pragma unroll
;         for (int i = 0; i < 32; ++i) { const float qd = sq[dk0 + i], kd = sk[dk0 + i]; part += qd * c[i]; __builtin_nontemporal_store(wc * c[i] + kd * wv, (f32x4*)(C1 + (dk0 + i) * 256)); } }
	v_pk_fma_f32 v[142:143], v[22:23], v[202:203], v[142:143] op_sel_hi:[1,0,1]
	v_pk_fma_f32 v[144:145], v[24:25], v[202:203], v[144:145] op_sel_hi:[1,0,1]
	v_pk_mul_f32 v[210:211], v[200:201], v[206:207] op_sel_hi:[1,0]
	v_pk_fma_f32 v[22:23], v[184:185], v[22:23], v[210:211]
	v_pk_mul_f32 v[210:211], v[198:199], v[206:207] op_sel_hi:[1,0]
	v_pk_fma_f32 v[24:25], v[190:191], v[24:25], v[210:211]
	global_store_dwordx4 v158, v[22:25], s[30:31] nt
	s_nop 0
	global_load_dwordx4 v[22:25], v158, s[28:29] nt
	s_waitcnt vmcnt(62)
	v_pk_fma_f32 v[142:143], v[18:19], v[202:203], v[142:143] op_sel:[0,1,0]
	v_pk_fma_f32 v[144:145], v[20:21], v[202:203], v[144:145] op_sel:[0,1,0]
	v_pk_mul_f32 v[210:211], v[200:201], v[206:207] op_sel:[0,1]
	v_pk_fma_f32 v[18:19], v[184:185], v[18:19], v[210:211]
	v_pk_mul_f32 v[210:211], v[198:199], v[206:207] op_sel:[0,1]
	v_pk_fma_f32 v[20:21], v[190:191], v[20:21], v[210:211]
	global_store_dwordx4 v158, v[18:21], s[30:31] offset:1024 nt
	s_nop 0
	global_load_dwordx4 v[18:21], v158, s[28:29] offset:1024 nt
	s_waitcnt vmcnt(62)
	v_pk_fma_f32 v[142:143], v[14:15], v[204:205], v[142:143] op_sel_hi:[1,0,1]
	v_pk_fma_f32 v[144:145], v[16:17], v[204:205], v[144:145] op_sel_hi:[1,0,1]
	v_pk_mul_f32 v[210:211], v[200:201], v[208:209] op_sel_hi:[1,0]
	v_pk_fma_f32 v[14:15], v[184:185], v[14:15], v[210:211]
	v_pk_mul_f32 v[210:211], v[198:199], v[208:209] op_sel_hi:[1,0]
	v_pk_fma_f32 v[16:17], v[190:191], v[16:17], v[210:211]
	global_store_dwordx4 v158, v[14:17], s[30:31] offset:2048 nt
	s_nop 0
	global_load_dwordx4 v[14:17], v158, s[28:29] offset:2048 nt
	s_waitcnt vmcnt(62)
	v_pk_fma_f32 v[142:143], v[10:11], v[204:205], v[142:143] op_sel:[0,1,0]
	v_pk_fma_f32 v[144:145], v[12:13], v[204:205], v[144:145] op_sel:[0,1,0]
	v_pk_mul_f32 v[210:211], v[200:201], v[208:209] op_sel:[0,1]
	v_pk_fma_f32 v[10:11], v[184:185], v[10:11], v[210:211]
	v_pk_mul_f32 v[210:211], v[198:199], v[208:209] op_sel:[0,1]
	v_pk_fma_f32 v[12:13], v[190:191], v[12:13], v[210:211]
	global_store_dwordx4 v158, v[10:13], s[30:31] offset:3072 nt
	s_add_u32 s30, s30, 0x1000
	s_addc_u32 s31, s31, 0
	global_load_dwordx4 v[10:13], v158, s[28:29] offset:3072 nt
	s_add_u32 s28, s28, 0x1000
	s_addc_u32 s29, s29, 0
	ds_read_b128 v[202:205], v179 offset:656
	ds_read_b128 v[206:209], v179 offset:1680
	s_waitcnt lgkmcnt(2)
	s_waitcnt vmcnt(62)
	v_pk_fma_f32 v[142:143], v[232:233], v[134:135], v[142:143] op_sel_hi:[1,0,1]
	v_pk_fma_f32 v[144:145], v[234:235], v[134:135], v[144:145] op_sel_hi:[1,0,1]
	v_pk_mul_f32 v[210:211], v[200:201], v[138:139] op_sel_hi:[1,0]
	v_pk_fma_f32 v[232:233], v[184:185], v[232:233], v[210:211]
	v_pk_mul_f32 v[210:211], v[198:199], v[138:139] op_sel_hi:[1,0]
	v_pk_fma_f32 v[234:235], v[190:191], v[234:235], v[210:211]
	global_store_dwordx4 v158, v[232:235], s[30:31] nt
	s_nop 0
	global_load_dwordx4 v[232:235], v158, s[28:29] nt
	s_waitcnt vmcnt(62)
	v_pk_fma_f32 v[142:143], v[130:131], v[134:135], v[142:143] op_sel:[0,1,0]
	v_pk_fma_f32 v[144:145], v[132:133], v[134:135], v[144:145] op_sel:[0,1,0]
	v_pk_mul_f32 v[210:211], v[200:201], v[138:139] op_sel:[0,1]
	v_pk_fma_f32 v[130:131], v[184:185], v[130:131], v[210:211]
	v_pk_mul_f32 v[210:211], v[198:199], v[138:139] op_sel:[0,1]
	v_pk_fma_f32 v[132:133], v[190:191], v[132:133], v[210:211]
	global_store_dwordx4 v158, v[130:133], s[30:31] offset:1024 nt
	s_nop 0
	global_load_dwordx4 v[130:133], v158, s[28:29] offset:1024 nt
	s_waitcnt vmcnt(62)
	v_pk_fma_f32 v[142:143], v[126:127], v[136:137], v[142:143] op_sel_hi:[1,0,1]
	v_pk_fma_f32 v[144:145], v[128:129], v[136:137], v[144:145] op_sel_hi:[1,0,1]
	v_pk_mul_f32 v[210:211], v[200:201], v[140:141] op_sel_hi:[1,0]
	v_pk_fma_f32 v[126:127], v[184:185], v[126:127], v[210:211]
	v_pk_mul_f32 v[210:211], v[198:199], v[140:141] op_sel_hi:[1,0]
	v_pk_fma_f32 v[128:129], v[190:191], v[128:129], v[210:211]
	global_store_dwordx4 v158, v[126:129], s[30:31] offset:2048 nt
	s_nop 0
	global_load_dwordx4 v[126:129], v158, s[28:29] offset:2048 nt
	s_waitcnt vmcnt(62)
	v_pk_fma_f32 v[142:143], v[122:123], v[136:137], v[142:143] op_sel:[0,1,0]
	v_pk_fma_f32 v[144:145], v[124:125], v[136:137], v[144:145] op_sel:[0,1,0]
	v_pk_mul_f32 v[210:211], v[200:201], v[140:141] op_sel:[0,1]
	v_pk_fma_f32 v[122:123], v[184:185], v[122:123], v[210:211]
	v_pk_mul_f32 v[210:211], v[198:199], v[140:141] op_sel:[0,1]
	v_pk_fma_f32 v[124:125], v[190:191], v[124:125], v[210:211]
	global_store_dwordx4 v158, v[122:125], s[30:31] offset:3072 nt
	s_add_u32 s30, s30, 0x1000
	s_addc_u32 s31, s31, 0
	global_load_dwordx4 v[122:125], v158, s[28:29] offset:3072 nt
	s_add_u32 s28, s28, 0x1000
	s_addc_u32 s29, s29, 0
	ds_read_b128 v[134:137], v179 offset:672
	ds_read_b128 v[138:141], v179 offset:1696
	s_waitcnt lgkmcnt(2)
	s_waitcnt vmcnt(62)
	v_pk_fma_f32 v[142:143], v[118:119], v[202:203], v[142:143] op_sel_hi:[1,0,1]
	v_pk_fma_f32 v[144:145], v[120:121], v[202:203], v[144:145] op_sel_hi:[1,0,1]
	v_pk_mul_f32 v[210:211], v[200:201], v[206:207] op_sel_hi:[1,0]
	v_pk_fma_f32 v[118:119], v[184:185], v[118:119], v[210:211]
	v_pk_mul_f32 v[210:211], v[198:199], v[206:207] op_sel_hi:[1,0]
	v_pk_fma_f32 v[120:121], v[190:191], v[120:121], v[210:211]
	global_store_dwordx4 v158, v[118:121], s[30:31] nt
	s_nop 0
	global_load_dwordx4 v[118:121], v158, s[28:29] nt
	s_waitcnt vmcnt(62)
	v_pk_fma_f32 v[142:143], v[114:115], v[202:203], v[142:143] op_sel:[0,1,0]
	v_pk_fma_f32 v[144:145], v[116:117], v[202:203], v[144:145] op_sel:[0,1,0]
	v_pk_mul_f32 v[210:211], v[200:201], v[206:207] op_sel:[0,1]
	v_pk_fma_f32 v[114:115], v[184:185], v[114:115], v[210:211]
	v_pk_mul_f32 v[210:211], v[198:199], v[206:207] op_sel:[0,1]
	v_pk_fma_f32 v[116:117], v[190:191], v[116:117], v[210:211]
	global_store_dwordx4 v158, v[114:117], s[30:31] offset:1024 nt
	s_nop 0
	global_load_dwordx4 v[114:117], v158, s[28:29] offset:1024 nt
	s_waitcnt vmcnt(62)
; __device__ __forceinline__ void mlstm_decode_wave(const Params& P, unsigned char* wl, int sh) {
;     ...
;     for (int dk0 = 0; dk0 < 256; dk0 += 32) { f32x4 c[32];
; #pragma unroll
;         for (int i = 0; i < 32; ++i) c[i] = __builtin_nontemporal_load((const f32x4*)(C0 + (dk0 + i) * 256));
; #pragma unroll
;         for (int i = 0; i < 32; ++i) { const float qd = sq[dk0 + i], kd = sk[dk0 + i]; part += qd * c[i]; __builtin_nontemporal_store(wc * c[i] + kd * wv, (f32x4*)(C1 + (dk0 + i) * 256)); } }
	v_pk_fma_f32 v[142:143], v[110:111], v[204:205], v[142:143] op_sel_hi:[1,0,1]
	v_pk_fma_f32 v[144:145], v[112:113], v[204:205], v[144:145] op_sel_hi:[1,0,1]
	v_pk_mul_f32 v[210:211], v[200:201], v[208:209] op_sel_hi:[1,0]
	v_pk_fma_f32 v[110:111], v[184:185], v[110:111], v[210:211]
	v_pk_mul_f32 v[210:211], v[198:199], v[208:209] op_sel_hi:[1,0]
	v_pk_fma_f32 v[112:113], v[190:191], v[112:113], v[210:211]
	global_store_dwordx4 v158, v[110:113], s[30:31] offset:2048 nt
	s_nop 0
	global_load_dwordx4 v[110:113], v158, s[28:29] offset:2048 nt
	s_waitcnt vmcnt(62)
	v_pk_fma_f32 v[142:143], v[106:107], v[204:205], v[142:143] op_sel:[0,1,0]
	v_pk_fma_f32 v[144:145], v[108:109], v[204:205], v[144:145] op_sel:[0,1,0]
	v_pk_mul_f32 v[210:211], v[200:201], v[208:209] op_sel:[0,1]
	v_pk_fma_f32 v[106:107], v[184:185], v[106:107], v[210:211]
	v_pk_mul_f32 v[210:211], v[198:199], v[208:209] op_sel:[0,1]
	v_pk_fma_f32 v[108:109], v[190:191], v[108:109], v[210:211]
	global_store_dwordx4 v158, v[106:109], s[30:31] offset:3072 nt
	s_add_u32 s30, s30, 0x1000
	s_addc_u32 s31, s31, 0
	global_load_dwordx4 v[106:109], v158, s[28:29] offset:3072 nt
	s_add_u32 s28, s28, 0x1000
	s_addc_u32 s29, s29, 0
	ds_read_b128 v[202:205], v179 offset:688
	ds_read_b128 v[206:209], v179 offset:1712
	s_waitcnt lgkmcnt(2)
	s_waitcnt vmcnt(62)
	v_pk_fma_f32 v[142:143], v[102:103], v[134:135], v[142:143] op_sel_hi:[1,0,1]
	v_pk_fma_f32 v[144:145], v[104:105], v[134:135], v[144:145] op_sel_hi:[1,0,1]
	v_pk_mul_f32 v[210:211], v[200:201], v[138:139] op_sel_hi:[1,0]
	v_pk_fma_f32 v[102:103], v[184:185], v[102:103], v[210:211]
	v_pk_mul_f32 v[210:211], v[198:199], v[138:139] op_sel_hi:[1,0]
	v_pk_fma_f32 v[104:105], v[190:191], v[104:105], v[210:211]
	global_store_dwordx4 v158, v[102:105], s[30:31] nt
	s_nop 0
	global_load_dwordx4 v[102:105], v158, s[28:29] nt
	s_waitcnt vmcnt(62)
	v_pk_fma_f32 v[142:143], v[98:99], v[134:135], v[142:143] op_sel:[0,1,0]
	v_pk_fma_f32 v[144:145], v[100:101], v[134:135], v[144:145] op_sel:[0,1,0]
	v_pk_mul_f32 v[210:211], v[200:201], v[138:139] op_sel:[0,1]
	v_pk_fma_f32 v[98:99], v[184:185], v[98:99], v[210:211]
	v_pk_mul_f32 v[210:211], v[198:199], v[138:139] op_sel:[0,1]
	v_pk_fma_f32 v[100:101], v[190:191], v[100:101], v[210:211]
	global_store_dwordx4 v158, v[98:101], s[30:31] offset:1024 nt
	s_nop 0
	global_load_dwordx4 v[98:101], v158, s[28:29] offset:1024 nt
	s_waitcnt vmcnt(62)
	v_pk_fma_f32 v[142:143], v[94:95], v[136:137], v[142:143] op_sel_hi:[1,0,1]
	v_pk_fma_f32 v[144:145], v[96:97], v[136:137], v[144:145] op_sel_hi:[1,0,1]
	v_pk_mul_f32 v[210:211], v[200:201], v[140:141] op_sel_hi:[1,0]
	v_pk_fma_f32 v[94:95], v[184:185], v[94:95], v[210:211]
	v_pk_mul_f32 v[210:211], v[198:199], v[140:141] op_sel_hi:[1,0]
	v_pk_fma_f32 v[96:97], v[190:191], v[96:97], v[210:211]
	global_store_dwordx4 v158, v[94:97], s[30:31] offset:2048 nt
	s_nop 0
	global_load_dwordx4 v[94:97], v158, s[28:29] offset:2048 nt
	s_waitcnt vmcnt(62)
	v_pk_fma_f32 v[142:143], v[90:91], v[136:137], v[142:143] op_sel:[0,1,0]
	v_pk_fma_f32 v[144:145], v[92:93], v[136:137], v[144:145] op_sel:[0,1,0]
	v_pk_mul_f32 v[210:211], v[200:201], v[140:141] op_sel:[0,1]
	v_pk_fma_f32 v[90:91], v[184:185], v[90:91], v[210:211]
	v_pk_mul_f32 v[210:211], v[198:199], v[140:141] op_sel:[0,1]
	v_pk_fma_f32 v[92:93], v[190:191], v[92:93], v[210:211]
	global_store_dwordx4 v158, v[90:93], s[30:31] offset:3072 nt
	s_add_u32 s30, s30, 0x1000
	s_addc_u32 s31, s31, 0
	global_load_dwordx4 v[90:93], v158, s[28:29] offset:3072 nt
	s_add_u32 s28, s28, 0x1000
	s_addc_u32 s29, s29, 0
	ds_read_b128 v[134:137], v179 offset:704
	ds_read_b128 v[138:141], v179 offset:1728
	s_waitcnt lgkmcnt(2)
	s_waitcnt vmcnt(62)
	v_pk_fma_f32 v[142:143], v[86:87], v[202:203], v[142:143] op_sel_hi:[1,0,1]
	v_pk_fma_f32 v[144:145], v[88:89], v[202:203], v[144:145] op_sel_hi:[1,0,1]
	v_pk_mul_f32 v[210:211], v[200:201], v[206:207] op_sel_hi:[1,0]
	v_pk_fma_f32 v[86:87], v[184:185], v[86:87], v[210:211]
	v_pk_mul_f32 v[210:211], v[198:199], v[206:207] op_sel_hi:[1,0]
	v_pk_fma_f32 v[88:89], v[190:191], v[88:89], v[210:211]
	global_store_dwordx4 v158, v[86:89], s[30:31] nt
	s_nop 0
	global_load_dwordx4 v[86:89], v158, s[28:29] nt
	s_waitcnt vmcnt(62)
	v_pk_fma_f32 v[142:143], v[82:83], v[202:203], v[142:143] op_sel:[0,1,0]
	v_pk_fma_f32 v[144:145], v[84:85], v[202:203], v[144:145] op_sel:[0,1,0]
	v_pk_mul_f32 v[210:211], v[200:201], v[206:207] op_sel:[0,1]
	v_pk_fma_f32 v[82:83], v[184:185], v[82:83], v[210:211]
	v_pk_mul_f32 v[210:211], v[198:199], v[206:207] op_sel:[0,1]
	v_pk_fma_f32 v[84:85], v[190:191], v[84:85], v[210:211]
	global_store_dwordx4 v158, v[82:85], s[30:31] offset:1024 nt
	s_nop 0
	global_load_dwordx4 v[82:85], v158, s[28:29] offset:1024 nt
	s_waitcnt vmcnt(62)
	v_pk_fma_f32 v[142:143], v[78:79], v[204:205], v[142:143] op_sel_hi:[1,0,1]
	v_pk_fma_f32 v[144:145], v[80:81], v[204:205], v[144:145] op_sel_hi:[1,0,1]
	v_pk_mul_f32 v[210:211], v[200:201], v[208:209] op_sel_hi:[1,0]
	v_pk_fma_f32 v[78:79], v[184:185], v[78:79], v[210:211]
	v_pk_mul_f32 v[210:211], v[198:199], v[208:209] op_sel_hi:[1,0]
	v_pk_fma_f32 v[80:81], v[190:191], v[80:81], v[210:211]
	global_store_dwordx4 v158, v[78:81], s[30:31] offset:2048 nt
	s_nop 0
	global_load_dwordx4 v[78:81], v158, s[28:29] offset:2048 nt
	s_waitcnt vmcnt(62)
; __device__ __forceinline__ void mlstm_decode_wave(const Params& P, unsigned char* wl, int sh) {
;     ...
;     for (int dk0 = 0; dk0 < 256; dk0 += 32) { f32x4 c[32];
; #pragma unroll
;         for (int i = 0; i < 32; ++i) c[i] = __builtin_nontemporal_load((const f32x4*)(C0 + (dk0 + i) * 256));
; #pragma unroll
;         for (int i = 0; i < 32; ++i) { const float qd = sq[dk0 + i], kd = sk[dk0 + i]; part += qd * c[i]; __builtin_nontemporal_store(wc * c[i] + kd * wv, (f32x4*)(C1 + (dk0 + i) * 256)); } }
	v_pk_fma_f32 v[142:143], v[74:75], v[204:205], v[142:143] op_sel:[0,1,0]
	v_pk_fma_f32 v[144:145], v[76:77], v[204:205], v[144:145] op_sel:[0,1,0]
	v_pk_mul_f32 v[210:211], v[200:201], v[208:209] op_sel:[0,1]
	v_pk_fma_f32 v[74:75], v[184:185], v[74:75], v[210:211]
	v_pk_mul_f32 v[210:211], v[198:199], v[208:209] op_sel:[0,1]
	v_pk_fma_f32 v[76:77], v[190:191], v[76:77], v[210:211]
	global_store_dwordx4 v158, v[74:77], s[30:31] offset:3072 nt
	s_add_u32 s30, s30, 0x1000
	s_addc_u32 s31, s31, 0
	global_load_dwordx4 v[74:77], v158, s[28:29] offset:3072 nt
	s_add_u32 s28, s28, 0x1000
	s_addc_u32 s29, s29, 0
	ds_read_b128 v[202:205], v179 offset:720
	ds_read_b128 v[206:209], v179 offset:1744
	s_waitcnt lgkmcnt(2)
	s_waitcnt vmcnt(62)
	v_pk_fma_f32 v[142:143], v[70:71], v[134:135], v[142:143] op_sel_hi:[1,0,1]
	v_pk_fma_f32 v[144:145], v[72:73], v[134:135], v[144:145] op_sel_hi:[1,0,1]
	v_pk_mul_f32 v[210:211], v[200:201], v[138:139] op_sel_hi:[1,0]
	v_pk_fma_f32 v[70:71], v[184:185], v[70:71], v[210:211]
	v_pk_mul_f32 v[210:211], v[198:199], v[138:139] op_sel_hi:[1,0]
	v_pk_fma_f32 v[72:73], v[190:191], v[72:73], v[210:211]
	global_store_dwordx4 v158, v[70:73], s[30:31] nt
	s_nop 0
	global_load_dwordx4 v[70:73], v158, s[28:29] nt
	s_waitcnt vmcnt(62)
	v_pk_fma_f32 v[142:143], v[66:67], v[134:135], v[142:143] op_sel:[0,1,0]
	v_pk_fma_f32 v[144:145], v[68:69], v[134:135], v[144:145] op_sel:[0,1,0]
	v_pk_mul_f32 v[210:211], v[200:201], v[138:139] op_sel:[0,1]
	v_pk_fma_f32 v[66:67], v[184:185], v[66:67], v[210:211]
	v_pk_mul_f32 v[210:211], v[198:199], v[138:139] op_sel:[0,1]
	v_pk_fma_f32 v[68:69], v[190:191], v[68:69], v[210:211]
	global_store_dwordx4 v158, v[66:69], s[30:31] offset:1024 nt
	s_nop 0
	global_load_dwordx4 v[66:69], v158, s[28:29] offset:1024 nt
	s_waitcnt vmcnt(62)
	v_pk_fma_f32 v[142:143], v[62:63], v[136:137], v[142:143] op_sel_hi:[1,0,1]
	v_pk_fma_f32 v[144:145], v[64:65], v[136:137], v[144:145] op_sel_hi:[1,0,1]
	v_pk_mul_f32 v[210:211], v[200:201], v[140:141] op_sel_hi:[1,0]
	v_pk_fma_f32 v[62:63], v[184:185], v[62:63], v[210:211]
	v_pk_mul_f32 v[210:211], v[198:199], v[140:141] op_sel_hi:[1,0]
	v_pk_fma_f32 v[64:65], v[190:191], v[64:65], v[210:211]
	global_store_dwordx4 v158, v[62:65], s[30:31] offset:2048 nt
	s_nop 0
	global_load_dwordx4 v[62:65], v158, s[28:29] offset:2048 nt
	s_waitcnt vmcnt(62)
	v_pk_fma_f32 v[142:143], v[58:59], v[136:137], v[142:143] op_sel:[0,1,0]
	v_pk_fma_f32 v[144:145], v[60:61], v[136:137], v[144:145] op_sel:[0,1,0]
	v_pk_mul_f32 v[210:211], v[200:201], v[140:141] op_sel:[0,1]
	v_pk_fma_f32 v[58:59], v[184:185], v[58:59], v[210:211]
	v_pk_mul_f32 v[210:211], v[198:199], v[140:141] op_sel:[0,1]
	v_pk_fma_f32 v[60:61], v[190:191], v[60:61], v[210:211]
	global_store_dwordx4 v158, v[58:61], s[30:31] offset:3072 nt
	s_add_u32 s30, s30, 0x1000
	s_addc_u32 s31, s31, 0
	global_load_dwordx4 v[58:61], v158, s[28:29] offset:3072 nt
	s_add_u32 s28, s28, 0x1000
	s_addc_u32 s29, s29, 0
	ds_read_b128 v[134:137], v179 offset:736
	ds_read_b128 v[138:141], v179 offset:1760
	s_waitcnt lgkmcnt(2)
	s_waitcnt vmcnt(62)
	v_pk_fma_f32 v[142:143], v[54:55], v[202:203], v[142:143] op_sel_hi:[1,0,1]
	v_pk_fma_f32 v[144:145], v[56:57], v[202:203], v[144:145] op_sel_hi:[1,0,1]
	v_pk_mul_f32 v[210:211], v[200:201], v[206:207] op_sel_hi:[1,0]
	v_pk_fma_f32 v[54:55], v[184:185], v[54:55], v[210:211]
	v_pk_mul_f32 v[210:211], v[198:199], v[206:207] op_sel_hi:[1,0]
	v_pk_fma_f32 v[56:57], v[190:191], v[56:57], v[210:211]
	global_store_dwordx4 v158, v[54:57], s[30:31] nt
	s_nop 0
	global_load_dwordx4 v[54:57], v158, s[28:29] nt
	s_waitcnt vmcnt(62)
	v_pk_fma_f32 v[142:143], v[50:51], v[202:203], v[142:143] op_sel:[0,1,0]
	v_pk_fma_f32 v[144:145], v[52:53], v[202:203], v[144:145] op_sel:[0,1,0]
	v_pk_mul_f32 v[210:211], v[200:201], v[206:207] op_sel:[0,1]
	v_pk_fma_f32 v[50:51], v[184:185], v[50:51], v[210:211]
	v_pk_mul_f32 v[210:211], v[198:199], v[206:207] op_sel:[0,1]
	v_pk_fma_f32 v[52:53], v[190:191], v[52:53], v[210:211]
	global_store_dwordx4 v158, v[50:53], s[30:31] offset:1024 nt
	s_nop 0
	global_load_dwordx4 v[50:53], v158, s[28:29] offset:1024 nt
	s_waitcnt vmcnt(62)
	v_pk_fma_f32 v[142:143], v[46:47], v[204:205], v[142:143] op_sel_hi:[1,0,1]
	v_pk_fma_f32 v[144:145], v[48:49], v[204:205], v[144:145] op_sel_hi:[1,0,1]
	v_pk_mul_f32 v[210:211], v[200:201], v[208:209] op_sel_hi:[1,0]
	v_pk_fma_f32 v[46:47], v[184:185], v[46:47], v[210:211]
	v_pk_mul_f32 v[210:211], v[198:199], v[208:209] op_sel_hi:[1,0]
	v_pk_fma_f32 v[48:49], v[190:191], v[48:49], v[210:211]
	global_store_dwordx4 v158, v[46:49], s[30:31] offset:2048 nt
	s_nop 0
	global_load_dwordx4 v[46:49], v158, s[28:29] offset:2048 nt
	s_waitcnt vmcnt(62)
	v_pk_fma_f32 v[142:143], v[42:43], v[204:205], v[142:143] op_sel:[0,1,0]
	v_pk_fma_f32 v[144:145], v[44:45], v[204:205], v[144:145] op_sel:[0,1,0]
	v_pk_mul_f32 v[210:211], v[200:201], v[208:209] op_sel:[0,1]
	v_pk_fma_f32 v[42:43], v[184:185], v[42:43], v[210:211]
	v_pk_mul_f32 v[210:211], v[198:199], v[208:209] op_sel:[0,1]
	v_pk_fma_f32 v[44:45], v[190:191], v[44:45], v[210:211]
	global_store_dwordx4 v158, v[42:45], s[30:31] offset:3072 nt
	s_add_u32 s30, s30, 0x1000
	s_addc_u32 s31, s31, 0
	global_load_dwordx4 v[42:45], v158, s[28:29] offset:3072 nt
	s_add_u32 s28, s28, 0x1000
	s_addc_u32 s29, s29, 0
	ds_read_b128 v[202:205], v179 offset:752
	ds_read_b128 v[206:209], v179 offset:1776
	s_waitcnt lgkmcnt(2)
	s_waitcnt vmcnt(62)
; __device__ __forceinline__ void mlstm_decode_wave(const Params& P, unsigned char* wl, int sh) {
;     ...
;     for (int dk0 = 0; dk0 < 256; dk0 += 32) { f32x4 c[32];
; #pragma unroll
;         for (int i = 0; i < 32; ++i) c[i] = __builtin_nontemporal_load((const f32x4*)(C0 + (dk0 + i) * 256));
; #pragma unroll
;         for (int i = 0; i < 32; ++i) { const float qd = sq[dk0 + i], kd = sk[dk0 + i]; part += qd * c[i]; __builtin_nontemporal_store(wc * c[i] + kd * wv, (f32x4*)(C1 + (dk0 + i) * 256)); } }
	v_pk_fma_f32 v[142:143], v[38:39], v[134:135], v[142:143] op_sel_hi:[1,0,1]
	v_pk_fma_f32 v[144:145], v[40:41], v[134:135], v[144:145] op_sel_hi:[1,0,1]
	v_pk_mul_f32 v[210:211], v[200:201], v[138:139] op_sel_hi:[1,0]
	v_pk_fma_f32 v[38:39], v[184:185], v[38:39], v[210:211]
	v_pk_mul_f32 v[210:211], v[198:199], v[138:139] op_sel_hi:[1,0]
	v_pk_fma_f32 v[40:41], v[190:191], v[40:41], v[210:211]
	global_store_dwordx4 v158, v[38:41], s[30:31] nt
	s_nop 0
	global_load_dwordx4 v[38:41], v158, s[28:29] nt
	s_waitcnt vmcnt(62)
	v_pk_fma_f32 v[142:143], v[34:35], v[134:135], v[142:143] op_sel:[0,1,0]
	v_pk_fma_f32 v[144:145], v[36:37], v[134:135], v[144:145] op_sel:[0,1,0]
	v_pk_mul_f32 v[210:211], v[200:201], v[138:139] op_sel:[0,1]
	v_pk_fma_f32 v[34:35], v[184:185], v[34:35], v[210:211]
	v_pk_mul_f32 v[210:211], v[198:199], v[138:139] op_sel:[0,1]
	v_pk_fma_f32 v[36:37], v[190:191], v[36:37], v[210:211]
	global_store_dwordx4 v158, v[34:37], s[30:31] offset:1024 nt
	s_nop 0
	global_load_dwordx4 v[34:37], v158, s[28:29] offset:1024 nt
	s_waitcnt vmcnt(62)
	v_pk_fma_f32 v[142:143], v[30:31], v[136:137], v[142:143] op_sel_hi:[1,0,1]
	v_pk_fma_f32 v[144:145], v[32:33], v[136:137], v[144:145] op_sel_hi:[1,0,1]
	v_pk_mul_f32 v[210:211], v[200:201], v[140:141] op_sel_hi:[1,0]
	v_pk_fma_f32 v[30:31], v[184:185], v[30:31], v[210:211]
	v_pk_mul_f32 v[210:211], v[198:199], v[140:141] op_sel_hi:[1,0]
	v_pk_fma_f32 v[32:33], v[190:191], v[32:33], v[210:211]
	global_store_dwordx4 v158, v[30:33], s[30:31] offset:2048 nt
	s_nop 0
	global_load_dwordx4 v[30:33], v158, s[28:29] offset:2048 nt
	s_waitcnt vmcnt(62)
	v_pk_fma_f32 v[142:143], v[26:27], v[136:137], v[142:143] op_sel:[0,1,0]
	v_pk_fma_f32 v[144:145], v[28:29], v[136:137], v[144:145] op_sel:[0,1,0]
	v_pk_mul_f32 v[210:211], v[200:201], v[140:141] op_sel:[0,1]
	v_pk_fma_f32 v[26:27], v[184:185], v[26:27], v[210:211]
	v_pk_mul_f32 v[210:211], v[198:199], v[140:141] op_sel:[0,1]
	v_pk_fma_f32 v[28:29], v[190:191], v[28:29], v[210:211]
	global_store_dwordx4 v158, v[26:29], s[30:31] offset:3072 nt
	s_add_u32 s30, s30, 0x1000
	s_addc_u32 s31, s31, 0
	global_load_dwordx4 v[26:29], v158, s[28:29] offset:3072 nt
	s_add_u32 s28, s28, 0x1000
	s_addc_u32 s29, s29, 0
	ds_read_b128 v[134:137], v179 offset:768
	ds_read_b128 v[138:141], v179 offset:1792
	s_waitcnt lgkmcnt(2)
	s_waitcnt vmcnt(62)
	v_pk_fma_f32 v[142:143], v[22:23], v[202:203], v[142:143] op_sel_hi:[1,0,1]
	v_pk_fma_f32 v[144:145], v[24:25], v[202:203], v[144:145] op_sel_hi:[1,0,1]
	v_pk_mul_f32 v[210:211], v[200:201], v[206:207] op_sel_hi:[1,0]
	v_pk_fma_f32 v[22:23], v[184:185], v[22:23], v[210:211]
	v_pk_mul_f32 v[210:211], v[198:199], v[206:207] op_sel_hi:[1,0]
	v_pk_fma_f32 v[24:25], v[190:191], v[24:25], v[210:211]
	global_store_dwordx4 v158, v[22:25], s[30:31] nt
	s_nop 0
	global_load_dwordx4 v[22:25], v158, s[28:29] nt
	s_waitcnt vmcnt(62)
	v_pk_fma_f32 v[142:143], v[18:19], v[202:203], v[142:143] op_sel:[0,1,0]
	v_pk_fma_f32 v[144:145], v[20:21], v[202:203], v[144:145] op_sel:[0,1,0]
	v_pk_mul_f32 v[210:211], v[200:201], v[206:207] op_sel:[0,1]
	v_pk_fma_f32 v[18:19], v[184:185], v[18:19], v[210:211]
	v_pk_mul_f32 v[210:211], v[198:199], v[206:207] op_sel:[0,1]
	v_pk_fma_f32 v[20:21], v[190:191], v[20:21], v[210:211]
	global_store_dwordx4 v158, v[18:21], s[30:31] offset:1024 nt
	s_nop 0
	global_load_dwordx4 v[18:21], v158, s[28:29] offset:1024 nt
	s_waitcnt vmcnt(62)
	v_pk_fma_f32 v[142:143], v[14:15], v[204:205], v[142:143] op_sel_hi:[1,0,1]
	v_pk_fma_f32 v[144:145], v[16:17], v[204:205], v[144:145] op_sel_hi:[1,0,1]
	v_pk_mul_f32 v[210:211], v[200:201], v[208:209] op_sel_hi:[1,0]
	v_pk_fma_f32 v[14:15], v[184:185], v[14:15], v[210:211]
	v_pk_mul_f32 v[210:211], v[198:199], v[208:209] op_sel_hi:[1,0]
	v_pk_fma_f32 v[16:17], v[190:191], v[16:17], v[210:211]
	global_store_dwordx4 v158, v[14:17], s[30:31] offset:2048 nt
	s_nop 0
	global_load_dwordx4 v[14:17], v158, s[28:29] offset:2048 nt
	s_waitcnt vmcnt(62)
	v_pk_fma_f32 v[142:143], v[10:11], v[204:205], v[142:143] op_sel:[0,1,0]
	v_pk_fma_f32 v[144:145], v[12:13], v[204:205], v[144:145] op_sel:[0,1,0]
	v_pk_mul_f32 v[210:211], v[200:201], v[208:209] op_sel:[0,1]
	v_pk_fma_f32 v[10:11], v[184:185], v[10:11], v[210:211]
	v_pk_mul_f32 v[210:211], v[198:199], v[208:209] op_sel:[0,1]
	v_pk_fma_f32 v[12:13], v[190:191], v[12:13], v[210:211]
	global_store_dwordx4 v158, v[10:13], s[30:31] offset:3072 nt
	s_add_u32 s30, s30, 0x1000
	s_addc_u32 s31, s31, 0
	global_load_dwordx4 v[10:13], v158, s[28:29] offset:3072 nt
	s_add_u32 s28, s28, 0x1000
	s_addc_u32 s29, s29, 0
	ds_read_b128 v[202:205], v179 offset:784
	ds_read_b128 v[206:209], v179 offset:1808
	s_waitcnt lgkmcnt(2)
	s_waitcnt vmcnt(62)
	v_pk_fma_f32 v[142:143], v[232:233], v[134:135], v[142:143] op_sel_hi:[1,0,1]
	v_pk_fma_f32 v[144:145], v[234:235], v[134:135], v[144:145] op_sel_hi:[1,0,1]
	v_pk_mul_f32 v[210:211], v[200:201], v[138:139] op_sel_hi:[1,0]
	v_pk_fma_f32 v[232:233], v[184:185], v[232:233], v[210:211]
	v_pk_mul_f32 v[210:211], v[198:199], v[138:139] op_sel_hi:[1,0]
	v_pk_fma_f32 v[234:235], v[190:191], v[234:235], v[210:211]
	global_store_dwordx4 v158, v[232:235], s[30:31] nt
	s_nop 0
	global_load_dwordx4 v[232:235], v158, s[28:29] nt
	s_waitcnt vmcnt(62)
	v_pk_fma_f32 v[142:143], v[130:131], v[134:135], v[142:143] op_sel:[0,1,0]
	v_pk_fma_f32 v[144:145], v[132:133], v[134:135], v[144:145] op_sel:[0,1,0]
	v_pk_mul_f32 v[210:211], v[200:201], v[138:139] op_sel:[0,1]
	v_pk_fma_f32 v[130:131], v[184:185], v[130:131], v[210:211]
	v_pk_mul_f32 v[210:211], v[198:199], v[138:139] op_sel:[0,1]
	v_pk_fma_f32 v[132:133], v[190:191], v[132:133], v[210:211]
	global_store_dwordx4 v158, v[130:133], s[30:31] offset:1024 nt
	s_nop 0
	global_load_dwordx4 v[130:133], v158, s[28:29] offset:1024 nt
	s_waitcnt vmcnt(62)
; __device__ __forceinline__ void mlstm_decode_wave(const Params& P, unsigned char* wl, int sh) {
;     ...
;     for (int dk0 = 0; dk0 < 256; dk0 += 32) { f32x4 c[32];
; #pragma unroll
;         for (int i = 0; i < 32; ++i) c[i] = __builtin_nontemporal_load((const f32x4*)(C0 + (dk0 + i) * 256));
; #pragma unroll
;         for (int i = 0; i < 32; ++i) { const float qd = sq[dk0 + i], kd = sk[dk0 + i]; part += qd * c[i]; __builtin_nontemporal_store(wc * c[i] + kd * wv, (f32x4*)(C1 + (dk0 + i) * 256)); } }
	v_pk_fma_f32 v[142:143], v[126:127], v[136:137], v[142:143] op_sel_hi:[1,0,1]
	v_pk_fma_f32 v[144:145], v[128:129], v[136:137], v[144:145] op_sel_hi:[1,0,1]
	v_pk_mul_f32 v[210:211], v[200:201], v[140:141] op_sel_hi:[1,0]
	v_pk_fma_f32 v[126:127], v[184:185], v[126:127], v[210:211]
	v_pk_mul_f32 v[210:211], v[198:199], v[140:141] op_sel_hi:[1,0]
	v_pk_fma_f32 v[128:129], v[190:191], v[128:129], v[210:211]
	global_store_dwordx4 v158, v[126:129], s[30:31] offset:2048 nt
	s_nop 0
	global_load_dwordx4 v[126:129], v158, s[28:29] offset:2048 nt
	s_waitcnt vmcnt(62)
	v_pk_fma_f32 v[142:143], v[122:123], v[136:137], v[142:143] op_sel:[0,1,0]
	v_pk_fma_f32 v[144:145], v[124:125], v[136:137], v[144:145] op_sel:[0,1,0]
	v_pk_mul_f32 v[210:211], v[200:201], v[140:141] op_sel:[0,1]
	v_pk_fma_f32 v[122:123], v[184:185], v[122:123], v[210:211]
	v_pk_mul_f32 v[210:211], v[198:199], v[140:141] op_sel:[0,1]
	v_pk_fma_f32 v[124:125], v[190:191], v[124:125], v[210:211]
	global_store_dwordx4 v158, v[122:125], s[30:31] offset:3072 nt
	s_add_u32 s30, s30, 0x1000
	s_addc_u32 s31, s31, 0
	global_load_dwordx4 v[122:125], v158, s[28:29] offset:3072 nt
	s_add_u32 s28, s28, 0x1000
	s_addc_u32 s29, s29, 0
	ds_read_b128 v[134:137], v179 offset:800
	ds_read_b128 v[138:141], v179 offset:1824
	s_waitcnt lgkmcnt(2)
	s_waitcnt vmcnt(62)
	v_pk_fma_f32 v[142:143], v[118:119], v[202:203], v[142:143] op_sel_hi:[1,0,1]
	v_pk_fma_f32 v[144:145], v[120:121], v[202:203], v[144:145] op_sel_hi:[1,0,1]
	v_pk_mul_f32 v[210:211], v[200:201], v[206:207] op_sel_hi:[1,0]
	v_pk_fma_f32 v[118:119], v[184:185], v[118:119], v[210:211]
	v_pk_mul_f32 v[210:211], v[198:199], v[206:207] op_sel_hi:[1,0]
	v_pk_fma_f32 v[120:121], v[190:191], v[120:121], v[210:211]
	global_store_dwordx4 v158, v[118:121], s[30:31] nt
	s_nop 0
	global_load_dwordx4 v[118:121], v158, s[28:29] nt
	s_waitcnt vmcnt(62)
	v_pk_fma_f32 v[142:143], v[114:115], v[202:203], v[142:143] op_sel:[0,1,0]
	v_pk_fma_f32 v[144:145], v[116:117], v[202:203], v[144:145] op_sel:[0,1,0]
	v_pk_mul_f32 v[210:211], v[200:201], v[206:207] op_sel:[0,1]
	v_pk_fma_f32 v[114:115], v[184:185], v[114:115], v[210:211]
	v_pk_mul_f32 v[210:211], v[198:199], v[206:207] op_sel:[0,1]
	v_pk_fma_f32 v[116:117], v[190:191], v[116:117], v[210:211]
	global_store_dwordx4 v158, v[114:117], s[30:31] offset:1024 nt
	s_nop 0
	global_load_dwordx4 v[114:117], v158, s[28:29] offset:1024 nt
	s_waitcnt vmcnt(62)
	v_pk_fma_f32 v[142:143], v[110:111], v[204:205], v[142:143] op_sel_hi:[1,0,1]
	v_pk_fma_f32 v[144:145], v[112:113], v[204:205], v[144:145] op_sel_hi:[1,0,1]
	v_pk_mul_f32 v[210:211], v[200:201], v[208:209] op_sel_hi:[1,0]
	v_pk_fma_f32 v[110:111], v[184:185], v[110:111], v[210:211]
	v_pk_mul_f32 v[210:211], v[198:199], v[208:209] op_sel_hi:[1,0]
	v_pk_fma_f32 v[112:113], v[190:191], v[112:113], v[210:211]
	global_store_dwordx4 v158, v[110:113], s[30:31] offset:2048 nt
	s_nop 0
	global_load_dwordx4 v[110:113], v158, s[28:29] offset:2048 nt
	s_waitcnt vmcnt(62)
	v_pk_fma_f32 v[142:143], v[106:107], v[204:205], v[142:143] op_sel:[0,1,0]
	v_pk_fma_f32 v[144:145], v[108:109], v[204:205], v[144:145] op_sel:[0,1,0]
	v_pk_mul_f32 v[210:211], v[200:201], v[208:209] op_sel:[0,1]
	v_pk_fma_f32 v[106:107], v[184:185], v[106:107], v[210:211]
	v_pk_mul_f32 v[210:211], v[198:199], v[208:209] op_sel:[0,1]
	v_pk_fma_f32 v[108:109], v[190:191], v[108:109], v[210:211]
	global_store_dwordx4 v158, v[106:109], s[30:31] offset:3072 nt
	s_add_u32 s30, s30, 0x1000
	s_addc_u32 s31, s31, 0
	global_load_dwordx4 v[106:109], v158, s[28:29] offset:3072 nt
	s_add_u32 s28, s28, 0x1000
	s_addc_u32 s29, s29, 0
	ds_read_b128 v[202:205], v179 offset:816
	ds_read_b128 v[206:209], v179 offset:1840
	s_waitcnt lgkmcnt(2)
	s_waitcnt vmcnt(62)
	v_pk_fma_f32 v[142:143], v[102:103], v[134:135], v[142:143] op_sel_hi:[1,0,1]
	v_pk_fma_f32 v[144:145], v[104:105], v[134:135], v[144:145] op_sel_hi:[1,0,1]
	v_pk_mul_f32 v[210:211], v[200:201], v[138:139] op_sel_hi:[1,0]
	v_pk_fma_f32 v[102:103], v[184:185], v[102:103], v[210:211]
	v_pk_mul_f32 v[210:211], v[198:199], v[138:139] op_sel_hi:[1,0]
	v_pk_fma_f32 v[104:105], v[190:191], v[104:105], v[210:211]
	global_store_dwordx4 v158, v[102:105], s[30:31] nt
	s_nop 0
	global_load_dwordx4 v[102:105], v158, s[28:29] nt
	s_waitcnt vmcnt(62)
	v_pk_fma_f32 v[142:143], v[98:99], v[134:135], v[142:143] op_sel:[0,1,0]
	v_pk_fma_f32 v[144:145], v[100:101], v[134:135], v[144:145] op_sel:[0,1,0]
	v_pk_mul_f32 v[210:211], v[200:201], v[138:139] op_sel:[0,1]
	v_pk_fma_f32 v[98:99], v[184:185], v[98:99], v[210:211]
	v_pk_mul_f32 v[210:211], v[198:199], v[138:139] op_sel:[0,1]
	v_pk_fma_f32 v[100:101], v[190:191], v[100:101], v[210:211]
	global_store_dwordx4 v158, v[98:101], s[30:31] offset:1024 nt
	s_nop 0
	global_load_dwordx4 v[98:101], v158, s[28:29] offset:1024 nt
	s_waitcnt vmcnt(62)
	v_pk_fma_f32 v[142:143], v[94:95], v[136:137], v[142:143] op_sel_hi:[1,0,1]
	v_pk_fma_f32 v[144:145], v[96:97], v[136:137], v[144:145] op_sel_hi:[1,0,1]
	v_pk_mul_f32 v[210:211], v[200:201], v[140:141] op_sel_hi:[1,0]
	v_pk_fma_f32 v[94:95], v[184:185], v[94:95], v[210:211]
	v_pk_mul_f32 v[210:211], v[198:199], v[140:141] op_sel_hi:[1,0]
	v_pk_fma_f32 v[96:97], v[190:191], v[96:97], v[210:211]
	global_store_dwordx4 v158, v[94:97], s[30:31] offset:2048 nt
	s_nop 0
	global_load_dwordx4 v[94:97], v158, s[28:29] offset:2048 nt
	s_waitcnt vmcnt(62)
; __device__ __forceinline__ void mlstm_decode_wave(const Params& P, unsigned char* wl, int sh) {
;     ...
;     for (int dk0 = 0; dk0 < 256; dk0 += 32) { f32x4 c[32];
; #pragma unroll
;         for (int i = 0; i < 32; ++i) c[i] = __builtin_nontemporal_load((const f32x4*)(C0 + (dk0 + i) * 256));
; #pragma unroll
;         for (int i = 0; i < 32; ++i) { const float qd = sq[dk0 + i], kd = sk[dk0 + i]; part += qd * c[i]; __builtin_nontemporal_store(wc * c[i] + kd * wv, (f32x4*)(C1 + (dk0 + i) * 256)); } }
	v_pk_fma_f32 v[142:143], v[90:91], v[136:137], v[142:143] op_sel:[0,1,0]
	v_pk_fma_f32 v[144:145], v[92:93], v[136:137], v[144:145] op_sel:[0,1,0]
	v_pk_mul_f32 v[210:211], v[200:201], v[140:141] op_sel:[0,1]
	v_pk_fma_f32 v[90:91], v[184:185], v[90:91], v[210:211]
	v_pk_mul_f32 v[210:211], v[198:199], v[140:141] op_sel:[0,1]
	v_pk_fma_f32 v[92:93], v[190:191], v[92:93], v[210:211]
	global_store_dwordx4 v158, v[90:93], s[30:31] offset:3072 nt
	s_add_u32 s30, s30, 0x1000
	s_addc_u32 s31, s31, 0
	global_load_dwordx4 v[90:93], v158, s[28:29] offset:3072 nt
	s_add_u32 s28, s28, 0x1000
	s_addc_u32 s29, s29, 0
	ds_read_b128 v[134:137], v179 offset:832
	ds_read_b128 v[138:141], v179 offset:1856
	s_waitcnt lgkmcnt(2)
	s_waitcnt vmcnt(62)
	v_pk_fma_f32 v[142:143], v[86:87], v[202:203], v[142:143] op_sel_hi:[1,0,1]
	v_pk_fma_f32 v[144:145], v[88:89], v[202:203], v[144:145] op_sel_hi:[1,0,1]
	v_pk_mul_f32 v[210:211], v[200:201], v[206:207] op_sel_hi:[1,0]
	v_pk_fma_f32 v[86:87], v[184:185], v[86:87], v[210:211]
	v_pk_mul_f32 v[210:211], v[198:199], v[206:207] op_sel_hi:[1,0]
	v_pk_fma_f32 v[88:89], v[190:191], v[88:89], v[210:211]
	global_store_dwordx4 v158, v[86:89], s[30:31] nt
	s_nop 0
	global_load_dwordx4 v[86:89], v158, s[28:29] nt
	s_waitcnt vmcnt(62)
	v_pk_fma_f32 v[142:143], v[82:83], v[202:203], v[142:143] op_sel:[0,1,0]
	v_pk_fma_f32 v[144:145], v[84:85], v[202:203], v[144:145] op_sel:[0,1,0]
	v_pk_mul_f32 v[210:211], v[200:201], v[206:207] op_sel:[0,1]
	v_pk_fma_f32 v[82:83], v[184:185], v[82:83], v[210:211]
	v_pk_mul_f32 v[210:211], v[198:199], v[206:207] op_sel:[0,1]
	v_pk_fma_f32 v[84:85], v[190:191], v[84:85], v[210:211]
	global_store_dwordx4 v158, v[82:85], s[30:31] offset:1024 nt
	s_nop 0
	global_load_dwordx4 v[82:85], v158, s[28:29] offset:1024 nt
	s_waitcnt vmcnt(62)
	v_pk_fma_f32 v[142:143], v[78:79], v[204:205], v[142:143] op_sel_hi:[1,0,1]
	v_pk_fma_f32 v[144:145], v[80:81], v[204:205], v[144:145] op_sel_hi:[1,0,1]
	v_pk_mul_f32 v[210:211], v[200:201], v[208:209] op_sel_hi:[1,0]
	v_pk_fma_f32 v[78:79], v[184:185], v[78:79], v[210:211]
	v_pk_mul_f32 v[210:211], v[198:199], v[208:209] op_sel_hi:[1,0]
	v_pk_fma_f32 v[80:81], v[190:191], v[80:81], v[210:211]
	global_store_dwordx4 v158, v[78:81], s[30:31] offset:2048 nt
	s_nop 0
	global_load_dwordx4 v[78:81], v158, s[28:29] offset:2048 nt
	s_waitcnt vmcnt(62)
	v_pk_fma_f32 v[142:143], v[74:75], v[204:205], v[142:143] op_sel:[0,1,0]
	v_pk_fma_f32 v[144:145], v[76:77], v[204:205], v[144:145] op_sel:[0,1,0]
	v_pk_mul_f32 v[210:211], v[200:201], v[208:209] op_sel:[0,1]
	v_pk_fma_f32 v[74:75], v[184:185], v[74:75], v[210:211]
	v_pk_mul_f32 v[210:211], v[198:199], v[208:209] op_sel:[0,1]
	v_pk_fma_f32 v[76:77], v[190:191], v[76:77], v[210:211]
	global_store_dwordx4 v158, v[74:77], s[30:31] offset:3072 nt
	s_add_u32 s30, s30, 0x1000
	s_addc_u32 s31, s31, 0
	global_load_dwordx4 v[74:77], v158, s[28:29] offset:3072 nt
	s_add_u32 s28, s28, 0x1000
	s_addc_u32 s29, s29, 0
	ds_read_b128 v[202:205], v179 offset:848
	ds_read_b128 v[206:209], v179 offset:1872
	s_waitcnt lgkmcnt(2)
	s_waitcnt vmcnt(62)
	v_pk_fma_f32 v[142:143], v[70:71], v[134:135], v[142:143] op_sel_hi:[1,0,1]
	v_pk_fma_f32 v[144:145], v[72:73], v[134:135], v[144:145] op_sel_hi:[1,0,1]
	v_pk_mul_f32 v[210:211], v[200:201], v[138:139] op_sel_hi:[1,0]
	v_pk_fma_f32 v[70:71], v[184:185], v[70:71], v[210:211]
	v_pk_mul_f32 v[210:211], v[198:199], v[138:139] op_sel_hi:[1,0]
	v_pk_fma_f32 v[72:73], v[190:191], v[72:73], v[210:211]
	global_store_dwordx4 v158, v[70:73], s[30:31] nt
	s_nop 0
	global_load_dwordx4 v[70:73], v158, s[28:29] nt
	s_waitcnt vmcnt(62)
	v_pk_fma_f32 v[142:143], v[66:67], v[134:135], v[142:143] op_sel:[0,1,0]
	v_pk_fma_f32 v[144:145], v[68:69], v[134:135], v[144:145] op_sel:[0,1,0]
	v_pk_mul_f32 v[210:211], v[200:201], v[138:139] op_sel:[0,1]
	v_pk_fma_f32 v[66:67], v[184:185], v[66:67], v[210:211]
	v_pk_mul_f32 v[210:211], v[198:199], v[138:139] op_sel:[0,1]
	v_pk_fma_f32 v[68:69], v[190:191], v[68:69], v[210:211]
	global_store_dwordx4 v158, v[66:69], s[30:31] offset:1024 nt
	s_nop 0
	global_load_dwordx4 v[66:69], v158, s[28:29] offset:1024 nt
	s_waitcnt vmcnt(62)
	v_pk_fma_f32 v[142:143], v[62:63], v[136:137], v[142:143] op_sel_hi:[1,0,1]
	v_pk_fma_f32 v[144:145], v[64:65], v[136:137], v[144:145] op_sel_hi:[1,0,1]
	v_pk_mul_f32 v[210:211], v[200:201], v[140:141] op_sel_hi:[1,0]
	v_pk_fma_f32 v[62:63], v[184:185], v[62:63], v[210:211]
	v_pk_mul_f32 v[210:211], v[198:199], v[140:141] op_sel_hi:[1,0]
	v_pk_fma_f32 v[64:65], v[190:191], v[64:65], v[210:211]
	global_store_dwordx4 v158, v[62:65], s[30:31] offset:2048 nt
	s_nop 0
	global_load_dwordx4 v[62:65], v158, s[28:29] offset:2048 nt
	s_waitcnt vmcnt(62)
	v_pk_fma_f32 v[142:143], v[58:59], v[136:137], v[142:143] op_sel:[0,1,0]
	v_pk_fma_f32 v[144:145], v[60:61], v[136:137], v[144:145] op_sel:[0,1,0]
	v_pk_mul_f32 v[210:211], v[200:201], v[140:141] op_sel:[0,1]
	v_pk_fma_f32 v[58:59], v[184:185], v[58:59], v[210:211]
	v_pk_mul_f32 v[210:211], v[198:199], v[140:141] op_sel:[0,1]
	v_pk_fma_f32 v[60:61], v[190:191], v[60:61], v[210:211]
	global_store_dwordx4 v158, v[58:61], s[30:31] offset:3072 nt
	s_add_u32 s30, s30, 0x1000
	s_addc_u32 s31, s31, 0
	global_load_dwordx4 v[58:61], v158, s[28:29] offset:3072 nt
	s_add_u32 s28, s28, 0x1000
	s_addc_u32 s29, s29, 0
	ds_read_b128 v[134:137], v179 offset:864
	ds_read_b128 v[138:141], v179 offset:1888
	s_waitcnt lgkmcnt(2)
	s_waitcnt vmcnt(62)
; __device__ __forceinline__ void mlstm_decode_wave(const Params& P, unsigned char* wl, int sh) {
;     ...
;     for (int dk0 = 0; dk0 < 256; dk0 += 32) { f32x4 c[32];
; #pragma unroll
;         for (int i = 0; i < 32; ++i) c[i] = __builtin_nontemporal_load((const f32x4*)(C0 + (dk0 + i) * 256));
; #pragma unroll
;         for (int i = 0; i < 32; ++i) { const float qd = sq[dk0 + i], kd = sk[dk0 + i]; part += qd * c[i]; __builtin_nontemporal_store(wc * c[i] + kd * wv, (f32x4*)(C1 + (dk0 + i) * 256)); } }
	v_pk_fma_f32 v[142:143], v[54:55], v[202:203], v[142:143] op_sel_hi:[1,0,1]
	v_pk_fma_f32 v[144:145], v[56:57], v[202:203], v[144:145] op_sel_hi:[1,0,1]
	v_pk_mul_f32 v[210:211], v[200:201], v[206:207] op_sel_hi:[1,0]
	v_pk_fma_f32 v[54:55], v[184:185], v[54:55], v[210:211]
	v_pk_mul_f32 v[210:211], v[198:199], v[206:207] op_sel_hi:[1,0]
	v_pk_fma_f32 v[56:57], v[190:191], v[56:57], v[210:211]
	global_store_dwordx4 v158, v[54:57], s[30:31] nt
	s_nop 0
	global_load_dwordx4 v[54:57], v158, s[28:29] nt
	s_waitcnt vmcnt(62)
	v_pk_fma_f32 v[142:143], v[50:51], v[202:203], v[142:143] op_sel:[0,1,0]
	v_pk_fma_f32 v[144:145], v[52:53], v[202:203], v[144:145] op_sel:[0,1,0]
	v_pk_mul_f32 v[210:211], v[200:201], v[206:207] op_sel:[0,1]
	v_pk_fma_f32 v[50:51], v[184:185], v[50:51], v[210:211]
	v_pk_mul_f32 v[210:211], v[198:199], v[206:207] op_sel:[0,1]
	v_pk_fma_f32 v[52:53], v[190:191], v[52:53], v[210:211]
	global_store_dwordx4 v158, v[50:53], s[30:31] offset:1024 nt
	s_nop 0
	global_load_dwordx4 v[50:53], v158, s[28:29] offset:1024 nt
	s_waitcnt vmcnt(62)
	v_pk_fma_f32 v[142:143], v[46:47], v[204:205], v[142:143] op_sel_hi:[1,0,1]
	v_pk_fma_f32 v[144:145], v[48:49], v[204:205], v[144:145] op_sel_hi:[1,0,1]
	v_pk_mul_f32 v[210:211], v[200:201], v[208:209] op_sel_hi:[1,0]
	v_pk_fma_f32 v[46:47], v[184:185], v[46:47], v[210:211]
	v_pk_mul_f32 v[210:211], v[198:199], v[208:209] op_sel_hi:[1,0]
	v_pk_fma_f32 v[48:49], v[190:191], v[48:49], v[210:211]
	global_store_dwordx4 v158, v[46:49], s[30:31] offset:2048 nt
	s_nop 0
	global_load_dwordx4 v[46:49], v158, s[28:29] offset:2048 nt
	s_waitcnt vmcnt(62)
	v_pk_fma_f32 v[142:143], v[42:43], v[204:205], v[142:143] op_sel:[0,1,0]
	v_pk_fma_f32 v[144:145], v[44:45], v[204:205], v[144:145] op_sel:[0,1,0]
	v_pk_mul_f32 v[210:211], v[200:201], v[208:209] op_sel:[0,1]
	v_pk_fma_f32 v[42:43], v[184:185], v[42:43], v[210:211]
	v_pk_mul_f32 v[210:211], v[198:199], v[208:209] op_sel:[0,1]
	v_pk_fma_f32 v[44:45], v[190:191], v[44:45], v[210:211]
	global_store_dwordx4 v158, v[42:45], s[30:31] offset:3072 nt
	s_add_u32 s30, s30, 0x1000
	s_addc_u32 s31, s31, 0
	global_load_dwordx4 v[42:45], v158, s[28:29] offset:3072 nt
	s_add_u32 s28, s28, 0x1000
	s_addc_u32 s29, s29, 0
	ds_read_b128 v[202:205], v179 offset:880
	ds_read_b128 v[206:209], v179 offset:1904
	s_waitcnt lgkmcnt(2)
	s_waitcnt vmcnt(62)
	v_pk_fma_f32 v[142:143], v[38:39], v[134:135], v[142:143] op_sel_hi:[1,0,1]
	v_pk_fma_f32 v[144:145], v[40:41], v[134:135], v[144:145] op_sel_hi:[1,0,1]
	v_pk_mul_f32 v[210:211], v[200:201], v[138:139] op_sel_hi:[1,0]
	v_pk_fma_f32 v[38:39], v[184:185], v[38:39], v[210:211]
	v_pk_mul_f32 v[210:211], v[198:199], v[138:139] op_sel_hi:[1,0]
	v_pk_fma_f32 v[40:41], v[190:191], v[40:41], v[210:211]
	global_store_dwordx4 v158, v[38:41], s[30:31] nt
	s_nop 0
	global_load_dwordx4 v[38:41], v158, s[28:29] nt
	s_waitcnt vmcnt(62)
	v_pk_fma_f32 v[142:143], v[34:35], v[134:135], v[142:143] op_sel:[0,1,0]
	v_pk_fma_f32 v[144:145], v[36:37], v[134:135], v[144:145] op_sel:[0,1,0]
	v_pk_mul_f32 v[210:211], v[200:201], v[138:139] op_sel:[0,1]
	v_pk_fma_f32 v[34:35], v[184:185], v[34:35], v[210:211]
	v_pk_mul_f32 v[210:211], v[198:199], v[138:139] op_sel:[0,1]
	v_pk_fma_f32 v[36:37], v[190:191], v[36:37], v[210:211]
	global_store_dwordx4 v158, v[34:37], s[30:31] offset:1024 nt
	s_nop 0
	global_load_dwordx4 v[34:37], v158, s[28:29] offset:1024 nt
	s_waitcnt vmcnt(62)
	v_pk_fma_f32 v[142:143], v[30:31], v[136:137], v[142:143] op_sel_hi:[1,0,1]
	v_pk_fma_f32 v[144:145], v[32:33], v[136:137], v[144:145] op_sel_hi:[1,0,1]
	v_pk_mul_f32 v[210:211], v[200:201], v[140:141] op_sel_hi:[1,0]
	v_pk_fma_f32 v[30:31], v[184:185], v[30:31], v[210:211]
	v_pk_mul_f32 v[210:211], v[198:199], v[140:141] op_sel_hi:[1,0]
	v_pk_fma_f32 v[32:33], v[190:191], v[32:33], v[210:211]
	global_store_dwordx4 v158, v[30:33], s[30:31] offset:2048 nt
	s_nop 0
	global_load_dwordx4 v[30:33], v158, s[28:29] offset:2048 nt
	s_waitcnt vmcnt(62)
	v_pk_fma_f32 v[142:143], v[26:27], v[136:137], v[142:143] op_sel:[0,1,0]
	v_pk_fma_f32 v[144:145], v[28:29], v[136:137], v[144:145] op_sel:[0,1,0]
	v_pk_mul_f32 v[210:211], v[200:201], v[140:141] op_sel:[0,1]
	v_pk_fma_f32 v[26:27], v[184:185], v[26:27], v[210:211]
	v_pk_mul_f32 v[210:211], v[198:199], v[140:141] op_sel:[0,1]
	v_pk_fma_f32 v[28:29], v[190:191], v[28:29], v[210:211]
	global_store_dwordx4 v158, v[26:29], s[30:31] offset:3072 nt
	s_add_u32 s30, s30, 0x1000
	s_addc_u32 s31, s31, 0
	global_load_dwordx4 v[26:29], v158, s[28:29] offset:3072 nt
	s_add_u32 s28, s28, 0x1000
	s_addc_u32 s29, s29, 0
	ds_read_b128 v[134:137], v179 offset:896
	ds_read_b128 v[138:141], v179 offset:1920
	s_waitcnt lgkmcnt(2)
	s_waitcnt vmcnt(62)
	v_pk_fma_f32 v[142:143], v[22:23], v[202:203], v[142:143] op_sel_hi:[1,0,1]
	v_pk_fma_f32 v[144:145], v[24:25], v[202:203], v[144:145] op_sel_hi:[1,0,1]
	v_pk_mul_f32 v[210:211], v[200:201], v[206:207] op_sel_hi:[1,0]
	v_pk_fma_f32 v[22:23], v[184:185], v[22:23], v[210:211]
	v_pk_mul_f32 v[210:211], v[198:199], v[206:207] op_sel_hi:[1,0]
	v_pk_fma_f32 v[24:25], v[190:191], v[24:25], v[210:211]
	global_store_dwordx4 v158, v[22:25], s[30:31] nt
	s_nop 0
	global_load_dwordx4 v[22:25], v158, s[28:29] nt
	s_waitcnt vmcnt(62)
	v_pk_fma_f32 v[142:143], v[18:19], v[202:203], v[142:143] op_sel:[0,1,0]
	v_pk_fma_f32 v[144:145], v[20:21], v[202:203], v[144:145] op_sel:[0,1,0]
	v_pk_mul_f32 v[210:211], v[200:201], v[206:207] op_sel:[0,1]
	v_pk_fma_f32 v[18:19], v[184:185], v[18:19], v[210:211]
	v_pk_mul_f32 v[210:211], v[198:199], v[206:207] op_sel:[0,1]
	v_pk_fma_f32 v[20:21], v[190:191], v[20:21], v[210:211]
	global_store_dwordx4 v158, v[18:21], s[30:31] offset:1024 nt
	s_nop 0
	global_load_dwordx4 v[18:21], v158, s[28:29] offset:1024 nt
	s_waitcnt vmcnt(62)
; __device__ __forceinline__ void mlstm_decode_wave(const Params& P, unsigned char* wl, int sh) {
;     ...
;     for (int dk0 = 0; dk0 < 256; dk0 += 32) { f32x4 c[32];
; #pragma unroll
;         for (int i = 0; i < 32; ++i) c[i] = __builtin_nontemporal_load((const f32x4*)(C0 + (dk0 + i) * 256));
; #pragma unroll
;         for (int i = 0; i < 32; ++i) { const float qd = sq[dk0 + i], kd = sk[dk0 + i]; part += qd * c[i]; __builtin_nontemporal_store(wc * c[i] + kd * wv, (f32x4*)(C1 + (dk0 + i) * 256)); } }
	v_pk_fma_f32 v[142:143], v[14:15], v[204:205], v[142:143] op_sel_hi:[1,0,1]
	v_pk_fma_f32 v[144:145], v[16:17], v[204:205], v[144:145] op_sel_hi:[1,0,1]
	v_pk_mul_f32 v[210:211], v[200:201], v[208:209] op_sel_hi:[1,0]
	v_pk_fma_f32 v[14:15], v[184:185], v[14:15], v[210:211]
	v_pk_mul_f32 v[210:211], v[198:199], v[208:209] op_sel_hi:[1,0]
	v_pk_fma_f32 v[16:17], v[190:191], v[16:17], v[210:211]
	global_store_dwordx4 v158, v[14:17], s[30:31] offset:2048 nt
	s_nop 0
	global_load_dwordx4 v[14:17], v158, s[28:29] offset:2048 nt
	s_waitcnt vmcnt(62)
	v_pk_fma_f32 v[142:143], v[10:11], v[204:205], v[142:143] op_sel:[0,1,0]
	v_pk_fma_f32 v[144:145], v[12:13], v[204:205], v[144:145] op_sel:[0,1,0]
	v_pk_mul_f32 v[210:211], v[200:201], v[208:209] op_sel:[0,1]
	v_pk_fma_f32 v[10:11], v[184:185], v[10:11], v[210:211]
	v_pk_mul_f32 v[210:211], v[198:199], v[208:209] op_sel:[0,1]
	v_pk_fma_f32 v[12:13], v[190:191], v[12:13], v[210:211]
	global_store_dwordx4 v158, v[10:13], s[30:31] offset:3072 nt
	s_add_u32 s30, s30, 0x1000
	s_addc_u32 s31, s31, 0
	global_load_dwordx4 v[10:13], v158, s[28:29] offset:3072 nt
	s_add_u32 s28, s28, 0x1000
	s_addc_u32 s29, s29, 0
	ds_read_b128 v[202:205], v179 offset:912
	ds_read_b128 v[206:209], v179 offset:1936
	s_waitcnt lgkmcnt(2)
	s_waitcnt vmcnt(62)
	v_pk_fma_f32 v[142:143], v[232:233], v[134:135], v[142:143] op_sel_hi:[1,0,1]
	v_pk_fma_f32 v[144:145], v[234:235], v[134:135], v[144:145] op_sel_hi:[1,0,1]
	v_pk_mul_f32 v[210:211], v[200:201], v[138:139] op_sel_hi:[1,0]
	v_pk_fma_f32 v[232:233], v[184:185], v[232:233], v[210:211]
	v_pk_mul_f32 v[210:211], v[198:199], v[138:139] op_sel_hi:[1,0]
	v_pk_fma_f32 v[234:235], v[190:191], v[234:235], v[210:211]
	global_store_dwordx4 v158, v[232:235], s[30:31] nt
	s_nop 0
	s_waitcnt vmcnt(61)
	v_pk_fma_f32 v[142:143], v[130:131], v[134:135], v[142:143] op_sel:[0,1,0]
	v_pk_fma_f32 v[144:145], v[132:133], v[134:135], v[144:145] op_sel:[0,1,0]
	v_pk_mul_f32 v[210:211], v[200:201], v[138:139] op_sel:[0,1]
	v_pk_fma_f32 v[130:131], v[184:185], v[130:131], v[210:211]
	v_pk_mul_f32 v[210:211], v[198:199], v[138:139] op_sel:[0,1]
	v_pk_fma_f32 v[132:133], v[190:191], v[132:133], v[210:211]
	global_store_dwordx4 v158, v[130:133], s[30:31] offset:1024 nt
	s_nop 0
	s_waitcnt vmcnt(60)
	v_pk_fma_f32 v[142:143], v[126:127], v[136:137], v[142:143] op_sel_hi:[1,0,1]
	v_pk_fma_f32 v[144:145], v[128:129], v[136:137], v[144:145] op_sel_hi:[1,0,1]
	v_pk_mul_f32 v[210:211], v[200:201], v[140:141] op_sel_hi:[1,0]
	v_pk_fma_f32 v[126:127], v[184:185], v[126:127], v[210:211]
	v_pk_mul_f32 v[210:211], v[198:199], v[140:141] op_sel_hi:[1,0]
	v_pk_fma_f32 v[128:129], v[190:191], v[128:129], v[210:211]
	global_store_dwordx4 v158, v[126:129], s[30:31] offset:2048 nt
	s_nop 0
	s_waitcnt vmcnt(59)
	v_pk_fma_f32 v[142:143], v[122:123], v[136:137], v[142:143] op_sel:[0,1,0]
	v_pk_fma_f32 v[144:145], v[124:125], v[136:137], v[144:145] op_sel:[0,1,0]
	v_pk_mul_f32 v[210:211], v[200:201], v[140:141] op_sel:[0,1]
	v_pk_fma_f32 v[122:123], v[184:185], v[122:123], v[210:211]
	v_pk_mul_f32 v[210:211], v[198:199], v[140:141] op_sel:[0,1]
	v_pk_fma_f32 v[124:125], v[190:191], v[124:125], v[210:211]
	global_store_dwordx4 v158, v[122:125], s[30:31] offset:3072 nt
	s_add_u32 s30, s30, 0x1000
	s_addc_u32 s31, s31, 0
	ds_read_b128 v[134:137], v179 offset:928
	ds_read_b128 v[138:141], v179 offset:1952
	s_waitcnt lgkmcnt(2)
	s_waitcnt vmcnt(58)
	v_pk_fma_f32 v[142:143], v[118:119], v[202:203], v[142:143] op_sel_hi:[1,0,1]
	v_pk_fma_f32 v[144:145], v[120:121], v[202:203], v[144:145] op_sel_hi:[1,0,1]
	v_pk_mul_f32 v[210:211], v[200:201], v[206:207] op_sel_hi:[1,0]
	v_pk_fma_f32 v[118:119], v[184:185], v[118:119], v[210:211]
	v_pk_mul_f32 v[210:211], v[198:199], v[206:207] op_sel_hi:[1,0]
	v_pk_fma_f32 v[120:121], v[190:191], v[120:121], v[210:211]
	global_store_dwordx4 v158, v[118:121], s[30:31] nt
	s_nop 0
	s_waitcnt vmcnt(57)
	v_pk_fma_f32 v[142:143], v[114:115], v[202:203], v[142:143] op_sel:[0,1,0]
	v_pk_fma_f32 v[144:145], v[116:117], v[202:203], v[144:145] op_sel:[0,1,0]
	v_pk_mul_f32 v[210:211], v[200:201], v[206:207] op_sel:[0,1]
	v_pk_fma_f32 v[114:115], v[184:185], v[114:115], v[210:211]
	v_pk_mul_f32 v[210:211], v[198:199], v[206:207] op_sel:[0,1]
	v_pk_fma_f32 v[116:117], v[190:191], v[116:117], v[210:211]
	global_store_dwordx4 v158, v[114:117], s[30:31] offset:1024 nt
	s_nop 0
	s_waitcnt vmcnt(56)
	v_pk_fma_f32 v[142:143], v[110:111], v[204:205], v[142:143] op_sel_hi:[1,0,1]
	v_pk_fma_f32 v[144:145], v[112:113], v[204:205], v[144:145] op_sel_hi:[1,0,1]
	v_pk_mul_f32 v[210:211], v[200:201], v[208:209] op_sel_hi:[1,0]
	v_pk_fma_f32 v[110:111], v[184:185], v[110:111], v[210:211]
	v_pk_mul_f32 v[210:211], v[198:199], v[208:209] op_sel_hi:[1,0]
	v_pk_fma_f32 v[112:113], v[190:191], v[112:113], v[210:211]
	global_store_dwordx4 v158, v[110:113], s[30:31] offset:2048 nt
	s_nop 0
	s_waitcnt vmcnt(55)
	v_pk_fma_f32 v[142:143], v[106:107], v[204:205], v[142:143] op_sel:[0,1,0]
	v_pk_fma_f32 v[144:145], v[108:109], v[204:205], v[144:145] op_sel:[0,1,0]
	v_pk_mul_f32 v[210:211], v[200:201], v[208:209] op_sel:[0,1]
	v_pk_fma_f32 v[106:107], v[184:185], v[106:107], v[210:211]
	v_pk_mul_f32 v[210:211], v[198:199], v[208:209] op_sel:[0,1]
	v_pk_fma_f32 v[108:109], v[190:191], v[108:109], v[210:211]
	global_store_dwordx4 v158, v[106:109], s[30:31] offset:3072 nt
	s_add_u32 s30, s30, 0x1000
	s_addc_u32 s31, s31, 0
	ds_read_b128 v[202:205], v179 offset:944
	ds_read_b128 v[206:209], v179 offset:1968
	s_waitcnt lgkmcnt(2)
	s_waitcnt vmcnt(54)
; __device__ __forceinline__ void mlstm_decode_wave(const Params& P, unsigned char* wl, int sh) {
;     ...
;     for (int dk0 = 0; dk0 < 256; dk0 += 32) { f32x4 c[32];
; #pragma unroll
;         for (int i = 0; i < 32; ++i) c[i] = __builtin_nontemporal_load((const f32x4*)(C0 + (dk0 + i) * 256));
; #pragma unroll
;         for (int i = 0; i < 32; ++i) { const float qd = sq[dk0 + i], kd = sk[dk0 + i]; part += qd * c[i]; __builtin_nontemporal_store(wc * c[i] + kd * wv, (f32x4*)(C1 + (dk0 + i) * 256)); } }
	v_pk_fma_f32 v[142:143], v[102:103], v[134:135], v[142:143] op_sel_hi:[1,0,1]
	v_pk_fma_f32 v[144:145], v[104:105], v[134:135], v[144:145] op_sel_hi:[1,0,1]
	v_pk_mul_f32 v[210:211], v[200:201], v[138:139] op_sel_hi:[1,0]
	v_pk_fma_f32 v[102:103], v[184:185], v[102:103], v[210:211]
	v_pk_mul_f32 v[210:211], v[198:199], v[138:139] op_sel_hi:[1,0]
	v_pk_fma_f32 v[104:105], v[190:191], v[104:105], v[210:211]
	global_store_dwordx4 v158, v[102:105], s[30:31] nt
	s_nop 0
	s_waitcnt vmcnt(53)
	v_pk_fma_f32 v[142:143], v[98:99], v[134:135], v[142:143] op_sel:[0,1,0]
	v_pk_fma_f32 v[144:145], v[100:101], v[134:135], v[144:145] op_sel:[0,1,0]
	v_pk_mul_f32 v[210:211], v[200:201], v[138:139] op_sel:[0,1]
	v_pk_fma_f32 v[98:99], v[184:185], v[98:99], v[210:211]
	v_pk_mul_f32 v[210:211], v[198:199], v[138:139] op_sel:[0,1]
	v_pk_fma_f32 v[100:101], v[190:191], v[100:101], v[210:211]
	global_store_dwordx4 v158, v[98:101], s[30:31] offset:1024 nt
	s_nop 0
	s_waitcnt vmcnt(52)
	v_pk_fma_f32 v[142:143], v[94:95], v[136:137], v[142:143] op_sel_hi:[1,0,1]
	v_pk_fma_f32 v[144:145], v[96:97], v[136:137], v[144:145] op_sel_hi:[1,0,1]
	v_pk_mul_f32 v[210:211], v[200:201], v[140:141] op_sel_hi:[1,0]
	v_pk_fma_f32 v[94:95], v[184:185], v[94:95], v[210:211]
	v_pk_mul_f32 v[210:211], v[198:199], v[140:141] op_sel_hi:[1,0]
	v_pk_fma_f32 v[96:97], v[190:191], v[96:97], v[210:211]
	global_store_dwordx4 v158, v[94:97], s[30:31] offset:2048 nt
	s_nop 0
	s_waitcnt vmcnt(51)
	v_pk_fma_f32 v[142:143], v[90:91], v[136:137], v[142:143] op_sel:[0,1,0]
	v_pk_fma_f32 v[144:145], v[92:93], v[136:137], v[144:145] op_sel:[0,1,0]
	v_pk_mul_f32 v[210:211], v[200:201], v[140:141] op_sel:[0,1]
	v_pk_fma_f32 v[90:91], v[184:185], v[90:91], v[210:211]
	v_pk_mul_f32 v[210:211], v[198:199], v[140:141] op_sel:[0,1]
	v_pk_fma_f32 v[92:93], v[190:191], v[92:93], v[210:211]
	global_store_dwordx4 v158, v[90:93], s[30:31] offset:3072 nt
	s_add_u32 s30, s30, 0x1000
	s_addc_u32 s31, s31, 0
	ds_read_b128 v[134:137], v179 offset:960
	ds_read_b128 v[138:141], v179 offset:1984
	s_waitcnt lgkmcnt(2)
	s_waitcnt vmcnt(50)
	v_pk_fma_f32 v[142:143], v[86:87], v[202:203], v[142:143] op_sel_hi:[1,0,1]
	v_pk_fma_f32 v[144:145], v[88:89], v[202:203], v[144:145] op_sel_hi:[1,0,1]
	v_pk_mul_f32 v[210:211], v[200:201], v[206:207] op_sel_hi:[1,0]
	v_pk_fma_f32 v[86:87], v[184:185], v[86:87], v[210:211]
	v_pk_mul_f32 v[210:211], v[198:199], v[206:207] op_sel_hi:[1,0]
	v_pk_fma_f32 v[88:89], v[190:191], v[88:89], v[210:211]
	global_store_dwordx4 v158, v[86:89], s[30:31] nt
	s_nop 0
	s_waitcnt vmcnt(49)
	v_pk_fma_f32 v[142:143], v[82:83], v[202:203], v[142:143] op_sel:[0,1,0]
	v_pk_fma_f32 v[144:145], v[84:85], v[202:203], v[144:145] op_sel:[0,1,0]
	v_pk_mul_f32 v[210:211], v[200:201], v[206:207] op_sel:[0,1]
	v_pk_fma_f32 v[82:83], v[184:185], v[82:83], v[210:211]
	v_pk_mul_f32 v[210:211], v[198:199], v[206:207] op_sel:[0,1]
	v_pk_fma_f32 v[84:85], v[190:191], v[84:85], v[210:211]
	global_store_dwordx4 v158, v[82:85], s[30:31] offset:1024 nt
	s_nop 0
	s_waitcnt vmcnt(48)
	v_pk_fma_f32 v[142:143], v[78:79], v[204:205], v[142:143] op_sel_hi:[1,0,1]
	v_pk_fma_f32 v[144:145], v[80:81], v[204:205], v[144:145] op_sel_hi:[1,0,1]
	v_pk_mul_f32 v[210:211], v[200:201], v[208:209] op_sel_hi:[1,0]
	v_pk_fma_f32 v[78:79], v[184:185], v[78:79], v[210:211]
	v_pk_mul_f32 v[210:211], v[198:199], v[208:209] op_sel_hi:[1,0]
	v_pk_fma_f32 v[80:81], v[190:191], v[80:81], v[210:211]
	global_store_dwordx4 v158, v[78:81], s[30:31] offset:2048 nt
	s_nop 0
	s_waitcnt vmcnt(47)
	v_pk_fma_f32 v[142:143], v[74:75], v[204:205], v[142:143] op_sel:[0,1,0]
	v_pk_fma_f32 v[144:145], v[76:77], v[204:205], v[144:145] op_sel:[0,1,0]
	v_pk_mul_f32 v[210:211], v[200:201], v[208:209] op_sel:[0,1]
	v_pk_fma_f32 v[74:75], v[184:185], v[74:75], v[210:211]
	v_pk_mul_f32 v[210:211], v[198:199], v[208:209] op_sel:[0,1]
	v_pk_fma_f32 v[76:77], v[190:191], v[76:77], v[210:211]
	global_store_dwordx4 v158, v[74:77], s[30:31] offset:3072 nt
	s_add_u32 s30, s30, 0x1000
	s_addc_u32 s31, s31, 0
	ds_read_b128 v[202:205], v179 offset:976
	ds_read_b128 v[206:209], v179 offset:2000
	s_waitcnt lgkmcnt(2)
	s_waitcnt vmcnt(46)
	v_pk_fma_f32 v[142:143], v[70:71], v[134:135], v[142:143] op_sel_hi:[1,0,1]
	v_pk_fma_f32 v[144:145], v[72:73], v[134:135], v[144:145] op_sel_hi:[1,0,1]
	v_pk_mul_f32 v[210:211], v[200:201], v[138:139] op_sel_hi:[1,0]
	v_pk_fma_f32 v[70:71], v[184:185], v[70:71], v[210:211]
	v_pk_mul_f32 v[210:211], v[198:199], v[138:139] op_sel_hi:[1,0]
	v_pk_fma_f32 v[72:73], v[190:191], v[72:73], v[210:211]
	global_store_dwordx4 v158, v[70:73], s[30:31] nt
	s_nop 0
	s_waitcnt vmcnt(45)
	v_pk_fma_f32 v[142:143], v[66:67], v[134:135], v[142:143] op_sel:[0,1,0]
	v_pk_fma_f32 v[144:145], v[68:69], v[134:135], v[144:145] op_sel:[0,1,0]
	v_pk_mul_f32 v[210:211], v[200:201], v[138:139] op_sel:[0,1]
	v_pk_fma_f32 v[66:67], v[184:185], v[66:67], v[210:211]
	v_pk_mul_f32 v[210:211], v[198:199], v[138:139] op_sel:[0,1]
	v_pk_fma_f32 v[68:69], v[190:191], v[68:69], v[210:211]
	global_store_dwordx4 v158, v[66:69], s[30:31] offset:1024 nt
	s_nop 0
	s_waitcnt vmcnt(44)
	v_pk_fma_f32 v[142:143], v[62:63], v[136:137], v[142:143] op_sel_hi:[1,0,1]
	v_pk_fma_f32 v[144:145], v[64:65], v[136:137], v[144:145] op_sel_hi:[1,0,1]
	v_pk_mul_f32 v[210:211], v[200:201], v[140:141] op_sel_hi:[1,0]
	v_pk_fma_f32 v[62:63], v[184:185], v[62:63], v[210:211]
	v_pk_mul_f32 v[210:211], v[198:199], v[140:141] op_sel_hi:[1,0]
	v_pk_fma_f32 v[64:65], v[190:191], v[64:65], v[210:211]
	global_store_dwordx4 v158, v[62:65], s[30:31] offset:2048 nt
	s_nop 0
	s_waitcnt vmcnt(43)
; __device__ __forceinline__ void mlstm_decode_wave(const Params& P, unsigned char* wl, int sh) {
;     ...
;     for (int dk0 = 0; dk0 < 256; dk0 += 32) { f32x4 c[32];
; #pragma unroll
;         for (int i = 0; i < 32; ++i) c[i] = __builtin_nontemporal_load((const f32x4*)(C0 + (dk0 + i) * 256));
; #pragma unroll
;         for (int i = 0; i < 32; ++i) { const float qd = sq[dk0 + i], kd = sk[dk0 + i]; part += qd * c[i]; __builtin_nontemporal_store(wc * c[i] + kd * wv, (f32x4*)(C1 + (dk0 + i) * 256)); } }
	v_pk_fma_f32 v[142:143], v[58:59], v[136:137], v[142:143] op_sel:[0,1,0]
	v_pk_fma_f32 v[144:145], v[60:61], v[136:137], v[144:145] op_sel:[0,1,0]
	v_pk_mul_f32 v[210:211], v[200:201], v[140:141] op_sel:[0,1]
	v_pk_fma_f32 v[58:59], v[184:185], v[58:59], v[210:211]
	v_pk_mul_f32 v[210:211], v[198:199], v[140:141] op_sel:[0,1]
	v_pk_fma_f32 v[60:61], v[190:191], v[60:61], v[210:211]
	global_store_dwordx4 v158, v[58:61], s[30:31] offset:3072 nt
	s_add_u32 s30, s30, 0x1000
	s_addc_u32 s31, s31, 0
	ds_read_b128 v[134:137], v179 offset:992
	ds_read_b128 v[138:141], v179 offset:2016
	s_waitcnt lgkmcnt(2)
	s_waitcnt vmcnt(42)
	v_pk_fma_f32 v[142:143], v[54:55], v[202:203], v[142:143] op_sel_hi:[1,0,1]
	v_pk_fma_f32 v[144:145], v[56:57], v[202:203], v[144:145] op_sel_hi:[1,0,1]
	v_pk_mul_f32 v[210:211], v[200:201], v[206:207] op_sel_hi:[1,0]
	v_pk_fma_f32 v[54:55], v[184:185], v[54:55], v[210:211]
	v_pk_mul_f32 v[210:211], v[198:199], v[206:207] op_sel_hi:[1,0]
	v_pk_fma_f32 v[56:57], v[190:191], v[56:57], v[210:211]
	global_store_dwordx4 v158, v[54:57], s[30:31] nt
	s_nop 0
	s_waitcnt vmcnt(41)
	v_pk_fma_f32 v[142:143], v[50:51], v[202:203], v[142:143] op_sel:[0,1,0]
	v_pk_fma_f32 v[144:145], v[52:53], v[202:203], v[144:145] op_sel:[0,1,0]
	v_pk_mul_f32 v[210:211], v[200:201], v[206:207] op_sel:[0,1]
	v_pk_fma_f32 v[50:51], v[184:185], v[50:51], v[210:211]
	v_pk_mul_f32 v[210:211], v[198:199], v[206:207] op_sel:[0,1]
	v_pk_fma_f32 v[52:53], v[190:191], v[52:53], v[210:211]
	global_store_dwordx4 v158, v[50:53], s[30:31] offset:1024 nt
	s_nop 0
	s_waitcnt vmcnt(40)
	v_pk_fma_f32 v[142:143], v[46:47], v[204:205], v[142:143] op_sel_hi:[1,0,1]
	v_pk_fma_f32 v[144:145], v[48:49], v[204:205], v[144:145] op_sel_hi:[1,0,1]
	v_pk_mul_f32 v[210:211], v[200:201], v[208:209] op_sel_hi:[1,0]
	v_pk_fma_f32 v[46:47], v[184:185], v[46:47], v[210:211]
	v_pk_mul_f32 v[210:211], v[198:199], v[208:209] op_sel_hi:[1,0]
	v_pk_fma_f32 v[48:49], v[190:191], v[48:49], v[210:211]
	global_store_dwordx4 v158, v[46:49], s[30:31] offset:2048 nt
	s_nop 0
	s_waitcnt vmcnt(39)
	v_pk_fma_f32 v[142:143], v[42:43], v[204:205], v[142:143] op_sel:[0,1,0]
	v_pk_fma_f32 v[144:145], v[44:45], v[204:205], v[144:145] op_sel:[0,1,0]
	v_pk_mul_f32 v[210:211], v[200:201], v[208:209] op_sel:[0,1]
	v_pk_fma_f32 v[42:43], v[184:185], v[42:43], v[210:211]
	v_pk_mul_f32 v[210:211], v[198:199], v[208:209] op_sel:[0,1]
	v_pk_fma_f32 v[44:45], v[190:191], v[44:45], v[210:211]
	global_store_dwordx4 v158, v[42:45], s[30:31] offset:3072 nt
	s_add_u32 s30, s30, 0x1000
	s_addc_u32 s31, s31, 0
	ds_read_b128 v[202:205], v179 offset:1008
	ds_read_b128 v[206:209], v179 offset:2032
	s_waitcnt lgkmcnt(2)
	s_waitcnt vmcnt(38)
	v_pk_fma_f32 v[142:143], v[38:39], v[134:135], v[142:143] op_sel_hi:[1,0,1]
	v_pk_fma_f32 v[144:145], v[40:41], v[134:135], v[144:145] op_sel_hi:[1,0,1]
	v_pk_mul_f32 v[210:211], v[200:201], v[138:139] op_sel_hi:[1,0]
	v_pk_fma_f32 v[38:39], v[184:185], v[38:39], v[210:211]
	v_pk_mul_f32 v[210:211], v[198:199], v[138:139] op_sel_hi:[1,0]
	v_pk_fma_f32 v[40:41], v[190:191], v[40:41], v[210:211]
	global_store_dwordx4 v158, v[38:41], s[30:31] nt
	s_nop 0
	s_waitcnt vmcnt(37)
	v_pk_fma_f32 v[142:143], v[34:35], v[134:135], v[142:143] op_sel:[0,1,0]
	v_pk_fma_f32 v[144:145], v[36:37], v[134:135], v[144:145] op_sel:[0,1,0]
	v_pk_mul_f32 v[210:211], v[200:201], v[138:139] op_sel:[0,1]
	v_pk_fma_f32 v[34:35], v[184:185], v[34:35], v[210:211]
	v_pk_mul_f32 v[210:211], v[198:199], v[138:139] op_sel:[0,1]
	v_pk_fma_f32 v[36:37], v[190:191], v[36:37], v[210:211]
	global_store_dwordx4 v158, v[34:37], s[30:31] offset:1024 nt
	s_nop 0
	s_waitcnt vmcnt(36)
	v_pk_fma_f32 v[142:143], v[30:31], v[136:137], v[142:143] op_sel_hi:[1,0,1]
	v_pk_fma_f32 v[144:145], v[32:33], v[136:137], v[144:145] op_sel_hi:[1,0,1]
	v_pk_mul_f32 v[210:211], v[200:201], v[140:141] op_sel_hi:[1,0]
	v_pk_fma_f32 v[30:31], v[184:185], v[30:31], v[210:211]
	v_pk_mul_f32 v[210:211], v[198:199], v[140:141] op_sel_hi:[1,0]
	v_pk_fma_f32 v[32:33], v[190:191], v[32:33], v[210:211]
	global_store_dwordx4 v158, v[30:33], s[30:31] offset:2048 nt
	s_nop 0
	s_waitcnt vmcnt(35)
	v_pk_fma_f32 v[142:143], v[26:27], v[136:137], v[142:143] op_sel:[0,1,0]
	v_pk_fma_f32 v[144:145], v[28:29], v[136:137], v[144:145] op_sel:[0,1,0]
	v_pk_mul_f32 v[210:211], v[200:201], v[140:141] op_sel:[0,1]
	v_pk_fma_f32 v[26:27], v[184:185], v[26:27], v[210:211]
	v_pk_mul_f32 v[210:211], v[198:199], v[140:141] op_sel:[0,1]
	v_pk_fma_f32 v[28:29], v[190:191], v[28:29], v[210:211]
	global_store_dwordx4 v158, v[26:29], s[30:31] offset:3072 nt
	s_add_u32 s30, s30, 0x1000
	s_addc_u32 s31, s31, 0
	s_waitcnt lgkmcnt(0)
	s_waitcnt vmcnt(34)
	v_pk_fma_f32 v[142:143], v[22:23], v[202:203], v[142:143] op_sel_hi:[1,0,1]
	v_pk_fma_f32 v[144:145], v[24:25], v[202:203], v[144:145] op_sel_hi:[1,0,1]
	v_pk_mul_f32 v[210:211], v[200:201], v[206:207] op_sel_hi:[1,0]
	v_pk_fma_f32 v[22:23], v[184:185], v[22:23], v[210:211]
	v_pk_mul_f32 v[210:211], v[198:199], v[206:207] op_sel_hi:[1,0]
	v_pk_fma_f32 v[24:25], v[190:191], v[24:25], v[210:211]
	global_store_dwordx4 v158, v[22:25], s[30:31] nt
	s_nop 0
	s_waitcnt vmcnt(33)
	v_pk_fma_f32 v[142:143], v[18:19], v[202:203], v[142:143] op_sel:[0,1,0]
	v_pk_fma_f32 v[144:145], v[20:21], v[202:203], v[144:145] op_sel:[0,1,0]
	v_pk_mul_f32 v[210:211], v[200:201], v[206:207] op_sel:[0,1]
	v_pk_fma_f32 v[18:19], v[184:185], v[18:19], v[210:211]
	v_pk_mul_f32 v[210:211], v[198:199], v[206:207] op_sel:[0,1]
	v_pk_fma_f32 v[20:21], v[190:191], v[20:21], v[210:211]
	global_store_dwordx4 v158, v[18:21], s[30:31] offset:1024 nt
	s_nop 0
	s_waitcnt vmcnt(32)
; __device__ __forceinline__ unsigned cvt_pk_bf16(float lo, float hi) { unsigned r; asm volatile("v_cvt_pk_bf16_f32 %0, %1, %2" : "=v"(r) : "v"(lo), "v"(hi)); return r; }
; __device__ __forceinline__ float wave_sum(float v) { v = row16_sum(v); return (lane_bcast(v, 0) + lane_bcast(v, 16)) + (lane_bcast(v, 32) + lane_bcast(v, 48)); }
; __device__ __forceinline__ f32x4 sig4(const f32x4 v) { return (f32x4){sigmoidf_(v[0]), sigmoidf_(v[1]), sigmoidf_(v[2]), sigmoidf_(v[3])}; }
; __device__ __forceinline__ void mlstm_decode_wave(const Params& P, unsigned char* wl, int sh) {
;     ...
;     for (int dk0 = 0; dk0 < 256; dk0 += 32) { f32x4 c[32];
; #pragma unroll
;         for (int i = 0; i < 32; ++i) c[i] = __builtin_nontemporal_load((const f32x4*)(C0 + (dk0 + i) * 256));
; #pragma unroll
;         for (int i = 0; i < 32; ++i) { const float qd = sq[dk0 + i], kd = sk[dk0 + i]; part += qd * c[i]; __builtin_nontemporal_store(wc * c[i] + kd * wv, (f32x4*)(C1 + (dk0 + i) * 256)); } }
;     const float s = qk * wi; const f32x4 num = wc * part + s * v4; const float den = wc * qn + s;
;     const float dinv = 1.0f / fmaxf(fabsf(den), __expf(-mt));
;     f32x4 hv = num * dinv;
;     const float mean = wave_sum((hv[0] + hv[1]) + (hv[2] + hv[3])) * (1.0f / 256.0f);
;     hv -= mean;
;     const float var = wave_sum((hv[0] * hv[0] + hv[1] * hv[1]) + (hv[2] * hv[2] + hv[3] * hv[3])) * (1.0f / 256.0f);
;     const float rstd = rsqrtf(var + EPS);
;     const f32x4 gn = *(const f32x4*)(P.in[21] + h * 256 + 4 * lane);
;     const f32x4 y = sig4(o4) * hv * rstd * gn;
;     u32x2 yw; yw.x = cvt_pk_bf16(y[0], y[1]); yw.y = cvt_pk_bf16(y[2], y[3]);
;     *(u32x2*)((bf16_t*)(P.ws + O_YB) + (size_t)row * 1024 + h * 256 + 4 * lane) = yw;
;     *(f32x4*)(P.out + OUT_SN + (size_t)sh * 256 + 4 * lane) = wc * n4 + wi * k4;
;     if (lane == 0) P.out[OUT_SM + sh] = mt;
	v_pk_fma_f32 v[142:143], v[14:15], v[204:205], v[142:143] op_sel_hi:[1,0,1]
	v_pk_fma_f32 v[144:145], v[16:17], v[204:205], v[144:145] op_sel_hi:[1,0,1]
	v_pk_mul_f32 v[210:211], v[200:201], v[208:209] op_sel_hi:[1,0]
	v_pk_fma_f32 v[14:15], v[184:185], v[14:15], v[210:211]
	v_pk_mul_f32 v[210:211], v[198:199], v[208:209] op_sel_hi:[1,0]
	v_pk_fma_f32 v[16:17], v[190:191], v[16:17], v[210:211]
	global_store_dwordx4 v158, v[14:17], s[30:31] offset:2048 nt
	s_nop 0
	s_waitcnt vmcnt(31)
	v_pk_fma_f32 v[142:143], v[10:11], v[204:205], v[142:143] op_sel:[0,1,0]
	v_pk_fma_f32 v[144:145], v[12:13], v[204:205], v[144:145] op_sel:[0,1,0]
	v_pk_mul_f32 v[210:211], v[200:201], v[208:209] op_sel:[0,1]
	v_pk_fma_f32 v[10:11], v[184:185], v[10:11], v[210:211]
	v_pk_mul_f32 v[210:211], v[198:199], v[208:209] op_sel:[0,1]
	v_pk_fma_f32 v[12:13], v[190:191], v[12:13], v[210:211]
	global_store_dwordx4 v158, v[10:13], s[30:31] offset:3072 nt
	s_add_u32 s30, s30, 0x1000
	s_addc_u32 s31, s31, 0
	v_readlane_b32 s30, v149, 0
	v_readlane_b32 s31, v173, 0
	v_readlane_b32 s28, v149, 32
	v_readlane_b32 s29, v173, 32
	v_mov_b32_e32 v10, s10
	v_mov_b32_e32 v11, s11
	v_mov_b32_e32 v12, s30
	v_mov_b32_e32 v13, s31
	v_pk_add_f32 v[10:11], s[28:29], v[10:11]
	v_pk_add_f32 v[12:13], s[8:9], v[12:13]
	v_lshlrev_b32_e32 v22, 16, v192
	v_pk_add_f32 v[10:11], v[10:11], v[12:13]
	v_mov_b32_e32 v12, v186
	v_mov_b32_e32 v13, v184
	v_pk_mul_f32 v[10:11], v[12:13], v[10:11]
	v_lshlrev_b32_e32 v20, 16, v193
	v_pk_mul_f32 v[12:13], v[10:11], v[196:197] op_sel_hi:[0,1]
	v_pk_mul_f32 v[14:15], v[10:11], v[194:195] op_sel_hi:[0,1]
	v_add_f32_e32 v10, v10, v11
	v_mul_f32_e32 v11, 0xbfb8aa3b, v1
	v_exp_f32_e32 v11, v11
	v_pk_fma_f32 v[14:15], v[184:185], v[142:143], v[14:15]
	v_pk_fma_f32 v[12:13], v[190:191], v[144:145], v[12:13]
	v_and_b32_e32 v21, 0xffff0000, v192
	v_max_f32_e64 v10, |v10|, v11
	v_div_scale_f32 v11, s[8:9], v10, v10, 1.0
	v_rcp_f32_e32 v16, v11
	v_and_b32_e32 v19, 0xffff0000, v193
	v_mul_f32_e32 v22, 0xbfb8aa3b, v22
	v_mul_f32_e32 v21, 0xbfb8aa3b, v21
	v_fma_f32 v17, -v11, v16, 1.0
	v_fmac_f32_e32 v16, v17, v16
	v_div_scale_f32 v17, vcc, 1.0, v10, 1.0
	v_mul_f32_e32 v18, v17, v16
	v_fma_f32 v23, -v11, v18, v17
	v_fmac_f32_e32 v18, v23, v16
	v_fma_f32 v11, -v11, v18, v17
	v_div_fmas_f32 v11, v11, v16, v18
	v_div_fixup_f32 v10, v11, v10, 1.0
	v_pk_mul_f32 v[16:17], v[12:13], v[10:11] op_sel_hi:[1,0]
	v_pk_mul_f32 v[24:25], v[14:15], v[10:11] op_sel_hi:[1,0]
	v_mul_f32_e32 v20, 0xbfb8aa3b, v20
	v_pk_mov_b32 v[26:27], v[24:25], v[16:17] op_sel:[1,0]
	v_mov_b32_e32 v25, v17
	v_pk_add_f32 v[16:17], v[26:27], v[24:25]
	v_mul_f32_e32 v19, 0xbfb8aa3b, v19
	v_add_f32_e32 v11, v16, v17
	v_exp_f32_e32 v22, v22
	v_exp_f32_e32 v21, v21
	v_add_f32_dpp v11, v11, v11 row_ror:8 row_mask:0xf bank_mask:0xf bound_ctrl:1
	v_exp_f32_e32 v20, v20
	v_exp_f32_e32 v19, v19
	v_add_f32_dpp v11, v11, v11 row_ror:4 row_mask:0xf bank_mask:0xf bound_ctrl:1
	v_add_f32_e32 v22, 1.0, v22
	v_add_f32_e32 v21, 1.0, v21
	v_add_f32_dpp v11, v11, v11 row_ror:2 row_mask:0xf bank_mask:0xf bound_ctrl:1
	v_add_f32_e32 v20, 1.0, v20
	v_add_f32_e32 v19, 1.0, v19
	v_add_f32_dpp v11, v11, v11 row_ror:1 row_mask:0xf bank_mask:0xf bound_ctrl:1
	v_rcp_f32_e32 v22, v22
	v_readlane_b32 s10, v11, 16
	v_readlane_b32 s11, v11, 48
	v_readlane_b32 s8, v11, 0
	v_readlane_b32 s9, v11, 32
	v_mov_b32_e32 v16, s10
	v_mov_b32_e32 v17, s11
	v_pk_add_f32 v[16:17], s[8:9], v[16:17]
	v_rcp_f32_e32 v23, v21
	v_add_f32_e32 v11, v16, v17
	v_mul_f32_e32 v16, 0xbb800000, v11
	v_pk_fma_f32 v[14:15], v[14:15], v[10:11], v[16:17] op_sel_hi:[1,0,0]
	v_pk_fma_f32 v[16:17], v[12:13], v[10:11], v[16:17] op_sel_hi:[1,0,0]
	v_pk_mul_f32 v[12:13], v[14:15], v[14:15]
	v_pk_mul_f32 v[10:11], v[16:17], v[16:17]
	v_rcp_f32_e32 v20, v20
	v_pk_mov_b32 v[24:25], v[12:13], v[10:11] op_sel:[1,0]
	v_mov_b32_e32 v13, v11
	v_pk_add_f32 v[10:11], v[24:25], v[12:13]
	v_rcp_f32_e32 v21, v19
	v_add_f32_e32 v10, v10, v11
	v_pk_mul_f32 v[14:15], v[22:23], v[14:15]
	v_mov_b32_e32 v179, v0
	v_add_f32_dpp v10, v10, v10 row_ror:8 row_mask:0xf bank_mask:0xf bound_ctrl:1
	v_pk_mul_f32 v[16:17], v[20:21], v[16:17]
	v_pk_mul_f32 v[8:9], v[8:9], v[188:189]
	v_add_f32_dpp v10, v10, v10 row_ror:4 row_mask:0xf bank_mask:0xf bound_ctrl:1
	v_pk_mul_f32 v[6:7], v[6:7], v[186:187]
	v_pk_fma_f32 v[4:5], v[4:5], v[190:191], v[8:9]
	v_add_f32_dpp v10, v10, v10 row_ror:2 row_mask:0xf bank_mask:0xf bound_ctrl:1
	v_pk_fma_f32 v[2:3], v[2:3], v[184:185], v[6:7]
	v_lshl_add_u64 v[6:7], v[180:181], 2, v[164:165]
	v_add_f32_dpp v10, v10, v10 row_ror:1 row_mask:0xf bank_mask:0xf bound_ctrl:1
	s_nop 0
	v_readlane_b32 s10, v10, 16
	v_readlane_b32 s11, v10, 48
	v_readlane_b32 s8, v10, 0
	v_readlane_b32 s9, v10, 32
	v_mov_b32_e32 v10, s10
	v_mov_b32_e32 v11, s11
	v_pk_add_f32 v[10:11], s[8:9], v[10:11]
	s_mov_b32 s8, 0x800000
	v_add_f32_e32 v10, v10, v11
	v_fmamk_f32 v10, v10, 0x3b800000, v225
	v_cmp_gt_f32_e32 vcc, s8, v10
	v_mul_f32_e32 v11, 0x4b800000, v10
	s_nop 0
	v_cndmask_b32_e32 v10, v10, v11, vcc
	v_rsq_f32_e32 v10, v10
	s_nop 0
	v_mul_f32_e32 v11, 0x45800000, v10
	v_cndmask_b32_e32 v18, v10, v11, vcc
	v_lshlrev_b32_e32 v10, 2, v182
	v_mov_b32_e32 v11, v0
	v_lshl_add_u64 v[10:11], v[162:163], 0, v[10:11]
	global_load_dwordx4 v[10:13], v[10:11], off
	v_pk_mul_f32 v[14:15], v[14:15], v[18:19] op_sel_hi:[1,0]
	v_pk_mul_f32 v[16:17], v[16:17], v[18:19] op_sel_hi:[1,0]
	s_waitcnt vmcnt(0)
	v_pk_mul_f32 v[10:11], v[10:11], v[14:15]
	v_pk_mul_f32 v[12:13], v[12:13], v[16:17]
	v_cvt_pk_bf16_f32 v10, v10, v11
	v_lshlrev_b32_e32 v14, 1, v182
	v_cvt_pk_bf16_f32 v11, v12, v13
	v_lshlrev_b64 v[12:13], 11, v[176:177]
	v_lshl_add_u64 v[12:13], s[20:21], 0, v[12:13]
	v_mov_b32_e32 v15, v0
	v_lshl_add_u64 v[12:13], v[12:13], 0, v[14:15]
	v_lshl_add_u64 v[12:13], v[12:13], 0, v[178:179]
	global_store_dwordx2 v[12:13], v[10:11], off
	global_store_dwordx4 v[6:7], v[2:5], off
	s_and_saveexec_b64 s[8:9], s[2:3]
	s_cbranch_execz .LBB0_345
	v_readlane_b32 s56, v245, 34
	v_readlane_b32 s70, v245, 48
	v_readlane_b32 s71, v245, 49
	v_readlane_b32 s57, v245, 35
	v_readlane_b32 s58, v245, 36
	v_lshl_add_u64 v[2:3], v[174:175], 2, s[70:71]
	v_add_co_u32_e32 v2, vcc, 0xc9a4000, v2
	v_readlane_b32 s59, v245, 37
	s_nop 0
	v_addc_co_u32_e32 v3, vcc, 0, v3, vcc
	v_readlane_b32 s60, v245, 38
	v_readlane_b32 s61, v245, 39
	v_readlane_b32 s62, v245, 40
	v_readlane_b32 s63, v245, 41
	v_readlane_b32 s64, v245, 42
	v_readlane_b32 s65, v245, 43
	v_readlane_b32 s66, v245, 44
	v_readlane_b32 s67, v245, 45
	v_readlane_b32 s68, v245, 46
	v_readlane_b32 s69, v245, 47
	global_store_dword v[2:3], v1, off offset:64
	s_branch .LBB0_345
